# drop hipcc's vmcnt(0) before barriers in 3-stage g2 GEMM loops (counted vmcnt(6) honoured)
# baseline (speedup 1.0000x reference)
; DEVI int opaque_tid() { int t = (int)threadIdx.x; asm volatile("" : "+v"(t)); return t; }
; DEVI void g2_issue(const G2Tile& t, int kt, int st, char* smem) {
;     const int tid = opaque_tid(), lane = tid & 63, w = tid >> 6;
;     const int rr = lane >> 2, sch = (lane & 3) ^ ((lane >> 5) << 1);
;     const bf16_t* ap = t.A + (size_t)kt * 32 + (size_t)(w * 16 + rr) * t.lda + sch * 8;
;     const bf16_t* bp = t.Bt + (size_t)kt * 32 + (size_t)(w * 16 + rr) * t.ldb + sch * 8;
;     char* sa = smem + st * 24576 + w * 1024 + lane * 16;
; #pragma unroll
;     for (int i = 0; i < 4; ++i) __builtin_amdgcn_global_load_lds((const unsigned*)(ap + (size_t)(64 * i) * t.lda), (unsigned*)(sa + i * 4096), 16, 0, 0);
; #pragma unroll
;     for (int i = 0; i < 2; ++i) __builtin_amdgcn_global_load_lds((const unsigned*)(bp + (size_t)(64 * i) * t.ldb), (unsigned*)(sa + 16384 + i * 4096), 16, 0, 0);
; template <bool TRANS, class Epi>
; DEVI int g2_body(const G2Tile& t, int st, char* smem, bool has_next, const G2Tile& nxt, const Epi& epi) {
;     ...
;     for (int kt = 0; kt < nk; ++kt) {
;         if (kt + 1 < nk) asm volatile("s_waitcnt vmcnt(6)" ::: "memory");
;         else asm volatile("s_waitcnt vmcnt(0)" ::: "memory");
;         __syncthreads();
;         if (kt + 2 < nk) g2_issue(t, kt + 2, st >= 1 ? st - 1 : 2, smem);
;         const char* sa = smem + st * 24576 + frag;
;         bf16x8 bfr[4];
; #pragma unroll
;         for (int n = 0; n < 4; ++n) bfr[n] = *(const bf16x8*)(sa + (16 + wc * 4 + n) * 1024);
; #pragma unroll
;         for (int mh = 0; mh < 2; ++mh) {
;             bf16x8 af[4];
; #pragma unroll
;             for (int m = 0; m < 4; ++m) af[m] = *(const bf16x8*)(sa + (wr * 8 + mh * 4 + m) * 1024);
;             __builtin_amdgcn_s_setprio(1);
; #pragma unroll
;             for (int m = 0; m < 4; ++m)
; #pragma unroll
;                 for (int n = 0; n < 4; ++n)
;                     acc[mh * 4 + m][n] = TRANS ? __builtin_amdgcn_mfma_f32_16x16x32_bf16(bfr[n], af[m], acc[mh * 4 + m][n], 0, 0, 0)
;                                                : __builtin_amdgcn_mfma_f32_16x16x32_bf16(af[m], bfr[n], acc[mh * 4 + m][n], 0, 0, 0);
;             __builtin_amdgcn_s_setprio(0);
;         }
;         st = st == 2 ? 0 : st + 1;
;     }
.LBB0_243:
	v_mov_b32_e32 v136, v172
	s_waitcnt vmcnt(6)
	s_waitcnt lgkmcnt(0)
	s_barrier
	s_mul_i32 s5, s4, 0x6000
	v_and_b32_e32 v142, 63, v136
	v_ashrrev_i32_e32 v143, 6, v136
	v_bfe_u32 v137, v136, 2, 4
	v_and_b32_e32 v138, 3, v136
	v_lshrrev_b32_e32 v136, 4, v136
	s_add_i32 s16, s5, 0xffffa000
	v_bitop3_b32 v138, v136, v138, 2 bitop3:0x6c
	v_lshl_or_b32 v136, v143, 4, v137
	s_cmp_gt_i32 s4, 0
	v_ashrrev_i32_e32 v137, 31, v136
	v_lshlrev_b64 v[136:137], 11, v[136:137]
	s_cselect_b32 s16, s16, 0xc000
	v_lshl_or_b32 v136, v138, 4, v136
	s_add_i32 s16, s16, 0
	v_lshlrev_b32_e32 v143, 10, v143
	v_lshlrev_b32_e32 v142, 4, v142
	v_lshl_add_u64 v[136:137], s[2:3], 0, v[136:137]
	v_add3_u32 v142, s16, v143, v142
	v_lshl_add_u64 v[138:139], s[96:97], 0, v[136:137]
	v_readfirstlane_b32 s16, v142
	v_add_u32_e32 v143, 0x1000, v142
	v_lshl_add_u64 v[140:141], v[138:139], 0, s[6:7]
	s_mov_b32 m0, s16
	v_readfirstlane_b32 s16, v143
	v_add_u32_e32 v143, 0x2000, v142
	global_load_lds_dwordx4 v[140:141], off
	v_lshl_add_u64 v[140:141], v[138:139], 0, s[8:9]
	s_mov_b32 m0, s16
	v_readfirstlane_b32 s16, v143
	global_load_lds_dwordx4 v[140:141], off
	v_lshl_add_u64 v[140:141], v[138:139], 0, s[10:11]
	s_mov_b32 m0, s16
	v_lshl_add_u64 v[138:139], v[138:139], 0, s[12:13]
	global_load_lds_dwordx4 v[140:141], off
	v_add_u32_e32 v140, 0x3000, v142
	v_lshl_add_u64 v[136:137], s[92:93], 0, v[136:137]
	v_readfirstlane_b32 s16, v140
	v_add_u32_e32 v140, 0x4000, v142
	s_mov_b32 m0, s16
	v_readfirstlane_b32 s16, v140
	global_load_lds_dwordx4 v[138:139], off
	v_lshl_add_u64 v[138:139], v[136:137], 0, s[6:7]
	s_mov_b32 m0, s16
	v_lshl_add_u64 v[136:137], v[136:137], 0, s[8:9]
	global_load_lds_dwordx4 v[138:139], off
	v_add_u32_e32 v138, 0x5000, v142
	v_add_u32_e32 v152, s5, v134
	v_readfirstlane_b32 s16, v138
	s_mov_b32 m0, s16
	v_add_u32_e32 v148, v152, v128
	global_load_lds_dwordx4 v[136:137], off
	v_add_u32_e32 v168, v152, v135
	ds_read_b128 v[136:139], v148 offset:16384
	ds_read_b128 v[140:143], v148 offset:17408
	ds_read_b128 v[144:147], v148 offset:18432
	ds_read_b128 v[148:151], v148 offset:19456
	ds_read_b128 v[152:155], v168
	ds_read_b128 v[156:159], v168 offset:1024
	ds_read_b128 v[160:163], v168 offset:2048
	ds_read_b128 v[164:167], v168 offset:3072
	s_setprio 1
	s_waitcnt lgkmcnt(0)
	v_mfma_f32_16x16x32_bf16 v[124:127], v[136:139], v[152:155], v[124:127]
	v_mfma_f32_16x16x32_bf16 v[120:123], v[140:143], v[152:155], v[120:123]
	v_mfma_f32_16x16x32_bf16 v[116:119], v[144:147], v[152:155], v[116:119]
	v_mfma_f32_16x16x32_bf16 v[112:115], v[148:151], v[152:155], v[112:115]
	v_mfma_f32_16x16x32_bf16 v[108:111], v[136:139], v[156:159], v[108:111]
	v_mfma_f32_16x16x32_bf16 v[96:99], v[140:143], v[156:159], v[96:99]
	v_mfma_f32_16x16x32_bf16 v[84:87], v[144:147], v[156:159], v[84:87]
	v_mfma_f32_16x16x32_bf16 v[80:83], v[148:151], v[156:159], v[80:83]
	v_mfma_f32_16x16x32_bf16 v[76:79], v[136:139], v[160:163], v[76:79]
	v_mfma_f32_16x16x32_bf16 v[72:75], v[140:143], v[160:163], v[72:75]
	v_mfma_f32_16x16x32_bf16 v[68:71], v[144:147], v[160:163], v[68:71]
	v_mfma_f32_16x16x32_bf16 v[64:67], v[148:151], v[160:163], v[64:67]
	v_mfma_f32_16x16x32_bf16 v[60:63], v[136:139], v[164:167], v[60:63]
	v_mfma_f32_16x16x32_bf16 v[56:59], v[140:143], v[164:167], v[56:59]
	v_mfma_f32_16x16x32_bf16 v[52:55], v[144:147], v[164:167], v[52:55]
	v_mfma_f32_16x16x32_bf16 v[48:51], v[148:151], v[164:167], v[48:51]
	s_setprio 0
	ds_read_b128 v[152:155], v168 offset:4096
	ds_read_b128 v[156:159], v168 offset:5120
	ds_read_b128 v[160:163], v168 offset:6144
	ds_read_b128 v[164:167], v168 offset:7168
	s_setprio 1
	s_waitcnt lgkmcnt(0)
	v_mfma_f32_16x16x32_bf16 v[44:47], v[136:139], v[152:155], v[44:47]
	v_mfma_f32_16x16x32_bf16 v[40:43], v[140:143], v[152:155], v[40:43]
	v_mfma_f32_16x16x32_bf16 v[36:39], v[144:147], v[152:155], v[36:39]
	v_mfma_f32_16x16x32_bf16 v[32:35], v[148:151], v[152:155], v[32:35]
	v_mfma_f32_16x16x32_bf16 v[28:31], v[136:139], v[156:159], v[28:31]
	v_mfma_f32_16x16x32_bf16 v[24:27], v[140:143], v[156:159], v[24:27]
	v_mfma_f32_16x16x32_bf16 v[20:23], v[144:147], v[156:159], v[20:23]
	v_mfma_f32_16x16x32_bf16 v[16:19], v[148:151], v[156:159], v[16:19]
	v_mfma_f32_16x16x32_bf16 v[12:15], v[136:139], v[160:163], v[12:15]
	v_mfma_f32_16x16x32_bf16 v[8:11], v[140:143], v[160:163], v[8:11]
	v_mfma_f32_16x16x32_bf16 v[4:7], v[144:147], v[160:163], v[4:7]
	v_mfma_f32_16x16x32_bf16 v[0:3], v[148:151], v[160:163], v[0:3]
	v_mfma_f32_16x16x32_bf16 v[88:91], v[136:139], v[164:167], v[88:91]
	v_mfma_f32_16x16x32_bf16 v[92:95], v[140:143], v[164:167], v[92:95]
	v_mfma_f32_16x16x32_bf16 v[100:103], v[144:147], v[164:167], v[100:103]
	v_mfma_f32_16x16x32_bf16 v[104:107], v[148:151], v[164:167], v[104:107]
	s_setprio 0
	s_add_i32 s5, s4, 1
	s_cmp_lg_u32 s4, 2
	s_cselect_b32 s4, s5, 0
	s_add_u32 s2, s2, 64
	s_addc_u32 s3, s3, 0
	s_cmpk_eq_i32 s2, 0x780
	s_cbranch_scc0 .LBB0_243
	s_mul_i32 s2, s4, 0x6000
	v_add_u32_e32 v152, s2, v134
	v_add_u32_e32 v148, v152, v128
	v_add_u32_e32 v168, v152, v135
	s_waitcnt vmcnt(6)
	s_barrier
; template <bool TRANS, class Epi>
; DEVI int g2_body(const G2Tile& t, int st, char* smem, bool has_next, const G2Tile& nxt, const Epi& epi) {
;     ...
;     for (int kt = 0; kt < nk; ++kt) {
;         if (kt + 1 < nk) asm volatile("s_waitcnt vmcnt(6)" ::: "memory");
;         else asm volatile("s_waitcnt vmcnt(0)" ::: "memory");
;         __syncthreads();
;         if (kt + 2 < nk) g2_issue(t, kt + 2, st >= 1 ? st - 1 : 2, smem);
;         const char* sa = smem + st * 24576 + frag;
;         bf16x8 bfr[4];
; #pragma unroll
;         for (int n = 0; n < 4; ++n) bfr[n] = *(const bf16x8*)(sa + (16 + wc * 4 + n) * 1024);
; #pragma unroll
;         for (int mh = 0; mh < 2; ++mh) {
;             bf16x8 af[4];
; #pragma unroll
;             for (int m = 0; m < 4; ++m) af[m] = *(const bf16x8*)(sa + (wr * 8 + mh * 4 + m) * 1024);
;             __builtin_amdgcn_s_setprio(1);
; #pragma unroll
;             for (int m = 0; m < 4; ++m)
; #pragma unroll
;                 for (int n = 0; n < 4; ++n)
;                     acc[mh * 4 + m][n] = TRANS ? __builtin_amdgcn_mfma_f32_16x16x32_bf16(bfr[n], af[m], acc[mh * 4 + m][n], 0, 0, 0)
;                                                : __builtin_amdgcn_mfma_f32_16x16x32_bf16(af[m], bfr[n], acc[mh * 4 + m][n], 0, 0, 0);
;             __builtin_amdgcn_s_setprio(0);
;         }
;         st = st == 2 ? 0 : st + 1;
	ds_read_b128 v[136:139], v148 offset:16384
	ds_read_b128 v[140:143], v148 offset:17408
	ds_read_b128 v[144:147], v148 offset:18432
	ds_read_b128 v[148:151], v148 offset:19456
	ds_read_b128 v[152:155], v168
	ds_read_b128 v[156:159], v168 offset:1024
	ds_read_b128 v[160:163], v168 offset:2048
	ds_read_b128 v[164:167], v168 offset:3072
	s_setprio 1
	s_waitcnt lgkmcnt(3)
	v_mfma_f32_16x16x32_bf16 v[124:127], v[136:139], v[152:155], v[124:127]
	v_mfma_f32_16x16x32_bf16 v[120:123], v[140:143], v[152:155], v[120:123]
	v_mfma_f32_16x16x32_bf16 v[116:119], v[144:147], v[152:155], v[116:119]
	v_mfma_f32_16x16x32_bf16 v[112:115], v[148:151], v[152:155], v[112:115]
	s_waitcnt lgkmcnt(2)
	v_mfma_f32_16x16x32_bf16 v[108:111], v[136:139], v[156:159], v[108:111]
	v_mfma_f32_16x16x32_bf16 v[96:99], v[140:143], v[156:159], v[96:99]
	v_mfma_f32_16x16x32_bf16 v[84:87], v[144:147], v[156:159], v[84:87]
	v_mfma_f32_16x16x32_bf16 v[80:83], v[148:151], v[156:159], v[80:83]
	s_waitcnt lgkmcnt(1)
	v_mfma_f32_16x16x32_bf16 v[76:79], v[136:139], v[160:163], v[76:79]
	v_mfma_f32_16x16x32_bf16 v[72:75], v[140:143], v[160:163], v[72:75]
	v_mfma_f32_16x16x32_bf16 v[68:71], v[144:147], v[160:163], v[68:71]
	v_mfma_f32_16x16x32_bf16 v[64:67], v[148:151], v[160:163], v[64:67]
	s_waitcnt lgkmcnt(0)
	v_mfma_f32_16x16x32_bf16 v[60:63], v[136:139], v[164:167], v[60:63]
	v_mfma_f32_16x16x32_bf16 v[56:59], v[140:143], v[164:167], v[56:59]
	v_mfma_f32_16x16x32_bf16 v[52:55], v[144:147], v[164:167], v[52:55]
	v_mfma_f32_16x16x32_bf16 v[48:51], v[148:151], v[164:167], v[48:51]
	s_setprio 0
	ds_read_b128 v[152:155], v168 offset:4096
	ds_read_b128 v[156:159], v168 offset:5120
	ds_read_b128 v[160:163], v168 offset:6144
	ds_read_b128 v[164:167], v168 offset:7168
	s_setprio 1
	s_waitcnt lgkmcnt(3)
	v_mfma_f32_16x16x32_bf16 v[44:47], v[136:139], v[152:155], v[44:47]
	v_mfma_f32_16x16x32_bf16 v[40:43], v[140:143], v[152:155], v[40:43]
	v_mfma_f32_16x16x32_bf16 v[36:39], v[144:147], v[152:155], v[36:39]
	v_mfma_f32_16x16x32_bf16 v[32:35], v[148:151], v[152:155], v[32:35]
	s_waitcnt lgkmcnt(2)
	v_mfma_f32_16x16x32_bf16 v[28:31], v[136:139], v[156:159], v[28:31]
	v_mfma_f32_16x16x32_bf16 v[24:27], v[140:143], v[156:159], v[24:27]
	v_mfma_f32_16x16x32_bf16 v[20:23], v[144:147], v[156:159], v[20:23]
	v_mfma_f32_16x16x32_bf16 v[16:19], v[148:151], v[156:159], v[16:19]
	s_waitcnt lgkmcnt(1)
	v_mfma_f32_16x16x32_bf16 v[12:15], v[136:139], v[160:163], v[12:15]
	v_mfma_f32_16x16x32_bf16 v[8:11], v[140:143], v[160:163], v[8:11]
	v_mfma_f32_16x16x32_bf16 v[4:7], v[144:147], v[160:163], v[4:7]
	v_mfma_f32_16x16x32_bf16 v[0:3], v[148:151], v[160:163], v[0:3]
	s_waitcnt lgkmcnt(0)
	v_mfma_f32_16x16x32_bf16 v[136:139], v[136:139], v[164:167], v[88:91]
	v_mfma_f32_16x16x32_bf16 v[140:143], v[140:143], v[164:167], v[92:95]
	v_mfma_f32_16x16x32_bf16 v[144:147], v[144:147], v[164:167], v[100:103]
	v_mfma_f32_16x16x32_bf16 v[148:151], v[148:151], v[164:167], v[104:107]
	s_setprio 0
	s_add_i32 s2, s4, 1
	s_cmp_lg_u32 s4, 2
	s_cselect_b32 s2, s2, 0
	s_mul_i32 s3, s2, 0x6000
	v_add_u32_e32 v100, s3, v134
	v_add_u32_e32 v134, v100, v135
	v_add_u32_e32 v100, v100, v128
	s_waitcnt vmcnt(0)
	s_barrier
	ds_read_b128 v[152:155], v134 offset:3072
	ds_read_b128 v[156:159], v134 offset:2048
	ds_read_b128 v[88:91], v134 offset:1024
	ds_read_b128 v[92:95], v134
	ds_read_b128 v[160:163], v100 offset:19456
	ds_read_b128 v[164:167], v100 offset:18432
	ds_read_b128 v[168:171], v100 offset:17408
	ds_read_b128 v[184:187], v100 offset:16384
	s_setprio 1
	s_waitcnt lgkmcnt(0)
	v_mfma_f32_16x16x32_bf16 v[124:127], v[184:187], v[92:95], v[124:127]
	v_mfma_f32_16x16x32_bf16 v[120:123], v[168:171], v[92:95], v[120:123]
	v_mfma_f32_16x16x32_bf16 v[116:119], v[164:167], v[92:95], v[116:119]
	v_mfma_f32_16x16x32_bf16 v[112:115], v[160:163], v[92:95], v[112:115]
	v_mfma_f32_16x16x32_bf16 v[108:111], v[184:187], v[88:91], v[108:111]
	v_mfma_f32_16x16x32_bf16 v[104:107], v[168:171], v[88:91], v[96:99]
	v_mfma_f32_16x16x32_bf16 v[100:103], v[164:167], v[88:91], v[84:87]
	v_mfma_f32_16x16x32_bf16 v[96:99], v[160:163], v[88:91], v[80:83]
	v_mfma_f32_16x16x32_bf16 v[92:95], v[184:187], v[156:159], v[76:79]
	v_mfma_f32_16x16x32_bf16 v[88:91], v[168:171], v[156:159], v[72:75]
	v_mfma_f32_16x16x32_bf16 v[84:87], v[164:167], v[156:159], v[68:71]
	v_mfma_f32_16x16x32_bf16 v[80:83], v[160:163], v[156:159], v[64:67]
	v_mfma_f32_16x16x32_bf16 v[76:79], v[184:187], v[152:155], v[60:63]
	v_mfma_f32_16x16x32_bf16 v[72:75], v[168:171], v[152:155], v[56:59]
	v_mfma_f32_16x16x32_bf16 v[68:71], v[164:167], v[152:155], v[52:55]
	v_mfma_f32_16x16x32_bf16 v[64:67], v[160:163], v[152:155], v[48:51]
	s_setprio 0
	s_nop 1
	ds_read_b128 v[48:51], v134 offset:4096
	ds_read_b128 v[152:155], v134 offset:5120
	ds_read_b128 v[156:159], v134 offset:6144
	ds_read_b128 v[188:191], v134 offset:7168
	s_setprio 1
	s_waitcnt lgkmcnt(3)
	v_mfma_f32_16x16x32_bf16 v[60:63], v[184:187], v[48:51], v[44:47]
	v_mfma_f32_16x16x32_bf16 v[56:59], v[168:171], v[48:51], v[40:43]
	v_mfma_f32_16x16x32_bf16 v[52:55], v[164:167], v[48:51], v[36:39]
	v_mfma_f32_16x16x32_bf16 v[48:51], v[160:163], v[48:51], v[32:35]
	s_waitcnt lgkmcnt(2)
	v_mfma_f32_16x16x32_bf16 v[44:47], v[184:187], v[152:155], v[28:31]
	v_mfma_f32_16x16x32_bf16 v[40:43], v[168:171], v[152:155], v[24:27]
	v_mfma_f32_16x16x32_bf16 v[36:39], v[164:167], v[152:155], v[20:23]
	v_mfma_f32_16x16x32_bf16 v[32:35], v[160:163], v[152:155], v[16:19]
	s_waitcnt lgkmcnt(1)
	v_mfma_f32_16x16x32_bf16 v[28:31], v[184:187], v[156:159], v[12:15]
	v_mfma_f32_16x16x32_bf16 v[24:27], v[168:171], v[156:159], v[8:11]
	v_mfma_f32_16x16x32_bf16 v[20:23], v[164:167], v[156:159], v[4:7]
	v_mfma_f32_16x16x32_bf16 v[16:19], v[160:163], v[156:159], v[0:3]
	s_waitcnt lgkmcnt(0)
	v_mfma_f32_16x16x32_bf16 v[12:15], v[184:187], v[188:191], v[136:139]
	v_mfma_f32_16x16x32_bf16 v[8:11], v[168:171], v[188:191], v[140:143]
	v_mfma_f32_16x16x32_bf16 v[4:7], v[164:167], v[188:191], v[144:147]
	v_mfma_f32_16x16x32_bf16 v[0:3], v[160:163], v[188:191], v[148:151]
	s_setprio 0
	s_add_i32 s3, s2, 1
	s_cmp_lg_u32 s2, 2
	s_cselect_b32 s50, s3, 0
	s_and_b64 vcc, exec, s[30:31]
	s_cbranch_vccz .LBB0_246
; DEVI int opaque_tid() { int t = (int)threadIdx.x; asm volatile("" : "+v"(t)); return t; }
; DEVI void g2_issue(const G2Tile& t, int kt, int st, char* smem) {
;     const int tid = opaque_tid(), lane = tid & 63, w = tid >> 6;
;     const int rr = lane >> 2, sch = (lane & 3) ^ ((lane >> 5) << 1);
;     const bf16_t* ap = t.A + (size_t)kt * 32 + (size_t)(w * 16 + rr) * t.lda + sch * 8;
;     const bf16_t* bp = t.Bt + (size_t)kt * 32 + (size_t)(w * 16 + rr) * t.ldb + sch * 8;
;     char* sa = smem + st * 24576 + w * 1024 + lane * 16;
; #pragma unroll
;     for (int i = 0; i < 4; ++i) __builtin_amdgcn_global_load_lds((const unsigned*)(ap + (size_t)(64 * i) * t.lda), (unsigned*)(sa + i * 4096), 16, 0, 0);
; #pragma unroll
;     for (int i = 0; i < 2; ++i) __builtin_amdgcn_global_load_lds((const unsigned*)(bp + (size_t)(64 * i) * t.ldb), (unsigned*)(sa + 16384 + i * 4096), 16, 0, 0);
; }
; DEVI void g2_prologue(const G2Tile& t, int st, char* smem) {
;     g2_issue(t, 0, st, smem);
;     g2_issue(t, 1, st == 2 ? 0 : st + 1, smem);
	v_mov_b32_e32 v128, v172
	s_mul_i32 s2, s50, 0x6000
	v_ashrrev_i32_e32 v139, 6, v128
	v_bfe_u32 v134, v128, 2, 4
	v_and_b32_e32 v138, 63, v128
	v_and_b32_e32 v135, 3, v128
	v_lshrrev_b32_e32 v128, 4, v128
	v_lshl_or_b32 v134, v139, 4, v134
	v_bitop3_b32 v128, v128, v135, 2 bitop3:0x6c
	v_ashrrev_i32_e32 v135, 31, v134
	s_add_i32 s3, s2, 0
	v_lshlrev_b32_e32 v139, 10, v139
	v_lshlrev_b32_e32 v138, 4, v138
	v_lshlrev_b64 v[134:135], 11, v[134:135]
	v_add3_u32 v140, s3, v139, v138
	v_lshl_add_u64 v[136:137], s[0:1], 0, v[134:135]
	v_lshlrev_b32_e32 v128, 4, v128
	v_readfirstlane_b32 s3, v140
	v_add_u32_e32 v141, 0x1000, v140
	v_lshl_add_u64 v[136:137], v[136:137], 0, v[128:129]
	s_mov_b32 m0, s3
	v_readfirstlane_b32 s3, v141
	v_add_u32_e32 v141, 0x2000, v140
	global_load_lds_dwordx4 v[136:137], off
	v_lshl_add_u64 v[138:139], v[136:137], 0, s[22:23]
	s_mov_b32 m0, s3
	v_readfirstlane_b32 s3, v141
	global_load_lds_dwordx4 v[138:139], off
	v_lshl_add_u64 v[138:139], v[136:137], 0, s[24:25]
	s_mov_b32 m0, s3
	v_lshl_add_u64 v[134:135], s[20:21], 0, v[134:135]
	global_load_lds_dwordx4 v[138:139], off
	v_add_u32_e32 v138, 0x3000, v140
	v_lshl_add_u64 v[134:135], v[134:135], 0, v[128:129]
	v_readfirstlane_b32 s3, v138
	v_add_u32_e32 v128, 0x4000, v140
	v_lshl_add_u64 v[136:137], v[136:137], 0, s[28:29]
	s_mov_b32 m0, s3
	v_readfirstlane_b32 s3, v128
	v_add_u32_e32 v128, 0x5000, v140
	global_load_lds_dwordx4 v[136:137], off
	s_mov_b32 m0, s3
	v_readfirstlane_b32 s3, v128
	global_load_lds_dwordx4 v[134:135], off
	v_lshl_add_u64 v[134:135], v[134:135], 0, s[22:23]
	s_mov_b32 m0, s3
	v_mov_b32_e32 v128, v172
	global_load_lds_dwordx4 v[134:135], off
	s_addk_i32 s2, 0x6000
	v_ashrrev_i32_e32 v141, 6, v128
	v_bfe_u32 v134, v128, 2, 4
	v_and_b32_e32 v140, 63, v128
	v_and_b32_e32 v135, 3, v128
	v_lshrrev_b32_e32 v128, 4, v128
	v_lshl_or_b32 v134, v141, 4, v134
	s_cmp_lg_u32 s50, 2
	v_bitop3_b32 v128, v128, v135, 2 bitop3:0x6c
	v_ashrrev_i32_e32 v135, 31, v134
	s_cselect_b32 s2, s2, 0
	v_lshlrev_b64 v[134:135], 11, v[134:135]
	s_add_i32 s2, s2, 0
	v_lshlrev_b32_e32 v141, 10, v141
	v_lshlrev_b32_e32 v140, 4, v140
	v_lshl_add_u64 v[136:137], s[0:1], 0, v[134:135]
	v_lshlrev_b32_e32 v128, 4, v128
	v_add3_u32 v140, s2, v141, v140
	v_lshl_add_u64 v[136:137], v[136:137], 0, v[128:129]
	v_readfirstlane_b32 s2, v140
	v_add_u32_e32 v141, 0x1000, v140
	v_lshl_add_u64 v[138:139], v[136:137], 0, 64
	s_mov_b32 m0, s2
	v_readfirstlane_b32 s2, v141
	v_add_u32_e32 v141, 0x2000, v140
	global_load_lds_dwordx4 v[138:139], off
	v_lshl_add_u64 v[138:139], v[136:137], 0, s[58:59]
	s_mov_b32 m0, s2
	v_readfirstlane_b32 s2, v141
	global_load_lds_dwordx4 v[138:139], off
	v_lshl_add_u64 v[138:139], v[136:137], 0, s[60:61]
	s_mov_b32 m0, s2
	v_lshl_add_u64 v[134:135], s[20:21], 0, v[134:135]
	global_load_lds_dwordx4 v[138:139], off
	v_add_u32_e32 v138, 0x3000, v140
	v_lshl_add_u64 v[134:135], v[134:135], 0, v[128:129]
	v_readfirstlane_b32 s2, v138
	v_add_u32_e32 v128, 0x4000, v140
	v_lshl_add_u64 v[136:137], v[136:137], 0, s[62:63]
	s_mov_b32 m0, s2
	v_readfirstlane_b32 s2, v128
	v_add_u32_e32 v128, 0x5000, v140
	global_load_lds_dwordx4 v[136:137], off
	v_lshl_add_u64 v[136:137], v[134:135], 0, 64
	s_mov_b32 m0, s2
	v_readfirstlane_b32 s2, v128
	global_load_lds_dwordx4 v[136:137], off
	v_lshl_add_u64 v[134:135], v[134:135], 0, s[58:59]
	s_mov_b32 m0, s2
	s_nop 0
	global_load_lds_dwordx4 v[134:135], off

; DEVI int opaque_tid() { int t = (int)threadIdx.x; asm volatile("" : "+v"(t)); return t; }
; DEVI void g2_issue(const G2Tile& t, int kt, int st, char* smem) {
;     const int tid = opaque_tid(), lane = tid & 63, w = tid >> 6;
;     const int rr = lane >> 2, sch = (lane & 3) ^ ((lane >> 5) << 1);
;     const bf16_t* ap = t.A + (size_t)kt * 32 + (size_t)(w * 16 + rr) * t.lda + sch * 8;
;     const bf16_t* bp = t.Bt + (size_t)kt * 32 + (size_t)(w * 16 + rr) * t.ldb + sch * 8;
;     char* sa = smem + st * 24576 + w * 1024 + lane * 16;
; #pragma unroll
;     for (int i = 0; i < 4; ++i) __builtin_amdgcn_global_load_lds((const unsigned*)(ap + (size_t)(64 * i) * t.lda), (unsigned*)(sa + i * 4096), 16, 0, 0);
; #pragma unroll
;     for (int i = 0; i < 2; ++i) __builtin_amdgcn_global_load_lds((const unsigned*)(bp + (size_t)(64 * i) * t.ldb), (unsigned*)(sa + 16384 + i * 4096), 16, 0, 0);
; template <bool TRANS, class Epi>
; DEVI int g2_body(const G2Tile& t, int st, char* smem, bool has_next, const G2Tile& nxt, const Epi& epi) {
;     ...
;     for (int kt = 0; kt < nk; ++kt) {
;         if (kt + 1 < nk) asm volatile("s_waitcnt vmcnt(6)" ::: "memory");
;         else asm volatile("s_waitcnt vmcnt(0)" ::: "memory");
;         __syncthreads();
;         if (kt + 2 < nk) g2_issue(t, kt + 2, st >= 1 ? st - 1 : 2, smem);
;         const char* sa = smem + st * 24576 + frag;
;         bf16x8 bfr[4];
; #pragma unroll
;         for (int n = 0; n < 4; ++n) bfr[n] = *(const bf16x8*)(sa + (16 + wc * 4 + n) * 1024);
; #pragma unroll
;         for (int mh = 0; mh < 2; ++mh) {
;             bf16x8 af[4];
; #pragma unroll
;             for (int m = 0; m < 4; ++m) af[m] = *(const bf16x8*)(sa + (wr * 8 + mh * 4 + m) * 1024);
;             __builtin_amdgcn_s_setprio(1);
; #pragma unroll
;             for (int m = 0; m < 4; ++m)
; #pragma unroll
;                 for (int n = 0; n < 4; ++n)
;                     acc[mh * 4 + m][n] = TRANS ? __builtin_amdgcn_mfma_f32_16x16x32_bf16(bfr[n], af[m], acc[mh * 4 + m][n], 0, 0, 0)
;                                                : __builtin_amdgcn_mfma_f32_16x16x32_bf16(af[m], bfr[n], acc[mh * 4 + m][n], 0, 0, 0);
;             __builtin_amdgcn_s_setprio(0);
;         }
;         st = st == 2 ? 0 : st + 1;
;     }
.LBB0_281:
	v_mov_b32_e32 v136, v172
	s_waitcnt vmcnt(6)
	s_waitcnt lgkmcnt(0)
	s_barrier
	s_mul_i32 s4, s43, 0x6000
	v_and_b32_e32 v142, 63, v136
	v_ashrrev_i32_e32 v143, 6, v136
	v_bfe_u32 v137, v136, 2, 4
	v_and_b32_e32 v138, 3, v136
	v_lshrrev_b32_e32 v136, 4, v136
	s_add_i32 s5, s4, 0xffffa000
	v_bitop3_b32 v138, v136, v138, 2 bitop3:0x6c
	v_lshl_or_b32 v136, v143, 4, v137
	s_cmp_gt_i32 s43, 0
	v_ashrrev_i32_e32 v137, 31, v136
	v_lshlrev_b64 v[136:137], 11, v[136:137]
	s_cselect_b32 s5, s5, 0xc000
	v_lshl_or_b32 v136, v138, 4, v136
	s_add_i32 s5, s5, 0
	v_lshlrev_b32_e32 v143, 10, v143
	v_lshlrev_b32_e32 v142, 4, v142
	v_lshl_add_u64 v[136:137], s[2:3], 0, v[136:137]
	v_add3_u32 v142, s5, v143, v142
	v_lshl_add_u64 v[138:139], s[96:97], 0, v[136:137]
	v_readfirstlane_b32 s5, v142
	v_add_u32_e32 v143, 0x1000, v142
	v_lshl_add_u64 v[140:141], v[138:139], 0, s[6:7]
	s_mov_b32 m0, s5
	v_readfirstlane_b32 s5, v143
	v_add_u32_e32 v143, 0x2000, v142
	global_load_lds_dwordx4 v[140:141], off
	v_lshl_add_u64 v[140:141], v[138:139], 0, s[8:9]
	s_mov_b32 m0, s5
	v_readfirstlane_b32 s5, v143
	global_load_lds_dwordx4 v[140:141], off
	v_lshl_add_u64 v[140:141], v[138:139], 0, s[10:11]
	s_mov_b32 m0, s5
	v_lshl_add_u64 v[138:139], v[138:139], 0, s[12:13]
	global_load_lds_dwordx4 v[140:141], off
	v_add_u32_e32 v140, 0x3000, v142
	v_lshl_add_u64 v[136:137], s[92:93], 0, v[136:137]
	v_readfirstlane_b32 s5, v140
	v_add_u32_e32 v140, 0x4000, v142
	s_mov_b32 m0, s5
	v_readfirstlane_b32 s5, v140
	global_load_lds_dwordx4 v[138:139], off
	v_lshl_add_u64 v[138:139], v[136:137], 0, s[6:7]
	s_mov_b32 m0, s5
	v_lshl_add_u64 v[136:137], v[136:137], 0, s[8:9]
	global_load_lds_dwordx4 v[138:139], off
	v_add_u32_e32 v138, 0x5000, v142
	v_add_u32_e32 v152, s4, v134
	v_readfirstlane_b32 s5, v138
	s_mov_b32 m0, s5
	v_add_u32_e32 v148, v152, v128
	global_load_lds_dwordx4 v[136:137], off
	v_add_u32_e32 v168, v152, v135
	ds_read_b128 v[136:139], v148 offset:16384
	ds_read_b128 v[140:143], v148 offset:17408
	ds_read_b128 v[144:147], v148 offset:18432
	ds_read_b128 v[148:151], v148 offset:19456
	ds_read_b128 v[152:155], v168
	ds_read_b128 v[156:159], v168 offset:1024
	ds_read_b128 v[160:163], v168 offset:2048
	ds_read_b128 v[164:167], v168 offset:3072
	s_setprio 1
	s_waitcnt lgkmcnt(0)
	v_mfma_f32_16x16x32_bf16 v[124:127], v[152:155], v[136:139], v[124:127]
	v_mfma_f32_16x16x32_bf16 v[120:123], v[152:155], v[140:143], v[120:123]
	v_mfma_f32_16x16x32_bf16 v[116:119], v[152:155], v[144:147], v[116:119]
	v_mfma_f32_16x16x32_bf16 v[112:115], v[152:155], v[148:151], v[112:115]
	v_mfma_f32_16x16x32_bf16 v[108:111], v[156:159], v[136:139], v[108:111]
	v_mfma_f32_16x16x32_bf16 v[96:99], v[156:159], v[140:143], v[96:99]
	v_mfma_f32_16x16x32_bf16 v[84:87], v[156:159], v[144:147], v[84:87]
	v_mfma_f32_16x16x32_bf16 v[80:83], v[156:159], v[148:151], v[80:83]
	v_mfma_f32_16x16x32_bf16 v[76:79], v[160:163], v[136:139], v[76:79]
	v_mfma_f32_16x16x32_bf16 v[72:75], v[160:163], v[140:143], v[72:75]
	v_mfma_f32_16x16x32_bf16 v[68:71], v[160:163], v[144:147], v[68:71]
	v_mfma_f32_16x16x32_bf16 v[64:67], v[160:163], v[148:151], v[64:67]
	v_mfma_f32_16x16x32_bf16 v[60:63], v[164:167], v[136:139], v[60:63]
	v_mfma_f32_16x16x32_bf16 v[56:59], v[164:167], v[140:143], v[56:59]
	v_mfma_f32_16x16x32_bf16 v[52:55], v[164:167], v[144:147], v[52:55]
	v_mfma_f32_16x16x32_bf16 v[48:51], v[164:167], v[148:151], v[48:51]
	s_setprio 0
	ds_read_b128 v[152:155], v168 offset:4096
	ds_read_b128 v[156:159], v168 offset:5120
	ds_read_b128 v[160:163], v168 offset:6144
	ds_read_b128 v[164:167], v168 offset:7168
	s_setprio 1
	s_waitcnt lgkmcnt(0)
	v_mfma_f32_16x16x32_bf16 v[44:47], v[152:155], v[136:139], v[44:47]
	v_mfma_f32_16x16x32_bf16 v[40:43], v[152:155], v[140:143], v[40:43]
	v_mfma_f32_16x16x32_bf16 v[36:39], v[152:155], v[144:147], v[36:39]
	v_mfma_f32_16x16x32_bf16 v[32:35], v[152:155], v[148:151], v[32:35]
	v_mfma_f32_16x16x32_bf16 v[28:31], v[156:159], v[136:139], v[28:31]
	v_mfma_f32_16x16x32_bf16 v[24:27], v[156:159], v[140:143], v[24:27]
	v_mfma_f32_16x16x32_bf16 v[20:23], v[156:159], v[144:147], v[20:23]
	v_mfma_f32_16x16x32_bf16 v[16:19], v[156:159], v[148:151], v[16:19]
	v_mfma_f32_16x16x32_bf16 v[12:15], v[160:163], v[136:139], v[12:15]
	v_mfma_f32_16x16x32_bf16 v[8:11], v[160:163], v[140:143], v[8:11]
	v_mfma_f32_16x16x32_bf16 v[4:7], v[160:163], v[144:147], v[4:7]
	v_mfma_f32_16x16x32_bf16 v[0:3], v[160:163], v[148:151], v[0:3]
	v_mfma_f32_16x16x32_bf16 v[88:91], v[164:167], v[136:139], v[88:91]
	v_mfma_f32_16x16x32_bf16 v[92:95], v[164:167], v[140:143], v[92:95]
	v_mfma_f32_16x16x32_bf16 v[100:103], v[164:167], v[144:147], v[100:103]
	v_mfma_f32_16x16x32_bf16 v[104:107], v[164:167], v[148:151], v[104:107]
	s_setprio 0
	s_add_i32 s4, s43, 1
	s_cmp_lg_u32 s43, 2
	s_cselect_b32 s43, s4, 0
	s_add_u32 s2, s2, 64
	s_addc_u32 s3, s3, 0
	s_cmpk_eq_i32 s2, 0x780
	s_cbranch_scc0 .LBB0_281
	s_mul_i32 s2, s43, 0x6000
	v_add_u32_e32 v152, s2, v134
	v_add_u32_e32 v148, v152, v128
	v_add_u32_e32 v168, v152, v135
	s_waitcnt vmcnt(6)
	s_barrier
; template <bool TRANS, class Epi>
; DEVI int g2_body(const G2Tile& t, int st, char* smem, bool has_next, const G2Tile& nxt, const Epi& epi) {
;     ...
;     for (int kt = 0; kt < nk; ++kt) {
;         if (kt + 1 < nk) asm volatile("s_waitcnt vmcnt(6)" ::: "memory");
;         else asm volatile("s_waitcnt vmcnt(0)" ::: "memory");
;         __syncthreads();
;         if (kt + 2 < nk) g2_issue(t, kt + 2, st >= 1 ? st - 1 : 2, smem);
;         const char* sa = smem + st * 24576 + frag;
;         bf16x8 bfr[4];
; #pragma unroll
;         for (int n = 0; n < 4; ++n) bfr[n] = *(const bf16x8*)(sa + (16 + wc * 4 + n) * 1024);
; #pragma unroll
;         for (int mh = 0; mh < 2; ++mh) {
;             bf16x8 af[4];
; #pragma unroll
;             for (int m = 0; m < 4; ++m) af[m] = *(const bf16x8*)(sa + (wr * 8 + mh * 4 + m) * 1024);
;             __builtin_amdgcn_s_setprio(1);
; #pragma unroll
;             for (int m = 0; m < 4; ++m)
; #pragma unroll
;                 for (int n = 0; n < 4; ++n)
;                     acc[mh * 4 + m][n] = TRANS ? __builtin_amdgcn_mfma_f32_16x16x32_bf16(bfr[n], af[m], acc[mh * 4 + m][n], 0, 0, 0)
;                                                : __builtin_amdgcn_mfma_f32_16x16x32_bf16(af[m], bfr[n], acc[mh * 4 + m][n], 0, 0, 0);
;             __builtin_amdgcn_s_setprio(0);
;         }
;         st = st == 2 ? 0 : st + 1;
	ds_read_b128 v[136:139], v148 offset:16384
	ds_read_b128 v[140:143], v148 offset:17408
	ds_read_b128 v[144:147], v148 offset:18432
	ds_read_b128 v[148:151], v148 offset:19456
	ds_read_b128 v[152:155], v168
	ds_read_b128 v[156:159], v168 offset:1024
	ds_read_b128 v[160:163], v168 offset:2048
	ds_read_b128 v[164:167], v168 offset:3072
	s_setprio 1
	s_waitcnt lgkmcnt(3)
	v_mfma_f32_16x16x32_bf16 v[124:127], v[152:155], v[136:139], v[124:127]
	v_mfma_f32_16x16x32_bf16 v[120:123], v[152:155], v[140:143], v[120:123]
	v_mfma_f32_16x16x32_bf16 v[116:119], v[152:155], v[144:147], v[116:119]
	v_mfma_f32_16x16x32_bf16 v[112:115], v[152:155], v[148:151], v[112:115]
	s_waitcnt lgkmcnt(2)
	v_mfma_f32_16x16x32_bf16 v[108:111], v[156:159], v[136:139], v[108:111]
	v_mfma_f32_16x16x32_bf16 v[96:99], v[156:159], v[140:143], v[96:99]
	v_mfma_f32_16x16x32_bf16 v[84:87], v[156:159], v[144:147], v[84:87]
	v_mfma_f32_16x16x32_bf16 v[80:83], v[156:159], v[148:151], v[80:83]
	s_waitcnt lgkmcnt(1)
	v_mfma_f32_16x16x32_bf16 v[76:79], v[160:163], v[136:139], v[76:79]
	v_mfma_f32_16x16x32_bf16 v[72:75], v[160:163], v[140:143], v[72:75]
	v_mfma_f32_16x16x32_bf16 v[68:71], v[160:163], v[144:147], v[68:71]
	v_mfma_f32_16x16x32_bf16 v[64:67], v[160:163], v[148:151], v[64:67]
	s_waitcnt lgkmcnt(0)
	v_mfma_f32_16x16x32_bf16 v[60:63], v[164:167], v[136:139], v[60:63]
	v_mfma_f32_16x16x32_bf16 v[56:59], v[164:167], v[140:143], v[56:59]
	v_mfma_f32_16x16x32_bf16 v[52:55], v[164:167], v[144:147], v[52:55]
	v_mfma_f32_16x16x32_bf16 v[48:51], v[164:167], v[148:151], v[48:51]
	s_setprio 0
	ds_read_b128 v[152:155], v168 offset:4096
	ds_read_b128 v[156:159], v168 offset:5120
	ds_read_b128 v[160:163], v168 offset:6144
	ds_read_b128 v[164:167], v168 offset:7168
	s_setprio 1
	s_waitcnt lgkmcnt(3)
	v_mfma_f32_16x16x32_bf16 v[44:47], v[152:155], v[136:139], v[44:47]
	v_mfma_f32_16x16x32_bf16 v[40:43], v[152:155], v[140:143], v[40:43]
	v_mfma_f32_16x16x32_bf16 v[36:39], v[152:155], v[144:147], v[36:39]
	v_mfma_f32_16x16x32_bf16 v[32:35], v[152:155], v[148:151], v[32:35]
	s_waitcnt lgkmcnt(2)
	v_mfma_f32_16x16x32_bf16 v[28:31], v[156:159], v[136:139], v[28:31]
	v_mfma_f32_16x16x32_bf16 v[24:27], v[156:159], v[140:143], v[24:27]
	v_mfma_f32_16x16x32_bf16 v[20:23], v[156:159], v[144:147], v[20:23]
	v_mfma_f32_16x16x32_bf16 v[16:19], v[156:159], v[148:151], v[16:19]
	s_waitcnt lgkmcnt(1)
	v_mfma_f32_16x16x32_bf16 v[12:15], v[160:163], v[136:139], v[12:15]
	v_mfma_f32_16x16x32_bf16 v[8:11], v[160:163], v[140:143], v[8:11]
	v_mfma_f32_16x16x32_bf16 v[4:7], v[160:163], v[144:147], v[4:7]
	v_mfma_f32_16x16x32_bf16 v[0:3], v[160:163], v[148:151], v[0:3]
	s_waitcnt lgkmcnt(0)
	v_mfma_f32_16x16x32_bf16 v[136:139], v[164:167], v[136:139], v[88:91]
	v_mfma_f32_16x16x32_bf16 v[140:143], v[164:167], v[140:143], v[92:95]
	v_mfma_f32_16x16x32_bf16 v[144:147], v[164:167], v[144:147], v[100:103]
	v_mfma_f32_16x16x32_bf16 v[148:151], v[164:167], v[148:151], v[104:107]
	s_setprio 0
	s_add_i32 s2, s43, 1
	s_cmp_lg_u32 s43, 2
	s_cselect_b32 s2, s2, 0
	s_mul_i32 s3, s2, 0x6000
	v_add_u32_e32 v100, s3, v134
	v_add_u32_e32 v134, v100, v135
	v_add_u32_e32 v100, v100, v128
	s_waitcnt vmcnt(0)
	s_barrier
	ds_read_b128 v[152:155], v134 offset:3072
	ds_read_b128 v[156:159], v134 offset:2048
	ds_read_b128 v[88:91], v134 offset:1024
	ds_read_b128 v[92:95], v134
	ds_read_b128 v[160:163], v100 offset:19456
	ds_read_b128 v[164:167], v100 offset:18432
	ds_read_b128 v[168:171], v100 offset:17408
	ds_read_b128 v[184:187], v100 offset:16384
	s_setprio 1
	s_waitcnt lgkmcnt(0)
	v_mfma_f32_16x16x32_bf16 v[124:127], v[92:95], v[184:187], v[124:127]
	v_mfma_f32_16x16x32_bf16 v[120:123], v[92:95], v[168:171], v[120:123]
	v_mfma_f32_16x16x32_bf16 v[116:119], v[92:95], v[164:167], v[116:119]
	v_mfma_f32_16x16x32_bf16 v[112:115], v[92:95], v[160:163], v[112:115]
	v_mfma_f32_16x16x32_bf16 v[108:111], v[88:91], v[184:187], v[108:111]
	v_mfma_f32_16x16x32_bf16 v[104:107], v[88:91], v[168:171], v[96:99]
	v_mfma_f32_16x16x32_bf16 v[100:103], v[88:91], v[164:167], v[84:87]
	v_mfma_f32_16x16x32_bf16 v[96:99], v[88:91], v[160:163], v[80:83]
	v_mfma_f32_16x16x32_bf16 v[92:95], v[156:159], v[184:187], v[76:79]
	v_mfma_f32_16x16x32_bf16 v[88:91], v[156:159], v[168:171], v[72:75]
	v_mfma_f32_16x16x32_bf16 v[84:87], v[156:159], v[164:167], v[68:71]
	v_mfma_f32_16x16x32_bf16 v[80:83], v[156:159], v[160:163], v[64:67]
	v_mfma_f32_16x16x32_bf16 v[76:79], v[152:155], v[184:187], v[60:63]
	v_mfma_f32_16x16x32_bf16 v[72:75], v[152:155], v[168:171], v[56:59]
	v_mfma_f32_16x16x32_bf16 v[68:71], v[152:155], v[164:167], v[52:55]
	v_mfma_f32_16x16x32_bf16 v[64:67], v[152:155], v[160:163], v[48:51]
	s_setprio 0
	s_nop 1
	ds_read_b128 v[48:51], v134 offset:4096
	ds_read_b128 v[152:155], v134 offset:5120
	ds_read_b128 v[156:159], v134 offset:6144
	ds_read_b128 v[188:191], v134 offset:7168
	s_setprio 1
	s_waitcnt lgkmcnt(3)
	v_mfma_f32_16x16x32_bf16 v[60:63], v[48:51], v[184:187], v[44:47]
	v_mfma_f32_16x16x32_bf16 v[56:59], v[48:51], v[168:171], v[40:43]
	v_mfma_f32_16x16x32_bf16 v[52:55], v[48:51], v[164:167], v[36:39]
	v_mfma_f32_16x16x32_bf16 v[48:51], v[48:51], v[160:163], v[32:35]
	s_waitcnt lgkmcnt(2)
	v_mfma_f32_16x16x32_bf16 v[44:47], v[152:155], v[184:187], v[28:31]
	v_mfma_f32_16x16x32_bf16 v[40:43], v[152:155], v[168:171], v[24:27]
	v_mfma_f32_16x16x32_bf16 v[36:39], v[152:155], v[164:167], v[20:23]
	v_mfma_f32_16x16x32_bf16 v[32:35], v[152:155], v[160:163], v[16:19]
	s_waitcnt lgkmcnt(1)
	v_mfma_f32_16x16x32_bf16 v[28:31], v[156:159], v[184:187], v[12:15]
	v_mfma_f32_16x16x32_bf16 v[24:27], v[156:159], v[168:171], v[8:11]
	v_mfma_f32_16x16x32_bf16 v[20:23], v[156:159], v[164:167], v[4:7]
	v_mfma_f32_16x16x32_bf16 v[16:19], v[156:159], v[160:163], v[0:3]
	s_waitcnt lgkmcnt(0)
	v_mfma_f32_16x16x32_bf16 v[12:15], v[188:191], v[184:187], v[136:139]
	v_mfma_f32_16x16x32_bf16 v[8:11], v[188:191], v[168:171], v[140:143]
	v_mfma_f32_16x16x32_bf16 v[4:7], v[188:191], v[164:167], v[144:147]
	v_mfma_f32_16x16x32_bf16 v[0:3], v[188:191], v[160:163], v[148:151]
	s_setprio 0
	s_add_i32 s3, s2, 1
	s_cmp_lg_u32 s2, 2
	s_cselect_b32 s50, s3, 0
	s_and_b64 vcc, exec, s[30:31]
	s_cbranch_vccz .LBB0_284
; DEVI int opaque_tid() { int t = (int)threadIdx.x; asm volatile("" : "+v"(t)); return t; }
; DEVI void g2_issue(const G2Tile& t, int kt, int st, char* smem) {
;     const int tid = opaque_tid(), lane = tid & 63, w = tid >> 6;
;     const int rr = lane >> 2, sch = (lane & 3) ^ ((lane >> 5) << 1);
;     const bf16_t* ap = t.A + (size_t)kt * 32 + (size_t)(w * 16 + rr) * t.lda + sch * 8;
;     const bf16_t* bp = t.Bt + (size_t)kt * 32 + (size_t)(w * 16 + rr) * t.ldb + sch * 8;
;     char* sa = smem + st * 24576 + w * 1024 + lane * 16;
; #pragma unroll
;     for (int i = 0; i < 4; ++i) __builtin_amdgcn_global_load_lds((const unsigned*)(ap + (size_t)(64 * i) * t.lda), (unsigned*)(sa + i * 4096), 16, 0, 0);
; #pragma unroll
;     for (int i = 0; i < 2; ++i) __builtin_amdgcn_global_load_lds((const unsigned*)(bp + (size_t)(64 * i) * t.ldb), (unsigned*)(sa + 16384 + i * 4096), 16, 0, 0);
; }
; DEVI void g2_prologue(const G2Tile& t, int st, char* smem) {
;     g2_issue(t, 0, st, smem);
;     g2_issue(t, 1, st == 2 ? 0 : st + 1, smem);
	v_mov_b32_e32 v128, v172
	s_mul_i32 s2, s50, 0x6000
	v_ashrrev_i32_e32 v139, 6, v128
	v_bfe_u32 v134, v128, 2, 4
	v_and_b32_e32 v138, 63, v128
	v_and_b32_e32 v135, 3, v128
	v_lshrrev_b32_e32 v128, 4, v128
	v_lshl_or_b32 v134, v139, 4, v134
	v_bitop3_b32 v128, v128, v135, 2 bitop3:0x6c
	v_ashrrev_i32_e32 v135, 31, v134
	s_add_i32 s3, s2, 0
	v_lshlrev_b32_e32 v139, 10, v139
	v_lshlrev_b32_e32 v138, 4, v138
	v_lshlrev_b64 v[134:135], 11, v[134:135]
	v_add3_u32 v140, s3, v139, v138
	v_lshl_add_u64 v[136:137], s[0:1], 0, v[134:135]
	v_lshlrev_b32_e32 v128, 4, v128
	v_readfirstlane_b32 s3, v140
	v_add_u32_e32 v141, 0x1000, v140
	v_lshl_add_u64 v[136:137], v[136:137], 0, v[128:129]
	s_mov_b32 m0, s3
	v_readfirstlane_b32 s3, v141
	v_add_u32_e32 v141, 0x2000, v140
	global_load_lds_dwordx4 v[136:137], off
	v_lshl_add_u64 v[138:139], v[136:137], 0, s[22:23]
	s_mov_b32 m0, s3
	v_readfirstlane_b32 s3, v141
	global_load_lds_dwordx4 v[138:139], off
	v_lshl_add_u64 v[138:139], v[136:137], 0, s[24:25]
	s_mov_b32 m0, s3
	v_lshl_add_u64 v[134:135], s[20:21], 0, v[134:135]
	global_load_lds_dwordx4 v[138:139], off
	v_add_u32_e32 v138, 0x3000, v140
	v_lshl_add_u64 v[134:135], v[134:135], 0, v[128:129]
	v_readfirstlane_b32 s3, v138
	v_add_u32_e32 v128, 0x4000, v140
	v_lshl_add_u64 v[136:137], v[136:137], 0, s[28:29]
	s_mov_b32 m0, s3
	v_readfirstlane_b32 s3, v128
	v_add_u32_e32 v128, 0x5000, v140
	global_load_lds_dwordx4 v[136:137], off
	s_mov_b32 m0, s3
	v_readfirstlane_b32 s3, v128
	global_load_lds_dwordx4 v[134:135], off
	v_lshl_add_u64 v[134:135], v[134:135], 0, s[22:23]
	s_mov_b32 m0, s3
	v_mov_b32_e32 v128, v172
	global_load_lds_dwordx4 v[134:135], off
	s_addk_i32 s2, 0x6000
	v_ashrrev_i32_e32 v141, 6, v128
	v_bfe_u32 v134, v128, 2, 4
	v_and_b32_e32 v140, 63, v128
	v_and_b32_e32 v135, 3, v128
	v_lshrrev_b32_e32 v128, 4, v128
	v_lshl_or_b32 v134, v141, 4, v134
	s_cmp_lg_u32 s50, 2
	v_bitop3_b32 v128, v128, v135, 2 bitop3:0x6c
	v_ashrrev_i32_e32 v135, 31, v134
	s_cselect_b32 s2, s2, 0
	v_lshlrev_b64 v[134:135], 11, v[134:135]
	s_add_i32 s2, s2, 0
	v_lshlrev_b32_e32 v141, 10, v141
	v_lshlrev_b32_e32 v140, 4, v140
	v_lshl_add_u64 v[136:137], s[0:1], 0, v[134:135]
	v_lshlrev_b32_e32 v128, 4, v128
	v_add3_u32 v140, s2, v141, v140
	v_lshl_add_u64 v[136:137], v[136:137], 0, v[128:129]
	v_readfirstlane_b32 s2, v140
	v_add_u32_e32 v141, 0x1000, v140
	v_lshl_add_u64 v[138:139], v[136:137], 0, 64
	s_mov_b32 m0, s2
	v_readfirstlane_b32 s2, v141
	v_add_u32_e32 v141, 0x2000, v140
	global_load_lds_dwordx4 v[138:139], off
	v_lshl_add_u64 v[138:139], v[136:137], 0, s[58:59]
	s_mov_b32 m0, s2
	v_readfirstlane_b32 s2, v141
	global_load_lds_dwordx4 v[138:139], off
	v_lshl_add_u64 v[138:139], v[136:137], 0, s[60:61]
	s_mov_b32 m0, s2
	v_lshl_add_u64 v[134:135], s[20:21], 0, v[134:135]
	global_load_lds_dwordx4 v[138:139], off
	v_add_u32_e32 v138, 0x3000, v140
	v_lshl_add_u64 v[134:135], v[134:135], 0, v[128:129]
	v_readfirstlane_b32 s2, v138
	v_add_u32_e32 v128, 0x4000, v140
	v_lshl_add_u64 v[136:137], v[136:137], 0, s[62:63]
	s_mov_b32 m0, s2
	v_readfirstlane_b32 s2, v128
	v_add_u32_e32 v128, 0x5000, v140
	global_load_lds_dwordx4 v[136:137], off
	v_lshl_add_u64 v[136:137], v[134:135], 0, 64
	s_mov_b32 m0, s2
	v_readfirstlane_b32 s2, v128
	global_load_lds_dwordx4 v[136:137], off
	v_lshl_add_u64 v[134:135], v[134:135], 0, s[58:59]
	s_mov_b32 m0, s2
	s_nop 0
	global_load_lds_dwordx4 v[134:135], off

; DEVI int opaque_tid() { int t = (int)threadIdx.x; asm volatile("" : "+v"(t)); return t; }
; DEVI void g2_issue(const G2Tile& t, int kt, int st, char* smem) {
;     const int tid = opaque_tid(), lane = tid & 63, w = tid >> 6;
;     const int rr = lane >> 2, sch = (lane & 3) ^ ((lane >> 5) << 1);
;     const bf16_t* ap = t.A + (size_t)kt * 32 + (size_t)(w * 16 + rr) * t.lda + sch * 8;
;     const bf16_t* bp = t.Bt + (size_t)kt * 32 + (size_t)(w * 16 + rr) * t.ldb + sch * 8;
;     char* sa = smem + st * 24576 + w * 1024 + lane * 16;
; #pragma unroll
;     for (int i = 0; i < 4; ++i) __builtin_amdgcn_global_load_lds((const unsigned*)(ap + (size_t)(64 * i) * t.lda), (unsigned*)(sa + i * 4096), 16, 0, 0);
; #pragma unroll
;     for (int i = 0; i < 2; ++i) __builtin_amdgcn_global_load_lds((const unsigned*)(bp + (size_t)(64 * i) * t.ldb), (unsigned*)(sa + 16384 + i * 4096), 16, 0, 0);
; template <bool TRANS, class Epi>
; DEVI int g2_body(const G2Tile& t, int st, char* smem, bool has_next, const G2Tile& nxt, const Epi& epi) {
;     ...
;     for (int kt = 0; kt < nk; ++kt) {
;         if (kt + 1 < nk) asm volatile("s_waitcnt vmcnt(6)" ::: "memory");
;         else asm volatile("s_waitcnt vmcnt(0)" ::: "memory");
;         __syncthreads();
;         if (kt + 2 < nk) g2_issue(t, kt + 2, st >= 1 ? st - 1 : 2, smem);
;         const char* sa = smem + st * 24576 + frag;
;         bf16x8 bfr[4];
; #pragma unroll
;         for (int n = 0; n < 4; ++n) bfr[n] = *(const bf16x8*)(sa + (16 + wc * 4 + n) * 1024);
; #pragma unroll
;         for (int mh = 0; mh < 2; ++mh) {
;             bf16x8 af[4];
; #pragma unroll
;             for (int m = 0; m < 4; ++m) af[m] = *(const bf16x8*)(sa + (wr * 8 + mh * 4 + m) * 1024);
;             __builtin_amdgcn_s_setprio(1);
; #pragma unroll
;             for (int m = 0; m < 4; ++m)
; #pragma unroll
;                 for (int n = 0; n < 4; ++n)
;                     acc[mh * 4 + m][n] = TRANS ? __builtin_amdgcn_mfma_f32_16x16x32_bf16(bfr[n], af[m], acc[mh * 4 + m][n], 0, 0, 0)
;                                                : __builtin_amdgcn_mfma_f32_16x16x32_bf16(af[m], bfr[n], acc[mh * 4 + m][n], 0, 0, 0);
;             __builtin_amdgcn_s_setprio(0);
;         }
;         st = st == 2 ? 0 : st + 1;
;     }
.LBB0_477:
	v_mov_b32_e32 v137, v172
	s_waitcnt vmcnt(6)
	s_waitcnt lgkmcnt(0)
	s_barrier
	s_mul_i32 s18, s60, 0x6000
	s_add_i32 s16, s18, 0xffffa000
	v_ashrrev_i32_e32 v145, 6, v137
	v_bfe_u32 v138, v137, 2, 4
	v_and_b32_e32 v144, 63, v137
	v_and_b32_e32 v139, 3, v137
	v_lshrrev_b32_e32 v137, 4, v137
	v_lshl_or_b32 v138, v145, 4, v138
	s_cmp_gt_i32 s60, 0
	v_bitop3_b32 v137, v137, v139, 2 bitop3:0x6c
	v_ashrrev_i32_e32 v139, 31, v138
	v_lshlrev_b64 v[138:139], 11, v[138:139]
	s_cselect_b32 s16, s16, 0xc000
	v_lshl_or_b32 v138, v137, 4, v138
	s_add_i32 s16, s16, 0
	v_lshlrev_b32_e32 v137, 10, v145
	v_lshlrev_b32_e32 v144, 4, v144
	v_lshl_add_u64 v[138:139], s[50:51], 0, v[138:139]
	v_add3_u32 v137, s16, v137, v144
	v_lshl_add_u64 v[140:141], s[34:35], 0, v[138:139]
	v_readfirstlane_b32 s16, v137
	v_add_u32_e32 v144, 0x1000, v137
	v_lshl_add_u64 v[142:143], v[140:141], 0, s[12:13]
	s_mov_b32 m0, s16
	v_readfirstlane_b32 s16, v144
	global_load_lds_dwordx4 v[142:143], off
	v_lshl_add_u64 v[142:143], v[140:141], 0, s[14:15]
	s_mov_b32 m0, s16
	s_mov_b64 s[16:17], 0x40080
	v_add_u32_e32 v144, 0x2000, v137
	global_load_lds_dwordx4 v[142:143], off
	v_lshl_add_u64 v[142:143], v[140:141], 0, s[16:17]
	v_readfirstlane_b32 s16, v144
	s_mov_b32 m0, s16
	s_mov_b64 s[16:17], 0x60080
	global_load_lds_dwordx4 v[142:143], off
	v_add_u32_e32 v142, 0x3000, v137
	v_lshl_add_u64 v[140:141], v[140:141], 0, s[16:17]
	v_readfirstlane_b32 s16, v142
	v_add_u32_e32 v142, 0x4000, v137
	s_mov_b32 m0, s16
	v_lshl_add_u64 v[138:139], s[36:37], 0, v[138:139]
	v_readfirstlane_b32 s16, v142
	v_add_u32_e32 v137, 0x5000, v137
	global_load_lds_dwordx4 v[140:141], off
	v_lshl_add_u64 v[140:141], v[138:139], 0, s[12:13]
	s_mov_b32 m0, s16
	v_readfirstlane_b32 s16, v137
	global_load_lds_dwordx4 v[140:141], off
	v_lshl_add_u64 v[138:139], v[138:139], 0, s[14:15]
	s_mov_b32 m0, s16
	v_add_u32_e32 v137, s18, v135
	global_load_lds_dwordx4 v[138:139], off
	v_add_u32_e32 v150, v137, v128
	v_add_u32_e32 v137, v137, v136
	ds_read_b128 v[138:141], v150 offset:16384
	ds_read_b128 v[142:145], v150 offset:17408
	ds_read_b128 v[146:149], v150 offset:18432
	ds_read_b128 v[150:153], v150 offset:19456
	ds_read_b128 v[154:157], v137
	ds_read_b128 v[158:161], v137 offset:1024
	ds_read_b128 v[162:165], v137 offset:2048
	ds_read_b128 v[166:169], v137 offset:3072
	s_setprio 1
	s_waitcnt lgkmcnt(0)
	v_mfma_f32_16x16x32_bf16 v[124:127], v[154:157], v[138:141], v[124:127]
	v_mfma_f32_16x16x32_bf16 v[120:123], v[154:157], v[142:145], v[120:123]
	v_mfma_f32_16x16x32_bf16 v[116:119], v[154:157], v[146:149], v[116:119]
	v_mfma_f32_16x16x32_bf16 v[112:115], v[154:157], v[150:153], v[112:115]
	v_mfma_f32_16x16x32_bf16 v[108:111], v[158:161], v[138:141], v[108:111]
	v_mfma_f32_16x16x32_bf16 v[96:99], v[158:161], v[142:145], v[96:99]
	v_mfma_f32_16x16x32_bf16 v[84:87], v[158:161], v[146:149], v[84:87]
	v_mfma_f32_16x16x32_bf16 v[80:83], v[158:161], v[150:153], v[80:83]
	v_mfma_f32_16x16x32_bf16 v[76:79], v[162:165], v[138:141], v[76:79]
	v_mfma_f32_16x16x32_bf16 v[72:75], v[162:165], v[142:145], v[72:75]
	v_mfma_f32_16x16x32_bf16 v[68:71], v[162:165], v[146:149], v[68:71]
	v_mfma_f32_16x16x32_bf16 v[64:67], v[162:165], v[150:153], v[64:67]
	v_mfma_f32_16x16x32_bf16 v[60:63], v[166:169], v[138:141], v[60:63]
	v_mfma_f32_16x16x32_bf16 v[56:59], v[166:169], v[142:145], v[56:59]
	v_mfma_f32_16x16x32_bf16 v[52:55], v[166:169], v[146:149], v[52:55]
	v_mfma_f32_16x16x32_bf16 v[48:51], v[166:169], v[150:153], v[48:51]
	s_setprio 0
	ds_read_b128 v[154:157], v137 offset:4096
	ds_read_b128 v[158:161], v137 offset:5120
	ds_read_b128 v[162:165], v137 offset:6144
	ds_read_b128 v[166:169], v137 offset:7168
	s_setprio 1
	s_waitcnt lgkmcnt(0)
	v_mfma_f32_16x16x32_bf16 v[44:47], v[154:157], v[138:141], v[44:47]
	v_mfma_f32_16x16x32_bf16 v[40:43], v[154:157], v[142:145], v[40:43]
	v_mfma_f32_16x16x32_bf16 v[36:39], v[154:157], v[146:149], v[36:39]
	v_mfma_f32_16x16x32_bf16 v[32:35], v[154:157], v[150:153], v[32:35]
	v_mfma_f32_16x16x32_bf16 v[28:31], v[158:161], v[138:141], v[28:31]
	v_mfma_f32_16x16x32_bf16 v[24:27], v[158:161], v[142:145], v[24:27]
	v_mfma_f32_16x16x32_bf16 v[20:23], v[158:161], v[146:149], v[20:23]
	v_mfma_f32_16x16x32_bf16 v[16:19], v[158:161], v[150:153], v[16:19]
	v_mfma_f32_16x16x32_bf16 v[12:15], v[162:165], v[138:141], v[12:15]
	v_mfma_f32_16x16x32_bf16 v[8:11], v[162:165], v[142:145], v[8:11]
	v_mfma_f32_16x16x32_bf16 v[4:7], v[162:165], v[146:149], v[4:7]
	v_mfma_f32_16x16x32_bf16 v[0:3], v[162:165], v[150:153], v[0:3]
	v_mfma_f32_16x16x32_bf16 v[88:91], v[166:169], v[138:141], v[88:91]
	v_mfma_f32_16x16x32_bf16 v[92:95], v[166:169], v[142:145], v[92:95]
	v_mfma_f32_16x16x32_bf16 v[100:103], v[166:169], v[146:149], v[100:103]
	v_mfma_f32_16x16x32_bf16 v[104:107], v[166:169], v[150:153], v[104:107]
	s_setprio 0
	s_add_i32 s16, s60, 1
	s_cmp_lg_u32 s60, 2
	s_cselect_b32 s60, s16, 0
	s_add_u32 s50, s50, 64
	s_addc_u32 s51, s51, 0
	s_cmpk_eq_i32 s50, 0x780
	s_cbranch_scc0 .LBB0_477
	s_mul_i32 s16, s60, 0x6000
	v_add_u32_e32 v137, s16, v135
	v_add_u32_e32 v150, v137, v128
	v_add_u32_e32 v137, v137, v136
	s_waitcnt vmcnt(6)
	s_barrier
; template <bool TRANS, class Epi>
; DEVI int g2_body(const G2Tile& t, int st, char* smem, bool has_next, const G2Tile& nxt, const Epi& epi) {
;     ...
;     for (int kt = 0; kt < nk; ++kt) {
;         if (kt + 1 < nk) asm volatile("s_waitcnt vmcnt(6)" ::: "memory");
;         else asm volatile("s_waitcnt vmcnt(0)" ::: "memory");
;         __syncthreads();
;         if (kt + 2 < nk) g2_issue(t, kt + 2, st >= 1 ? st - 1 : 2, smem);
;         const char* sa = smem + st * 24576 + frag;
;         bf16x8 bfr[4];
; #pragma unroll
;         for (int n = 0; n < 4; ++n) bfr[n] = *(const bf16x8*)(sa + (16 + wc * 4 + n) * 1024);
; #pragma unroll
;         for (int mh = 0; mh < 2; ++mh) {
;             bf16x8 af[4];
; #pragma unroll
;             for (int m = 0; m < 4; ++m) af[m] = *(const bf16x8*)(sa + (wr * 8 + mh * 4 + m) * 1024);
;             __builtin_amdgcn_s_setprio(1);
; #pragma unroll
;             for (int m = 0; m < 4; ++m)
; #pragma unroll
;                 for (int n = 0; n < 4; ++n)
;                     acc[mh * 4 + m][n] = TRANS ? __builtin_amdgcn_mfma_f32_16x16x32_bf16(bfr[n], af[m], acc[mh * 4 + m][n], 0, 0, 0)
;                                                : __builtin_amdgcn_mfma_f32_16x16x32_bf16(af[m], bfr[n], acc[mh * 4 + m][n], 0, 0, 0);
;             __builtin_amdgcn_s_setprio(0);
;         }
;         st = st == 2 ? 0 : st + 1;
	ds_read_b128 v[138:141], v150 offset:16384
	ds_read_b128 v[142:145], v150 offset:17408
	ds_read_b128 v[146:149], v150 offset:18432
	ds_read_b128 v[150:153], v150 offset:19456
	ds_read_b128 v[154:157], v137
	ds_read_b128 v[158:161], v137 offset:1024
	ds_read_b128 v[162:165], v137 offset:2048
	ds_read_b128 v[166:169], v137 offset:3072
	s_setprio 1
	s_waitcnt lgkmcnt(3)
	v_mfma_f32_16x16x32_bf16 v[124:127], v[154:157], v[138:141], v[124:127]
	v_mfma_f32_16x16x32_bf16 v[120:123], v[154:157], v[142:145], v[120:123]
	v_mfma_f32_16x16x32_bf16 v[116:119], v[154:157], v[146:149], v[116:119]
	v_mfma_f32_16x16x32_bf16 v[112:115], v[154:157], v[150:153], v[112:115]
	s_waitcnt lgkmcnt(2)
	v_mfma_f32_16x16x32_bf16 v[108:111], v[158:161], v[138:141], v[108:111]
	v_mfma_f32_16x16x32_bf16 v[96:99], v[158:161], v[142:145], v[96:99]
	v_mfma_f32_16x16x32_bf16 v[84:87], v[158:161], v[146:149], v[84:87]
	v_mfma_f32_16x16x32_bf16 v[80:83], v[158:161], v[150:153], v[80:83]
	s_waitcnt lgkmcnt(1)
	v_mfma_f32_16x16x32_bf16 v[76:79], v[162:165], v[138:141], v[76:79]
	v_mfma_f32_16x16x32_bf16 v[72:75], v[162:165], v[142:145], v[72:75]
	v_mfma_f32_16x16x32_bf16 v[68:71], v[162:165], v[146:149], v[68:71]
	v_mfma_f32_16x16x32_bf16 v[64:67], v[162:165], v[150:153], v[64:67]
	s_waitcnt lgkmcnt(0)
	v_mfma_f32_16x16x32_bf16 v[60:63], v[166:169], v[138:141], v[60:63]
	v_mfma_f32_16x16x32_bf16 v[56:59], v[166:169], v[142:145], v[56:59]
	v_mfma_f32_16x16x32_bf16 v[52:55], v[166:169], v[146:149], v[52:55]
	v_mfma_f32_16x16x32_bf16 v[48:51], v[166:169], v[150:153], v[48:51]
	s_setprio 0
	ds_read_b128 v[154:157], v137 offset:4096
	ds_read_b128 v[158:161], v137 offset:5120
	ds_read_b128 v[162:165], v137 offset:6144
	ds_read_b128 v[166:169], v137 offset:7168
	s_setprio 1
	s_waitcnt lgkmcnt(3)
	v_mfma_f32_16x16x32_bf16 v[44:47], v[154:157], v[138:141], v[44:47]
	v_mfma_f32_16x16x32_bf16 v[40:43], v[154:157], v[142:145], v[40:43]
	v_mfma_f32_16x16x32_bf16 v[36:39], v[154:157], v[146:149], v[36:39]
	v_mfma_f32_16x16x32_bf16 v[32:35], v[154:157], v[150:153], v[32:35]
	s_waitcnt lgkmcnt(2)
	v_mfma_f32_16x16x32_bf16 v[28:31], v[158:161], v[138:141], v[28:31]
	v_mfma_f32_16x16x32_bf16 v[24:27], v[158:161], v[142:145], v[24:27]
	v_mfma_f32_16x16x32_bf16 v[20:23], v[158:161], v[146:149], v[20:23]
	v_mfma_f32_16x16x32_bf16 v[16:19], v[158:161], v[150:153], v[16:19]
	s_waitcnt lgkmcnt(1)
	v_mfma_f32_16x16x32_bf16 v[12:15], v[162:165], v[138:141], v[12:15]
	v_mfma_f32_16x16x32_bf16 v[8:11], v[162:165], v[142:145], v[8:11]
	v_mfma_f32_16x16x32_bf16 v[4:7], v[162:165], v[146:149], v[4:7]
	v_mfma_f32_16x16x32_bf16 v[0:3], v[162:165], v[150:153], v[0:3]
	s_waitcnt lgkmcnt(0)
	v_mfma_f32_16x16x32_bf16 v[138:141], v[166:169], v[138:141], v[88:91]
	v_mfma_f32_16x16x32_bf16 v[142:145], v[166:169], v[142:145], v[92:95]
	v_mfma_f32_16x16x32_bf16 v[146:149], v[166:169], v[146:149], v[100:103]
	v_mfma_f32_16x16x32_bf16 v[150:153], v[166:169], v[150:153], v[104:107]
	s_setprio 0
	s_add_i32 s16, s60, 1
	s_cmp_lg_u32 s60, 2
	s_cselect_b32 s16, s16, 0
	s_mul_i32 s17, s16, 0x6000
	v_add_u32_e32 v100, s17, v135
	v_add_u32_e32 v135, v100, v136
	v_add_u32_e32 v100, v100, v128
	s_waitcnt vmcnt(0)
	s_barrier
	ds_read_b128 v[154:157], v135 offset:3072
	ds_read_b128 v[158:161], v135 offset:2048
	ds_read_b128 v[88:91], v135 offset:1024
	ds_read_b128 v[92:95], v135
	ds_read_b128 v[162:165], v100 offset:19456
	ds_read_b128 v[166:169], v100 offset:18432
	ds_read_b128 v[184:187], v100 offset:17408
	ds_read_b128 v[188:191], v100 offset:16384
	s_setprio 1
	s_waitcnt lgkmcnt(0)
	v_mfma_f32_16x16x32_bf16 v[124:127], v[92:95], v[188:191], v[124:127]
	v_mfma_f32_16x16x32_bf16 v[120:123], v[92:95], v[184:187], v[120:123]
	v_mfma_f32_16x16x32_bf16 v[116:119], v[92:95], v[166:169], v[116:119]
	v_mfma_f32_16x16x32_bf16 v[112:115], v[92:95], v[162:165], v[112:115]
	v_mfma_f32_16x16x32_bf16 v[108:111], v[88:91], v[188:191], v[108:111]
	v_mfma_f32_16x16x32_bf16 v[104:107], v[88:91], v[184:187], v[96:99]
	v_mfma_f32_16x16x32_bf16 v[100:103], v[88:91], v[166:169], v[84:87]
	v_mfma_f32_16x16x32_bf16 v[96:99], v[88:91], v[162:165], v[80:83]
	v_mfma_f32_16x16x32_bf16 v[92:95], v[158:161], v[188:191], v[76:79]
	v_mfma_f32_16x16x32_bf16 v[88:91], v[158:161], v[184:187], v[72:75]
	v_mfma_f32_16x16x32_bf16 v[84:87], v[158:161], v[166:169], v[68:71]
	v_mfma_f32_16x16x32_bf16 v[80:83], v[158:161], v[162:165], v[64:67]
	v_mfma_f32_16x16x32_bf16 v[76:79], v[154:157], v[188:191], v[60:63]
	v_mfma_f32_16x16x32_bf16 v[72:75], v[154:157], v[184:187], v[56:59]
	v_mfma_f32_16x16x32_bf16 v[68:71], v[154:157], v[166:169], v[52:55]
	v_mfma_f32_16x16x32_bf16 v[64:67], v[154:157], v[162:165], v[48:51]
	s_setprio 0
	s_nop 1
	ds_read_b128 v[48:51], v135 offset:4096
	ds_read_b128 v[154:157], v135 offset:5120
	ds_read_b128 v[158:161], v135 offset:6144
	ds_read_b128 v[192:195], v135 offset:7168
	s_setprio 1
	s_waitcnt lgkmcnt(3)
	v_mfma_f32_16x16x32_bf16 v[60:63], v[48:51], v[188:191], v[44:47]
	v_mfma_f32_16x16x32_bf16 v[56:59], v[48:51], v[184:187], v[40:43]
	v_mfma_f32_16x16x32_bf16 v[52:55], v[48:51], v[166:169], v[36:39]
	v_mfma_f32_16x16x32_bf16 v[48:51], v[48:51], v[162:165], v[32:35]
	s_waitcnt lgkmcnt(2)
	v_mfma_f32_16x16x32_bf16 v[44:47], v[154:157], v[188:191], v[28:31]
	v_mfma_f32_16x16x32_bf16 v[40:43], v[154:157], v[184:187], v[24:27]
	v_mfma_f32_16x16x32_bf16 v[36:39], v[154:157], v[166:169], v[20:23]
	v_mfma_f32_16x16x32_bf16 v[32:35], v[154:157], v[162:165], v[16:19]
	s_waitcnt lgkmcnt(1)
	v_mfma_f32_16x16x32_bf16 v[28:31], v[158:161], v[188:191], v[12:15]
	v_mfma_f32_16x16x32_bf16 v[24:27], v[158:161], v[184:187], v[8:11]
	v_mfma_f32_16x16x32_bf16 v[20:23], v[158:161], v[166:169], v[4:7]
	v_mfma_f32_16x16x32_bf16 v[16:19], v[158:161], v[162:165], v[0:3]
	s_waitcnt lgkmcnt(0)
	v_mfma_f32_16x16x32_bf16 v[12:15], v[192:195], v[188:191], v[138:141]
	v_mfma_f32_16x16x32_bf16 v[8:11], v[192:195], v[184:187], v[142:145]
	v_mfma_f32_16x16x32_bf16 v[4:7], v[192:195], v[166:169], v[146:149]
	v_mfma_f32_16x16x32_bf16 v[0:3], v[192:195], v[162:165], v[150:153]
	s_setprio 0
	s_add_i32 s17, s16, 1
	s_cmp_lg_u32 s16, 2
	s_cselect_b32 s60, s17, 0
	s_and_b64 vcc, exec, s[42:43]
	s_cbranch_vccz .LBB0_473
; DEVI int opaque_tid() { int t = (int)threadIdx.x; asm volatile("" : "+v"(t)); return t; }
; DEVI void g2_issue(const G2Tile& t, int kt, int st, char* smem) {
;     const int tid = opaque_tid(), lane = tid & 63, w = tid >> 6;
;     const int rr = lane >> 2, sch = (lane & 3) ^ ((lane >> 5) << 1);
;     const bf16_t* ap = t.A + (size_t)kt * 32 + (size_t)(w * 16 + rr) * t.lda + sch * 8;
;     const bf16_t* bp = t.Bt + (size_t)kt * 32 + (size_t)(w * 16 + rr) * t.ldb + sch * 8;
;     char* sa = smem + st * 24576 + w * 1024 + lane * 16;
; #pragma unroll
;     for (int i = 0; i < 4; ++i) __builtin_amdgcn_global_load_lds((const unsigned*)(ap + (size_t)(64 * i) * t.lda), (unsigned*)(sa + i * 4096), 16, 0, 0);
; #pragma unroll
;     for (int i = 0; i < 2; ++i) __builtin_amdgcn_global_load_lds((const unsigned*)(bp + (size_t)(64 * i) * t.ldb), (unsigned*)(sa + 16384 + i * 4096), 16, 0, 0);
; }
; DEVI void g2_prologue(const G2Tile& t, int st, char* smem) {
;     g2_issue(t, 0, st, smem);
;     g2_issue(t, 1, st == 2 ? 0 : st + 1, smem);
	v_mov_b32_e32 v128, v172
	s_mul_i32 s16, s60, 0x6000
	v_ashrrev_i32_e32 v140, 6, v128
	v_bfe_u32 v136, v128, 2, 4
	v_and_b32_e32 v135, 63, v128
	v_and_b32_e32 v137, 3, v128
	v_lshrrev_b32_e32 v128, 4, v128
	v_lshl_or_b32 v136, v140, 4, v136
	v_bitop3_b32 v128, v128, v137, 2 bitop3:0x6c
	v_ashrrev_i32_e32 v137, 31, v136
	s_add_i32 s17, s16, 0
	v_lshlrev_b32_e32 v140, 10, v140
	v_lshlrev_b32_e32 v135, 4, v135
	v_lshlrev_b64 v[136:137], 11, v[136:137]
	v_add3_u32 v135, s17, v140, v135
	v_lshl_add_u64 v[138:139], s[22:23], 0, v[136:137]
	v_lshlrev_b32_e32 v128, 4, v128
	v_readfirstlane_b32 s17, v135
	v_add_u32_e32 v142, 0x1000, v135
	v_lshl_add_u64 v[138:139], v[138:139], 0, v[128:129]
	s_mov_b32 m0, s17
	v_readfirstlane_b32 s17, v142
	v_add_u32_e32 v142, 0x2000, v135
	global_load_lds_dwordx4 v[138:139], off
	v_lshl_add_u64 v[140:141], v[138:139], 0, s[0:1]
	s_mov_b32 m0, s17
	v_readfirstlane_b32 s17, v142
	global_load_lds_dwordx4 v[140:141], off
	v_lshl_add_u64 v[140:141], v[138:139], 0, s[2:3]
	s_mov_b32 m0, s17
	v_lshl_add_u64 v[136:137], s[24:25], 0, v[136:137]
	global_load_lds_dwordx4 v[140:141], off
	v_add_u32_e32 v140, 0x3000, v135
	v_lshl_add_u64 v[136:137], v[136:137], 0, v[128:129]
	v_readfirstlane_b32 s17, v140
	v_add_u32_e32 v128, 0x4000, v135
	v_lshl_add_u64 v[138:139], v[138:139], 0, s[4:5]
	s_mov_b32 m0, s17
	v_readfirstlane_b32 s17, v128
	v_add_u32_e32 v128, 0x5000, v135
	global_load_lds_dwordx4 v[138:139], off
	s_mov_b32 m0, s17
	v_readfirstlane_b32 s17, v128
	global_load_lds_dwordx4 v[136:137], off
	v_lshl_add_u64 v[136:137], v[136:137], 0, s[0:1]
	s_mov_b32 m0, s17
	v_mov_b32_e32 v128, v172
	global_load_lds_dwordx4 v[136:137], off
	s_addk_i32 s16, 0x6000
	v_ashrrev_i32_e32 v142, 6, v128
	v_bfe_u32 v136, v128, 2, 4
	v_and_b32_e32 v135, 63, v128
	v_and_b32_e32 v137, 3, v128
	v_lshrrev_b32_e32 v128, 4, v128
	v_lshl_or_b32 v136, v142, 4, v136
	s_cmp_lg_u32 s60, 2
	v_bitop3_b32 v128, v128, v137, 2 bitop3:0x6c
	v_ashrrev_i32_e32 v137, 31, v136
	s_cselect_b32 s16, s16, 0
	v_lshlrev_b64 v[136:137], 11, v[136:137]
	s_add_i32 s16, s16, 0
	v_lshlrev_b32_e32 v142, 10, v142
	v_lshlrev_b32_e32 v135, 4, v135
	v_lshl_add_u64 v[138:139], s[22:23], 0, v[136:137]
	v_lshlrev_b32_e32 v128, 4, v128
	v_add3_u32 v135, s16, v142, v135
	v_lshl_add_u64 v[138:139], v[138:139], 0, v[128:129]
	v_readfirstlane_b32 s16, v135
	v_add_u32_e32 v142, 0x1000, v135
	v_lshl_add_u64 v[140:141], v[138:139], 0, 64
	s_mov_b32 m0, s16
	v_readfirstlane_b32 s16, v142
	v_add_u32_e32 v142, 0x2000, v135
	global_load_lds_dwordx4 v[140:141], off
	v_lshl_add_u64 v[140:141], v[138:139], 0, s[6:7]
	s_mov_b32 m0, s16
	v_readfirstlane_b32 s16, v142
	global_load_lds_dwordx4 v[140:141], off
	v_lshl_add_u64 v[140:141], v[138:139], 0, s[8:9]
	s_mov_b32 m0, s16
	v_lshl_add_u64 v[136:137], s[24:25], 0, v[136:137]
	global_load_lds_dwordx4 v[140:141], off
	v_add_u32_e32 v140, 0x3000, v135
	v_lshl_add_u64 v[136:137], v[136:137], 0, v[128:129]
	v_readfirstlane_b32 s16, v140
	v_add_u32_e32 v128, 0x4000, v135
	v_lshl_add_u64 v[138:139], v[138:139], 0, s[10:11]
	s_mov_b32 m0, s16
	v_readfirstlane_b32 s16, v128
	v_add_u32_e32 v128, 0x5000, v135
	global_load_lds_dwordx4 v[138:139], off
	v_lshl_add_u64 v[138:139], v[136:137], 0, 64
	s_mov_b32 m0, s16
	v_readfirstlane_b32 s16, v128
	global_load_lds_dwordx4 v[138:139], off
	v_lshl_add_u64 v[136:137], v[136:137], 0, s[6:7]
	s_mov_b32 m0, s16
	s_nop 0
	global_load_lds_dwordx4 v[136:137], off
	s_branch .LBB0_473

; template <bool TRANS, class Epi>
; DEVI int g2_body(const G2Tile& t, int st, char* smem, bool has_next, const G2Tile& nxt, const Epi& epi) {
;     ...
;     for (int kt = 0; kt < nk; ++kt) {
;         if (kt + 1 < nk) asm volatile("s_waitcnt vmcnt(6)" ::: "memory");
;         else asm volatile("s_waitcnt vmcnt(0)" ::: "memory");
;         __syncthreads();
;         if (kt + 2 < nk) g2_issue(t, kt + 2, st >= 1 ? st - 1 : 2, smem);
;         const char* sa = smem + st * 24576 + frag;
;         bf16x8 bfr[4];
; #pragma unroll
;         for (int n = 0; n < 4; ++n) bfr[n] = *(const bf16x8*)(sa + (16 + wc * 4 + n) * 1024);
; #pragma unroll
;         for (int mh = 0; mh < 2; ++mh) {
;             bf16x8 af[4];
; #pragma unroll
;             for (int m = 0; m < 4; ++m) af[m] = *(const bf16x8*)(sa + (wr * 8 + mh * 4 + m) * 1024);
;             __builtin_amdgcn_s_setprio(1);
; #pragma unroll
;             for (int m = 0; m < 4; ++m)
; #pragma unroll
;                 for (int n = 0; n < 4; ++n)
;                     acc[mh * 4 + m][n] = TRANS ? __builtin_amdgcn_mfma_f32_16x16x32_bf16(bfr[n], af[m], acc[mh * 4 + m][n], 0, 0, 0)
;                                                : __builtin_amdgcn_mfma_f32_16x16x32_bf16(af[m], bfr[n], acc[mh * 4 + m][n], 0, 0, 0);
;             __builtin_amdgcn_s_setprio(0);
;         }
;         st = st == 2 ? 0 : st + 1;
;     }
; __global__ void __launch_bounds__(256, 2) fwd_megakernel(P p) {
;     ...
;         auto desc = [&](int L, int sn, G2Tile& q) { const int b = L >> 6, par = (L >> 5) & 1; int pm, pn; tile_map(L & 31, 4, 8, pm, pn);
;             q.A = (const bf16_t*)(ws + OFF_DL + (size_t)(2 * sn + par) * 2 * MiB) + (size_t)pm * 256 * 1024;
;             q.Bt = (const bf16_t*)(ws + (sn ? OFF_QF : OFF_PE) + (size_t)par * 16 * MiB) + (size_t)(b * 1024 + pn * 128) * 1024;
;             q.lda = 1024; q.ldb = 1024; q.nk = 32; q.row0 = pm * 256; q.col0 = pn * 128; q.aux = b * 2 + par; };
;         if (bid < 512) { desc(bid, 0, tc); __syncthreads(); g2_prologue(tc, 0, smem); }
;         for (int L = bid; L < 512; L += G) {
;             desc(L, 1, ts);
.LBB0_819:
	v_mov_b32_e32 v134, v172
	s_waitcnt vmcnt(6)
	s_waitcnt lgkmcnt(0)
	s_barrier
	s_mul_i32 s26, s72, 0x6000
	v_and_b32_e32 v140, 63, v134
	v_ashrrev_i32_e32 v141, 6, v134
	v_bfe_u32 v135, v134, 2, 4
	v_and_b32_e32 v136, 3, v134
	v_lshrrev_b32_e32 v134, 4, v134
	s_add_i32 s33, s26, 0xffffa000
	v_bitop3_b32 v136, v134, v136, 2 bitop3:0x6c
	v_lshl_or_b32 v134, v141, 4, v135
	s_cmp_gt_i32 s72, 0
	v_ashrrev_i32_e32 v135, 31, v134
	v_lshlrev_b64 v[134:135], 11, v[134:135]
	s_cselect_b32 s33, s33, 0xc000
	v_lshl_or_b32 v134, v136, 4, v134
	s_add_i32 s33, s33, 0
	v_lshlrev_b32_e32 v141, 10, v141
	v_lshlrev_b32_e32 v140, 4, v140
	v_lshl_add_u64 v[134:135], s[34:35], 0, v[134:135]
	v_add3_u32 v140, s33, v141, v140
	v_lshl_add_u64 v[136:137], s[28:29], 0, v[134:135]
	v_readfirstlane_b32 s33, v140
	v_add_u32_e32 v141, 0x1000, v140
	v_lshl_add_u64 v[138:139], v[136:137], 0, s[2:3]
	s_mov_b32 m0, s33
	v_readfirstlane_b32 s33, v141
	v_add_u32_e32 v141, 0x2000, v140
	global_load_lds_dwordx4 v[138:139], off
	v_lshl_add_u64 v[138:139], v[136:137], 0, s[4:5]
	s_mov_b32 m0, s33
	s_mov_b64 s[44:45], 0x40080
	v_readfirstlane_b32 s33, v141
	global_load_lds_dwordx4 v[138:139], off
	v_lshl_add_u64 v[138:139], v[136:137], 0, s[44:45]
	s_mov_b32 m0, s33
	s_mov_b64 s[44:45], 0x60080
	global_load_lds_dwordx4 v[138:139], off
	v_add_u32_e32 v138, 0x3000, v140
	v_lshl_add_u64 v[136:137], v[136:137], 0, s[44:45]
	v_readfirstlane_b32 s33, v138
	v_add_u32_e32 v138, 0x4000, v140
	s_mov_b32 m0, s33
	v_lshl_add_u64 v[134:135], s[30:31], 0, v[134:135]
	v_readfirstlane_b32 s33, v138
	global_load_lds_dwordx4 v[136:137], off
	v_lshl_add_u64 v[136:137], v[134:135], 0, s[2:3]
	s_mov_b32 m0, s33
	v_lshl_add_u64 v[134:135], v[134:135], 0, s[4:5]
	global_load_lds_dwordx4 v[136:137], off
	v_add_u32_e32 v136, 0x5000, v140
	v_add_u32_e32 v150, s26, v132
	v_readfirstlane_b32 s33, v136
	s_mov_b32 m0, s33
	v_add_u32_e32 v146, v150, v131
	global_load_lds_dwordx4 v[134:135], off
	v_add_u32_e32 v166, v150, v133
	ds_read_b128 v[134:137], v146 offset:16384
	ds_read_b128 v[138:141], v146 offset:17408
	ds_read_b128 v[142:145], v146 offset:18432
	ds_read_b128 v[146:149], v146 offset:19456
	ds_read_b128 v[150:153], v166
	ds_read_b128 v[154:157], v166 offset:1024
	ds_read_b128 v[158:161], v166 offset:2048
	ds_read_b128 v[162:165], v166 offset:3072
	s_setprio 1
	s_waitcnt lgkmcnt(0)
	v_mfma_f32_16x16x32_bf16 v[124:127], v[134:137], v[150:153], v[124:127]
	v_mfma_f32_16x16x32_bf16 v[120:123], v[138:141], v[150:153], v[120:123]
	v_mfma_f32_16x16x32_bf16 v[116:119], v[142:145], v[150:153], v[116:119]
	v_mfma_f32_16x16x32_bf16 v[112:115], v[146:149], v[150:153], v[112:115]
	v_mfma_f32_16x16x32_bf16 v[108:111], v[134:137], v[154:157], v[108:111]
	v_mfma_f32_16x16x32_bf16 v[96:99], v[138:141], v[154:157], v[96:99]
	v_mfma_f32_16x16x32_bf16 v[84:87], v[142:145], v[154:157], v[84:87]
	v_mfma_f32_16x16x32_bf16 v[80:83], v[146:149], v[154:157], v[80:83]
	v_mfma_f32_16x16x32_bf16 v[76:79], v[134:137], v[158:161], v[76:79]
	v_mfma_f32_16x16x32_bf16 v[72:75], v[138:141], v[158:161], v[72:75]
	v_mfma_f32_16x16x32_bf16 v[68:71], v[142:145], v[158:161], v[68:71]
	v_mfma_f32_16x16x32_bf16 v[64:67], v[146:149], v[158:161], v[64:67]
	v_mfma_f32_16x16x32_bf16 v[60:63], v[134:137], v[162:165], v[60:63]
	v_mfma_f32_16x16x32_bf16 v[56:59], v[138:141], v[162:165], v[56:59]
	v_mfma_f32_16x16x32_bf16 v[52:55], v[142:145], v[162:165], v[52:55]
	v_mfma_f32_16x16x32_bf16 v[48:51], v[146:149], v[162:165], v[48:51]
	s_setprio 0
	ds_read_b128 v[150:153], v166 offset:4096
	ds_read_b128 v[154:157], v166 offset:5120
	ds_read_b128 v[158:161], v166 offset:6144
	ds_read_b128 v[162:165], v166 offset:7168
	s_setprio 1
	s_waitcnt lgkmcnt(0)
	v_mfma_f32_16x16x32_bf16 v[44:47], v[134:137], v[150:153], v[44:47]
	v_mfma_f32_16x16x32_bf16 v[40:43], v[138:141], v[150:153], v[40:43]
	v_mfma_f32_16x16x32_bf16 v[36:39], v[142:145], v[150:153], v[36:39]
	v_mfma_f32_16x16x32_bf16 v[32:35], v[146:149], v[150:153], v[32:35]
	v_mfma_f32_16x16x32_bf16 v[28:31], v[134:137], v[154:157], v[28:31]
	v_mfma_f32_16x16x32_bf16 v[24:27], v[138:141], v[154:157], v[24:27]
	v_mfma_f32_16x16x32_bf16 v[20:23], v[142:145], v[154:157], v[20:23]
	v_mfma_f32_16x16x32_bf16 v[16:19], v[146:149], v[154:157], v[16:19]
	v_mfma_f32_16x16x32_bf16 v[12:15], v[134:137], v[158:161], v[12:15]
	v_mfma_f32_16x16x32_bf16 v[8:11], v[138:141], v[158:161], v[8:11]
	v_mfma_f32_16x16x32_bf16 v[4:7], v[142:145], v[158:161], v[4:7]
	v_mfma_f32_16x16x32_bf16 v[0:3], v[146:149], v[158:161], v[0:3]
	v_mfma_f32_16x16x32_bf16 v[88:91], v[134:137], v[162:165], v[88:91]
	v_mfma_f32_16x16x32_bf16 v[92:95], v[138:141], v[162:165], v[92:95]
	v_mfma_f32_16x16x32_bf16 v[100:103], v[142:145], v[162:165], v[100:103]
	v_mfma_f32_16x16x32_bf16 v[104:107], v[146:149], v[162:165], v[104:107]
	s_setprio 0
	s_add_i32 s26, s72, 1
	s_cmp_lg_u32 s72, 2
	s_cselect_b32 s72, s26, 0
	s_add_u32 s34, s34, 64
	s_addc_u32 s35, s35, 0
	s_cmpk_lg_i32 s34, 0x780
	s_cbranch_scc1 .LBB0_819
	s_bfe_u32 s71, s36, 0x10005
	s_bfe_u32 s74, s36, 0x20003
	s_lshl_b32 s26, s71, 21
	s_lshl_b32 s28, s74, 19
	s_ashr_i32 s33, s79, 1
	s_and_b32 s75, s63, 0x380
	s_or_b32 s29, s26, s28
	s_add_u32 s30, s90, s29
	s_addc_u32 s31, s91, 0
	s_ashr_i32 s73, s36, 6
	s_add_u32 s26, s19, s26
	s_addc_u32 s29, s42, 0
	s_add_u32 s26, s26, s28
	s_addc_u32 s28, s29, 0
	s_add_u32 s34, s26, 0x400000
	s_mul_i32 s37, s72, 0x6000
	s_addc_u32 s35, s28, 0
	s_lshl_b32 s76, s71, 24
	v_add_u32_e32 v150, s37, v132
	s_add_u32 s26, s43, s76
	v_add_u32_e32 v146, v150, v131
	v_add_u32_e32 v166, v150, v133
	s_addc_u32 s44, s50, 0
	s_lshl_b32 s29, s36, 7
	s_waitcnt vmcnt(6)
	s_barrier
; template <bool TRANS, class Epi>
; DEVI int g2_body(const G2Tile& t, int st, char* smem, bool has_next, const G2Tile& nxt, const Epi& epi) {
;     ...
;     for (int kt = 0; kt < nk; ++kt) {
;         if (kt + 1 < nk) asm volatile("s_waitcnt vmcnt(6)" ::: "memory");
;         else asm volatile("s_waitcnt vmcnt(0)" ::: "memory");
;         __syncthreads();
;         if (kt + 2 < nk) g2_issue(t, kt + 2, st >= 1 ? st - 1 : 2, smem);
;         const char* sa = smem + st * 24576 + frag;
;         bf16x8 bfr[4];
; #pragma unroll
;         for (int n = 0; n < 4; ++n) bfr[n] = *(const bf16x8*)(sa + (16 + wc * 4 + n) * 1024);
; #pragma unroll
;         for (int mh = 0; mh < 2; ++mh) {
;             bf16x8 af[4];
; #pragma unroll
;             for (int m = 0; m < 4; ++m) af[m] = *(const bf16x8*)(sa + (wr * 8 + mh * 4 + m) * 1024);
;             __builtin_amdgcn_s_setprio(1);
; #pragma unroll
;             for (int m = 0; m < 4; ++m)
; #pragma unroll
;                 for (int n = 0; n < 4; ++n)
;                     acc[mh * 4 + m][n] = TRANS ? __builtin_amdgcn_mfma_f32_16x16x32_bf16(bfr[n], af[m], acc[mh * 4 + m][n], 0, 0, 0)
;                                                : __builtin_amdgcn_mfma_f32_16x16x32_bf16(af[m], bfr[n], acc[mh * 4 + m][n], 0, 0, 0);
;             __builtin_amdgcn_s_setprio(0);
;         }
;         st = st == 2 ? 0 : st + 1;
	ds_read_b128 v[134:137], v146 offset:16384
	ds_read_b128 v[138:141], v146 offset:17408
	ds_read_b128 v[142:145], v146 offset:18432
	ds_read_b128 v[146:149], v146 offset:19456
	ds_read_b128 v[150:153], v166
	ds_read_b128 v[154:157], v166 offset:1024
	ds_read_b128 v[158:161], v166 offset:2048
	ds_read_b128 v[162:165], v166 offset:3072
	s_lshl_b32 s28, s73, 10
	s_and_b32 s29, s29, 0x380
	s_or_b32 s36, s28, s29
	s_ashr_i32 s37, s36, 31
	s_lshl_b64 s[36:37], s[36:37], 11
	s_add_u32 s36, s26, s36
	s_addc_u32 s37, s44, s37
	s_setprio 1
	s_waitcnt lgkmcnt(3)
	v_mfma_f32_16x16x32_bf16 v[124:127], v[134:137], v[150:153], v[124:127]
	v_mfma_f32_16x16x32_bf16 v[120:123], v[138:141], v[150:153], v[120:123]
	v_mfma_f32_16x16x32_bf16 v[116:119], v[142:145], v[150:153], v[116:119]
	v_mfma_f32_16x16x32_bf16 v[112:115], v[146:149], v[150:153], v[112:115]
	s_waitcnt lgkmcnt(2)
	v_mfma_f32_16x16x32_bf16 v[108:111], v[134:137], v[154:157], v[108:111]
	v_mfma_f32_16x16x32_bf16 v[96:99], v[138:141], v[154:157], v[96:99]
	v_mfma_f32_16x16x32_bf16 v[84:87], v[142:145], v[154:157], v[84:87]
	v_mfma_f32_16x16x32_bf16 v[80:83], v[146:149], v[154:157], v[80:83]
	s_waitcnt lgkmcnt(1)
	v_mfma_f32_16x16x32_bf16 v[76:79], v[134:137], v[158:161], v[76:79]
	v_mfma_f32_16x16x32_bf16 v[72:75], v[138:141], v[158:161], v[72:75]
	s_waitcnt lgkmcnt(0)
	v_mfma_f32_16x16x32_bf16 v[60:63], v[134:137], v[162:165], v[60:63]
	v_mfma_f32_16x16x32_bf16 v[56:59], v[138:141], v[162:165], v[56:59]
	v_mfma_f32_16x16x32_bf16 v[52:55], v[142:145], v[162:165], v[52:55]
	v_mfma_f32_16x16x32_bf16 v[48:51], v[146:149], v[162:165], v[48:51]
	v_mfma_f32_16x16x32_bf16 v[150:153], v[142:145], v[158:161], v[68:71]
	v_mfma_f32_16x16x32_bf16 v[154:157], v[146:149], v[158:161], v[64:67]
	s_setprio 0
	s_nop 1
	ds_read_b128 v[64:67], v166 offset:4096
	ds_read_b128 v[68:71], v166 offset:5120
	ds_read_b128 v[158:161], v166 offset:6144
	ds_read_b128 v[162:165], v166 offset:7168
	s_setprio 1
	s_waitcnt lgkmcnt(3)
	v_mfma_f32_16x16x32_bf16 v[166:169], v[134:137], v[64:67], v[44:47]
	v_mfma_f32_16x16x32_bf16 v[186:189], v[138:141], v[64:67], v[40:43]
	s_waitcnt lgkmcnt(2)
	v_mfma_f32_16x16x32_bf16 v[198:201], v[134:137], v[68:71], v[28:31]
	v_mfma_f32_16x16x32_bf16 v[202:205], v[138:141], v[68:71], v[24:27]
	s_waitcnt lgkmcnt(1)
	v_mfma_f32_16x16x32_bf16 v[218:221], v[134:137], v[158:161], v[12:15]
	v_mfma_f32_16x16x32_bf16 v[222:225], v[138:141], v[158:161], v[8:11]
	v_mfma_f32_16x16x32_bf16 v[4:7], v[142:145], v[158:161], v[4:7]
	v_mfma_f32_16x16x32_bf16 v[0:3], v[146:149], v[158:161], v[0:3]
	s_waitcnt lgkmcnt(0)
	v_mfma_f32_16x16x32_bf16 v[134:137], v[134:137], v[162:165], v[88:91]
	v_mfma_f32_16x16x32_bf16 v[92:95], v[138:141], v[162:165], v[92:95]
	v_mfma_f32_16x16x32_bf16 v[138:141], v[142:145], v[162:165], v[100:103]
	v_mfma_f32_16x16x32_bf16 v[190:193], v[142:145], v[64:67], v[36:39]
	v_mfma_f32_16x16x32_bf16 v[194:197], v[146:149], v[64:67], v[32:35]
	v_mfma_f32_16x16x32_bf16 v[206:209], v[142:145], v[68:71], v[20:23]
	v_mfma_f32_16x16x32_bf16 v[210:213], v[146:149], v[68:71], v[16:19]
	v_mfma_f32_16x16x32_bf16 v[142:145], v[146:149], v[162:165], v[104:107]
	s_setprio 0
	s_add_i32 s26, s72, 1
	s_cmp_lg_u32 s72, 2
	s_cselect_b32 s26, s26, 0
	s_mul_i32 s44, s26, 0x6000
	v_add_u32_e32 v24, s44, v132
	v_add_u32_e32 v88, v24, v133
	v_add_u32_e32 v24, v24, v131
	s_waitcnt vmcnt(0)
	s_barrier
	ds_read_b128 v[8:11], v88 offset:3072
	ds_read_b128 v[12:15], v88 offset:2048
	ds_read_b128 v[16:19], v88 offset:1024
	ds_read_b128 v[20:23], v88
	ds_read_b128 v[146:149], v24 offset:19456
	ds_read_b128 v[158:161], v24 offset:18432
	ds_read_b128 v[162:165], v24 offset:17408
	ds_read_b128 v[226:229], v24 offset:16384
	s_setprio 1
	s_waitcnt lgkmcnt(0)
	v_mfma_f32_16x16x32_bf16 v[124:127], v[226:229], v[20:23], v[124:127]
	v_mfma_f32_16x16x32_bf16 v[64:67], v[162:165], v[20:23], v[120:123]
	v_mfma_f32_16x16x32_bf16 v[32:35], v[158:161], v[20:23], v[116:119]
	v_mfma_f32_16x16x32_bf16 v[28:31], v[146:149], v[20:23], v[112:115]
	v_mfma_f32_16x16x32_bf16 v[120:123], v[226:229], v[16:19], v[108:111]
	v_mfma_f32_16x16x32_bf16 v[68:71], v[162:165], v[16:19], v[96:99]
	v_mfma_f32_16x16x32_bf16 v[36:39], v[158:161], v[16:19], v[84:87]
	v_mfma_f32_16x16x32_bf16 v[24:27], v[146:149], v[16:19], v[80:83]
	v_mfma_f32_16x16x32_bf16 v[116:119], v[226:229], v[12:15], v[76:79]
	v_mfma_f32_16x16x32_bf16 v[72:75], v[162:165], v[12:15], v[72:75]
	v_mfma_f32_16x16x32_bf16 v[40:43], v[158:161], v[12:15], v[150:153]
	v_mfma_f32_16x16x32_bf16 v[20:23], v[146:149], v[12:15], v[154:157]
	v_mfma_f32_16x16x32_bf16 v[108:111], v[226:229], v[8:11], v[60:63]
	v_mfma_f32_16x16x32_bf16 v[76:79], v[162:165], v[8:11], v[56:59]
	v_mfma_f32_16x16x32_bf16 v[44:47], v[158:161], v[8:11], v[52:55]
	v_mfma_f32_16x16x32_bf16 v[12:15], v[146:149], v[8:11], v[48:51]
	s_setprio 0
	ds_read_b128 v[8:11], v88 offset:4096
	ds_read_b128 v[56:59], v88 offset:5120
	ds_read_b128 v[60:63], v88 offset:6144
	ds_read_b128 v[150:153], v88 offset:7168
	s_setprio 1
	s_waitcnt lgkmcnt(3)
	v_mfma_f32_16x16x32_bf16 v[112:115], v[226:229], v[8:11], v[166:169]
	v_mfma_f32_16x16x32_bf16 v[80:83], v[162:165], v[8:11], v[186:189]
	v_mfma_f32_16x16x32_bf16 v[48:51], v[158:161], v[8:11], v[190:193]
	v_mfma_f32_16x16x32_bf16 v[16:19], v[146:149], v[8:11], v[194:197]
	s_waitcnt lgkmcnt(2)
	v_mfma_f32_16x16x32_bf16 v[104:107], v[226:229], v[56:59], v[198:201]
	v_mfma_f32_16x16x32_bf16 v[84:87], v[162:165], v[56:59], v[202:205]
	v_mfma_f32_16x16x32_bf16 v[52:55], v[158:161], v[56:59], v[206:209]
	v_mfma_f32_16x16x32_bf16 v[8:11], v[146:149], v[56:59], v[210:213]
	s_waitcnt lgkmcnt(1)
; DEVI int opaque_tid() { int t = (int)threadIdx.x; asm volatile("" : "+v"(t)); return t; }
; DEVI void g2_issue(const G2Tile& t, int kt, int st, char* smem) {
;     const int tid = opaque_tid(), lane = tid & 63, w = tid >> 6;
;     const int rr = lane >> 2, sch = (lane & 3) ^ ((lane >> 5) << 1);
;     const bf16_t* ap = t.A + (size_t)kt * 32 + (size_t)(w * 16 + rr) * t.lda + sch * 8;
;     const bf16_t* bp = t.Bt + (size_t)kt * 32 + (size_t)(w * 16 + rr) * t.ldb + sch * 8;
;     char* sa = smem + st * 24576 + w * 1024 + lane * 16;
; #pragma unroll
;     for (int i = 0; i < 4; ++i) __builtin_amdgcn_global_load_lds((const unsigned*)(ap + (size_t)(64 * i) * t.lda), (unsigned*)(sa + i * 4096), 16, 0, 0);
; #pragma unroll
;     for (int i = 0; i < 2; ++i) __builtin_amdgcn_global_load_lds((const unsigned*)(bp + (size_t)(64 * i) * t.ldb), (unsigned*)(sa + 16384 + i * 4096), 16, 0, 0);
; }
; DEVI void g2_prologue(const G2Tile& t, int st, char* smem) {
;     g2_issue(t, 0, st, smem);
;     g2_issue(t, 1, st == 2 ? 0 : st + 1, smem);
;     template <int MT> DEVI void operator()(f32x4 (&acc)[MT][4], int row0, int col0, int fr, int fq) const {
; #pragma unroll
;         for (int n = 0; n < 4; ++n) {
;             const int e = col0 + 16 * n + 4 * fq;
;             f32x4 pv = *(const f32x4*)(ps1024 + b * 1024 + e);
;             if (par) pv = (f32x4){0.f, 0.f, 0.f, 0.f};
; #pragma unroll
;             for (int m = 0; m < MT; ++m) {
;                 const int k = row0 + 16 * m + fr;
;                 const float sg = (k & 1) ? -1.0f : 1.0f;
;                 *(f32x4*)(T + ((size_t)((b * 2 + par) * 1024 + k)) * 1024 + e) = acc[m][n] + pv * sg;
	v_mfma_f32_16x16x32_bf16 v[100:103], v[226:229], v[60:63], v[218:221]
	v_mfma_f32_16x16x32_bf16 v[88:91], v[162:165], v[60:63], v[222:225]
	v_mfma_f32_16x16x32_bf16 v[56:59], v[158:161], v[60:63], v[4:7]
	v_mfma_f32_16x16x32_bf16 v[4:7], v[146:149], v[60:63], v[0:3]
	s_waitcnt lgkmcnt(0)
	v_mfma_f32_16x16x32_bf16 v[96:99], v[226:229], v[150:153], v[134:137]
	v_mfma_f32_16x16x32_bf16 v[92:95], v[162:165], v[150:153], v[92:95]
	v_mfma_f32_16x16x32_bf16 v[60:63], v[158:161], v[150:153], v[138:141]
	v_mfma_f32_16x16x32_bf16 v[0:3], v[146:149], v[150:153], v[142:145]
	s_setprio 0
	s_add_i32 s44, s26, 1
	v_mov_b32_e32 v131, v172
	s_cmp_lg_u32 s26, 2
	s_cselect_b32 s72, s44, 0
	v_and_b32_e32 v136, 63, v131
	v_ashrrev_i32_e32 v137, 6, v131
	v_bfe_u32 v132, v131, 2, 4
	v_and_b32_e32 v133, 3, v131
	v_lshrrev_b32_e32 v131, 4, v131
	v_bitop3_b32 v131, v131, v133, 2 bitop3:0x6c
	v_lshl_or_b32 v132, v137, 4, v132
	s_mul_i32 s44, s72, 0x6000
	v_ashrrev_i32_e32 v133, 31, v132
	v_lshlrev_b32_e32 v184, 4, v131
	s_add_i32 s45, s44, 0
	v_lshlrev_b32_e32 v131, 10, v137
	v_lshlrev_b32_e32 v136, 4, v136
	v_lshlrev_b64 v[132:133], 11, v[132:133]
	v_add3_u32 v131, s45, v131, v136
	v_lshl_add_u64 v[134:135], s[34:35], 0, v[132:133]
	v_readfirstlane_b32 s45, v131
	v_add_u32_e32 v138, 0x1000, v131
	v_lshl_add_u64 v[134:135], v[134:135], 0, v[184:185]
	s_mov_b32 m0, s45
	v_readfirstlane_b32 s45, v138
	v_add_u32_e32 v138, 0x2000, v131
	global_load_lds_dwordx4 v[134:135], off
	v_lshl_add_u64 v[136:137], v[134:135], 0, s[6:7]
	s_mov_b32 m0, s45
	v_readfirstlane_b32 s45, v138
	global_load_lds_dwordx4 v[136:137], off
	v_lshl_add_u64 v[136:137], v[134:135], 0, s[8:9]
	s_mov_b32 m0, s45
	v_lshl_add_u64 v[134:135], v[134:135], 0, s[10:11]
	global_load_lds_dwordx4 v[136:137], off
	v_add_u32_e32 v136, 0x3000, v131
	v_lshl_add_u64 v[132:133], s[36:37], 0, v[132:133]
	v_readfirstlane_b32 s45, v136
	s_mov_b32 m0, s45
	v_lshl_add_u64 v[132:133], v[132:133], 0, v[184:185]
	global_load_lds_dwordx4 v[134:135], off
	v_add_u32_e32 v134, 0x4000, v131
	v_add_u32_e32 v131, 0x5000, v131
	v_readfirstlane_b32 s45, v134
	s_mov_b32 m0, s45
	v_readfirstlane_b32 s45, v131
	global_load_lds_dwordx4 v[132:133], off
	v_lshl_add_u64 v[132:133], v[132:133], 0, s[6:7]
	s_mov_b32 m0, s45
	v_mov_b32_e32 v131, v172
	global_load_lds_dwordx4 v[132:133], off
	s_and_b32 s26, s79, 1
	v_ashrrev_i32_e32 v139, 6, v131
	v_bfe_u32 v132, v131, 2, 4
	v_and_b32_e32 v138, 63, v131
	v_and_b32_e32 v133, 3, v131
	v_lshrrev_b32_e32 v131, 4, v131
	v_lshl_or_b32 v132, v139, 4, v132
	v_bitop3_b32 v131, v131, v133, 2 bitop3:0x6c
	v_ashrrev_i32_e32 v133, 31, v132
	s_addk_i32 s44, 0x6000
	v_lshlrev_b64 v[132:133], 11, v[132:133]
	s_cmp_lg_u32 s72, 2
	v_lshl_add_u64 v[134:135], s[34:35], 0, v[132:133]
	s_cselect_b32 s34, s44, 0
	v_lshlrev_b32_e32 v184, 4, v131
	s_add_i32 s34, s34, 0
	v_lshlrev_b32_e32 v131, 10, v139
	v_lshlrev_b32_e32 v138, 4, v138
	v_add3_u32 v131, s34, v131, v138
	v_lshl_add_u64 v[134:135], v[134:135], 0, v[184:185]
	v_readfirstlane_b32 s34, v131
	v_add_u32_e32 v138, 0x1000, v131
	v_lshl_add_u64 v[136:137], v[134:135], 0, 64
	s_mov_b32 m0, s34
	v_readfirstlane_b32 s34, v138
	v_add_u32_e32 v138, 0x2000, v131
	global_load_lds_dwordx4 v[136:137], off
	v_lshl_add_u64 v[136:137], v[134:135], 0, s[12:13]
	s_mov_b32 m0, s34
	v_readfirstlane_b32 s34, v138
	global_load_lds_dwordx4 v[136:137], off
	v_lshl_add_u64 v[136:137], v[134:135], 0, s[14:15]
	s_mov_b32 m0, s34
	v_lshl_add_u64 v[132:133], s[36:37], 0, v[132:133]
	global_load_lds_dwordx4 v[136:137], off
	v_add_u32_e32 v136, 0x3000, v131
	v_lshl_add_u64 v[134:135], v[134:135], 0, s[16:17]
	v_readfirstlane_b32 s34, v136
	v_add_u32_e32 v136, 0x4000, v131
	s_mov_b32 m0, s34
	v_lshl_add_u64 v[132:133], v[132:133], 0, v[184:185]
	v_readfirstlane_b32 s34, v136
	v_add_u32_e32 v131, 0x5000, v131
	global_load_lds_dwordx4 v[134:135], off
	v_lshl_add_u64 v[134:135], v[132:133], 0, 64
	s_mov_b32 m0, s34
	v_readfirstlane_b32 s34, v131
	global_load_lds_dwordx4 v[134:135], off
	s_mov_b32 m0, s34
	s_lshl_b32 s34, s33, 10
	v_lshlrev_b32_e32 v129, 6, v129
	v_lshlrev_b32_e32 v130, 2, v130
	s_ashr_i32 s35, s34, 31
	v_add3_u32 v130, v129, s77, v130
	s_lshl_b64 s[34:35], s[34:35], 2
	s_add_u32 s34, s59, s34
	v_ashrrev_i32_e32 v131, 31, v130
	s_addc_u32 s35, s60, s35
	v_lshlrev_b64 v[136:137], 2, v[130:131]
	v_lshl_add_u64 v[132:133], v[132:133], 0, s[12:13]
	v_lshl_add_u64 v[130:131], s[34:35], 0, v[136:137]
	global_load_lds_dwordx4 v[132:133], off
	global_load_dwordx4 v[132:135], v[130:131], off
	v_and_b32_e32 v128, 0xffffff8f, v128
	v_add_u32_e32 v129, s78, v128
	v_and_b32_e32 v128, 1, v129
	v_cmp_eq_u32_e32 vcc, 0, v128
	s_cmp_eq_u32 s26, 0
	s_mov_b64 s[36:37], 0
	v_cndmask_b32_e64 v128, -1.0, 1.0, vcc
	s_cselect_b64 vcc, -1, 0
	s_lshl_b32 s33, s33, 11
	s_lshl_b32 s26, s26, 10
	s_or_b32 s26, s26, s33
	s_or_b32 s34, s28, s75
	s_ashr_i32 s35, s34, 31
	s_lshl_b64 s[34:35], s[34:35], 11
	s_waitcnt vmcnt(0)
;     template <int MT> DEVI void operator()(f32x4 (&acc)[MT][4], int row0, int col0, int fr, int fq) const {
; #pragma unroll
;         for (int n = 0; n < 4; ++n) {
;             const int e = col0 + 16 * n + 4 * fq;
;             f32x4 pv = *(const f32x4*)(ps1024 + b * 1024 + e);
;             if (par) pv = (f32x4){0.f, 0.f, 0.f, 0.f};
; #pragma unroll
;             for (int m = 0; m < MT; ++m) {
;                 const int k = row0 + 16 * m + fr;
;                 const float sg = (k & 1) ? -1.0f : 1.0f;
;                 *(f32x4*)(T + ((size_t)((b * 2 + par) * 1024 + k)) * 1024 + e) = acc[m][n] + pv * sg;
;             }
;         }
;     }
	v_cndmask_b32_e32 v141, 0, v135, vcc
	v_cndmask_b32_e32 v140, 0, v134, vcc
	v_pk_fma_f32 v[134:135], v[128:129], v[140:141], v[126:127] op_sel_hi:[0,1,1]
	v_add_u32_e32 v126, s26, v129
	v_cndmask_b32_e32 v139, 0, v133, vcc
	v_cndmask_b32_e32 v138, 0, v132, vcc
	v_ashrrev_i32_e32 v127, 31, v126
	v_pk_fma_f32 v[132:133], v[128:129], v[138:139], v[124:125] op_sel_hi:[0,1,1]
	v_lshlrev_b64 v[124:125], 12, v[126:127]
	v_lshl_add_u64 v[124:125], s[40:41], 0, v[124:125]
	v_lshl_add_u64 v[124:125], v[124:125], 0, v[136:137]
	global_store_dwordx4 v[124:125], v[132:135], off
	v_pk_fma_f32 v[114:115], v[128:129], v[140:141], v[114:115] op_sel_hi:[0,1,1]
	v_pk_fma_f32 v[112:113], v[128:129], v[138:139], v[112:113] op_sel_hi:[0,1,1]
	v_pk_fma_f32 v[132:133], v[128:129], v[138:139], v[120:121] op_sel_hi:[0,1,1]
	v_add_u32_e32 v120, 16, v126
	v_ashrrev_i32_e32 v121, 31, v120
	v_lshlrev_b64 v[120:121], 12, v[120:121]
	v_lshl_add_u64 v[120:121], s[40:41], 0, v[120:121]
	v_pk_fma_f32 v[134:135], v[128:129], v[140:141], v[122:123] op_sel_hi:[0,1,1]
	v_lshl_add_u64 v[120:121], v[120:121], 0, v[136:137]
	global_store_dwordx4 v[120:121], v[132:135], off
	s_add_u32 s26, s76, s34
	s_addc_u32 s33, 0, s35
	v_pk_fma_f32 v[132:133], v[128:129], v[138:139], v[116:117] op_sel_hi:[0,1,1]
	v_add_u32_e32 v116, 32, v126
	v_ashrrev_i32_e32 v117, 31, v116
	v_lshlrev_b64 v[116:117], 12, v[116:117]
	v_lshl_add_u64 v[116:117], s[40:41], 0, v[116:117]
	v_pk_fma_f32 v[134:135], v[128:129], v[140:141], v[118:119] op_sel_hi:[0,1,1]
	v_lshl_add_u64 v[116:117], v[116:117], 0, v[136:137]
	global_store_dwordx4 v[116:117], v[132:135], off
	s_add_u32 s34, s90, s26
	s_addc_u32 s35, s91, s33
	v_pk_fma_f32 v[132:133], v[128:129], v[138:139], v[108:109] op_sel_hi:[0,1,1]
	v_add_u32_e32 v108, 48, v126
	v_ashrrev_i32_e32 v109, 31, v108
	v_lshlrev_b64 v[108:109], 12, v[108:109]
	v_lshl_add_u64 v[108:109], s[40:41], 0, v[108:109]
	v_pk_fma_f32 v[134:135], v[128:129], v[140:141], v[110:111] op_sel_hi:[0,1,1]
	v_lshl_add_u64 v[110:111], v[108:109], 0, v[136:137]
	v_add_u32_e32 v108, 64, v126
	v_ashrrev_i32_e32 v109, 31, v108
	v_lshlrev_b64 v[108:109], 12, v[108:109]
	v_lshl_add_u64 v[108:109], s[40:41], 0, v[108:109]
	v_lshl_add_u64 v[108:109], v[108:109], 0, v[136:137]
	global_store_dwordx4 v[108:109], v[112:115], off
	global_store_dwordx4 v[110:111], v[132:135], off
	s_nop 0
	v_pk_fma_f32 v[112:113], v[128:129], v[138:139], v[104:105] op_sel_hi:[0,1,1]
	v_add_u32_e32 v104, 0x50, v126
	v_ashrrev_i32_e32 v105, 31, v104
	v_lshlrev_b64 v[104:105], 12, v[104:105]
	v_lshl_add_u64 v[104:105], s[40:41], 0, v[104:105]
	v_pk_fma_f32 v[114:115], v[128:129], v[140:141], v[106:107] op_sel_hi:[0,1,1]
	v_lshl_add_u64 v[104:105], v[104:105], 0, v[136:137]
	global_store_dwordx4 v[104:105], v[112:115], off
	s_nop 1
	v_pk_fma_f32 v[112:113], v[128:129], v[138:139], v[100:101] op_sel_hi:[0,1,1]
	v_add_u32_e32 v100, 0x60, v126
	v_ashrrev_i32_e32 v101, 31, v100
	v_lshlrev_b64 v[100:101], 12, v[100:101]
	v_lshl_add_u64 v[100:101], s[40:41], 0, v[100:101]
	v_pk_fma_f32 v[114:115], v[128:129], v[140:141], v[102:103] op_sel_hi:[0,1,1]
	v_lshl_add_u64 v[100:101], v[100:101], 0, v[136:137]
	global_store_dwordx4 v[100:101], v[112:115], off
	s_nop 1
	v_pk_fma_f32 v[112:113], v[128:129], v[138:139], v[96:97] op_sel_hi:[0,1,1]
	v_add_u32_e32 v96, 0x70, v126
	v_ashrrev_i32_e32 v97, 31, v96
	v_lshlrev_b64 v[96:97], 12, v[96:97]
	v_lshl_add_u64 v[96:97], s[40:41], 0, v[96:97]
	v_pk_fma_f32 v[114:115], v[128:129], v[140:141], v[98:99] op_sel_hi:[0,1,1]
	v_lshl_add_u64 v[96:97], v[96:97], 0, v[136:137]
	global_store_dwordx4 v[96:97], v[112:115], off
	global_load_dwordx4 v[112:115], v[130:131], off offset:64
	v_mov_b32_e32 v136, v172
	s_waitcnt vmcnt(0)
	v_cndmask_b32_e32 v99, 0, v113, vcc
	v_cndmask_b32_e32 v98, 0, v112, vcc
	v_cndmask_b32_e32 v103, 0, v115, vcc
	v_cndmask_b32_e32 v102, 0, v114, vcc
	v_pk_fma_f32 v[66:67], v[128:129], v[102:103], v[66:67] op_sel_hi:[0,1,1]
	v_pk_fma_f32 v[64:65], v[128:129], v[98:99], v[64:65] op_sel_hi:[0,1,1]
	global_store_dwordx4 v[124:125], v[64:67], off offset:64
	s_nop 1
	v_pk_fma_f32 v[66:67], v[128:129], v[102:103], v[70:71] op_sel_hi:[0,1,1]
	v_pk_fma_f32 v[64:65], v[128:129], v[98:99], v[68:69] op_sel_hi:[0,1,1]
	global_store_dwordx4 v[120:121], v[64:67], off offset:64
	s_nop 1
	v_pk_fma_f32 v[66:67], v[128:129], v[102:103], v[74:75] op_sel_hi:[0,1,1]
	v_pk_fma_f32 v[64:65], v[128:129], v[98:99], v[72:73] op_sel_hi:[0,1,1]
	global_store_dwordx4 v[116:117], v[64:67], off offset:64
	s_nop 1
	v_pk_fma_f32 v[66:67], v[128:129], v[102:103], v[78:79] op_sel_hi:[0,1,1]
	v_pk_fma_f32 v[64:65], v[128:129], v[98:99], v[76:77] op_sel_hi:[0,1,1]
	global_store_dwordx4 v[110:111], v[64:67], off offset:64
	s_nop 1
	v_pk_fma_f32 v[66:67], v[128:129], v[102:103], v[82:83] op_sel_hi:[0,1,1]
	v_pk_fma_f32 v[64:65], v[128:129], v[98:99], v[80:81] op_sel_hi:[0,1,1]
	global_store_dwordx4 v[108:109], v[64:67], off offset:64
	s_nop 1
	v_pk_fma_f32 v[66:67], v[128:129], v[102:103], v[86:87] op_sel_hi:[0,1,1]
	v_pk_fma_f32 v[64:65], v[128:129], v[98:99], v[84:85] op_sel_hi:[0,1,1]
	global_store_dwordx4 v[104:105], v[64:67], off offset:64
	s_nop 1
	v_pk_fma_f32 v[66:67], v[128:129], v[102:103], v[90:91] op_sel_hi:[0,1,1]
	v_pk_fma_f32 v[64:65], v[128:129], v[98:99], v[88:89] op_sel_hi:[0,1,1]
	global_store_dwordx4 v[100:101], v[64:67], off offset:64
	s_nop 1
	v_pk_fma_f32 v[66:67], v[128:129], v[102:103], v[94:95] op_sel_hi:[0,1,1]
	v_pk_fma_f32 v[64:65], v[128:129], v[98:99], v[92:93] op_sel_hi:[0,1,1]
	global_store_dwordx4 v[96:97], v[64:67], off offset:64
	global_load_dwordx4 v[64:67], v[130:131], off offset:128
	s_waitcnt vmcnt(0)
; DEVI int opaque_tid() { int t = (int)threadIdx.x; asm volatile("" : "+v"(t)); return t; }
; template <bool TRANS, class Epi>
; DEVI int g2_body(const G2Tile& t, int st, char* smem, bool has_next, const G2Tile& nxt, const Epi& epi) {
;     const int tid = opaque_tid(), lane = tid & 63, w = tid >> 6, wr = w >> 1, wc = w & 1, fr = lane & 15, fq = lane >> 4;
;     f32x4 acc[8][4];
; #pragma unroll
;     for (int m = 0; m < 8; ++m)
; #pragma unroll
;         for (int n = 0; n < 4; ++n) acc[m][n] = (f32x4){0.f, 0.f, 0.f, 0.f};
;     const int frag = fr * 64 + ((fq ^ ((fr >> 3) << 1)) << 4);
;     template <int MT> DEVI void operator()(f32x4 (&acc)[MT][4], int row0, int col0, int fr, int fq) const {
; #pragma unroll
;         for (int n = 0; n < 4; ++n) {
;             const int e = col0 + 16 * n + 4 * fq;
;             f32x4 pv = *(const f32x4*)(ps1024 + b * 1024 + e);
;             if (par) pv = (f32x4){0.f, 0.f, 0.f, 0.f};
; #pragma unroll
;             for (int m = 0; m < MT; ++m) {
;                 const int k = row0 + 16 * m + fr;
;                 const float sg = (k & 1) ? -1.0f : 1.0f;
;                 *(f32x4*)(T + ((size_t)((b * 2 + par) * 1024 + k)) * 1024 + e) = acc[m][n] + pv * sg;
;             }
;         }
;     }
	v_cndmask_b32_e32 v65, 0, v65, vcc
	v_cndmask_b32_e32 v64, 0, v64, vcc
	v_cndmask_b32_e32 v67, 0, v67, vcc
	v_cndmask_b32_e32 v66, 0, v66, vcc
	v_pk_fma_f32 v[34:35], v[128:129], v[66:67], v[34:35] op_sel_hi:[0,1,1]
	v_pk_fma_f32 v[32:33], v[128:129], v[64:65], v[32:33] op_sel_hi:[0,1,1]
	global_store_dwordx4 v[124:125], v[32:35], off offset:128
	s_nop 1
	v_pk_fma_f32 v[34:35], v[128:129], v[66:67], v[38:39] op_sel_hi:[0,1,1]
	v_pk_fma_f32 v[32:33], v[128:129], v[64:65], v[36:37] op_sel_hi:[0,1,1]
	global_store_dwordx4 v[120:121], v[32:35], off offset:128
	s_nop 1
	v_pk_fma_f32 v[34:35], v[128:129], v[66:67], v[42:43] op_sel_hi:[0,1,1]
	v_pk_fma_f32 v[32:33], v[128:129], v[64:65], v[40:41] op_sel_hi:[0,1,1]
	global_store_dwordx4 v[116:117], v[32:35], off offset:128
	s_nop 1
	v_pk_fma_f32 v[34:35], v[128:129], v[66:67], v[46:47] op_sel_hi:[0,1,1]
	v_pk_fma_f32 v[32:33], v[128:129], v[64:65], v[44:45] op_sel_hi:[0,1,1]
	global_store_dwordx4 v[110:111], v[32:35], off offset:128
	s_nop 1
	v_pk_fma_f32 v[34:35], v[128:129], v[66:67], v[50:51] op_sel_hi:[0,1,1]
	v_pk_fma_f32 v[32:33], v[128:129], v[64:65], v[48:49] op_sel_hi:[0,1,1]
	global_store_dwordx4 v[108:109], v[32:35], off offset:128
	s_nop 1
	v_pk_fma_f32 v[34:35], v[128:129], v[66:67], v[54:55] op_sel_hi:[0,1,1]
	v_pk_fma_f32 v[32:33], v[128:129], v[64:65], v[52:53] op_sel_hi:[0,1,1]
	global_store_dwordx4 v[104:105], v[32:35], off offset:128
	s_nop 1
	v_pk_fma_f32 v[34:35], v[128:129], v[66:67], v[58:59] op_sel_hi:[0,1,1]
	v_pk_fma_f32 v[32:33], v[128:129], v[64:65], v[56:57] op_sel_hi:[0,1,1]
	global_store_dwordx4 v[100:101], v[32:35], off offset:128
	s_nop 1
	v_pk_fma_f32 v[34:35], v[128:129], v[66:67], v[62:63] op_sel_hi:[0,1,1]
	v_pk_fma_f32 v[32:33], v[128:129], v[64:65], v[60:61] op_sel_hi:[0,1,1]
	global_store_dwordx4 v[96:97], v[32:35], off offset:128
	global_load_dwordx4 v[32:35], v[130:131], off offset:192
	s_waitcnt vmcnt(0)
	v_cndmask_b32_e32 v33, 0, v33, vcc
	v_cndmask_b32_e32 v32, 0, v32, vcc
	v_cndmask_b32_e32 v35, 0, v35, vcc
	v_cndmask_b32_e32 v34, 0, v34, vcc
	v_pk_fma_f32 v[14:15], v[128:129], v[34:35], v[14:15] op_sel_hi:[0,1,1]
	v_pk_fma_f32 v[12:13], v[128:129], v[32:33], v[12:13] op_sel_hi:[0,1,1]
	v_pk_fma_f32 v[30:31], v[128:129], v[34:35], v[30:31] op_sel_hi:[0,1,1]
	v_pk_fma_f32 v[28:29], v[128:129], v[32:33], v[28:29] op_sel_hi:[0,1,1]
	v_pk_fma_f32 v[26:27], v[128:129], v[34:35], v[26:27] op_sel_hi:[0,1,1]
	v_pk_fma_f32 v[24:25], v[128:129], v[32:33], v[24:25] op_sel_hi:[0,1,1]
	v_pk_fma_f32 v[22:23], v[128:129], v[34:35], v[22:23] op_sel_hi:[0,1,1]
	v_pk_fma_f32 v[20:21], v[128:129], v[32:33], v[20:21] op_sel_hi:[0,1,1]
	global_store_dwordx4 v[110:111], v[12:15], off offset:192
	v_pk_fma_f32 v[10:11], v[128:129], v[34:35], v[10:11] op_sel_hi:[0,1,1]
	v_pk_fma_f32 v[8:9], v[128:129], v[32:33], v[8:9] op_sel_hi:[0,1,1]
	v_pk_fma_f32 v[14:15], v[128:129], v[34:35], v[18:19] op_sel_hi:[0,1,1]
	v_pk_fma_f32 v[12:13], v[128:129], v[32:33], v[16:17] op_sel_hi:[0,1,1]
	v_pk_fma_f32 v[6:7], v[128:129], v[34:35], v[6:7] op_sel_hi:[0,1,1]
	v_pk_fma_f32 v[4:5], v[128:129], v[32:33], v[4:5] op_sel_hi:[0,1,1]
	v_pk_fma_f32 v[2:3], v[128:129], v[34:35], v[2:3] op_sel_hi:[0,1,1]
	v_pk_fma_f32 v[0:1], v[128:129], v[32:33], v[0:1] op_sel_hi:[0,1,1]
	global_store_dwordx4 v[124:125], v[28:31], off offset:192
	global_store_dwordx4 v[120:121], v[24:27], off offset:192
	global_store_dwordx4 v[116:117], v[20:23], off offset:192
	global_store_dwordx4 v[108:109], v[12:15], off offset:192
	global_store_dwordx4 v[104:105], v[8:11], off offset:192
	global_store_dwordx4 v[100:101], v[4:7], off offset:192
	global_store_dwordx4 v[96:97], v[0:3], off offset:192
	s_nop 0
	v_and_b32_e32 v137, 15, v136
	v_lshrrev_b32_e32 v2, 2, v136
	v_lshrrev_b32_e32 v0, 4, v136
	v_and_b32_e32 v2, 2, v2
	v_bitop3_b32 v0, v0, v2, 3 bitop3:0x6c
	v_lshlrev_b32_e32 v1, 6, v137
	v_lshlrev_b32_e32 v0, 4, v0
	v_add3_u32 v129, 0, v1, v0
	v_lshlrev_b32_e32 v0, 6, v136
	v_bfe_u32 v138, v136, 6, 1
	v_and_b32_e32 v130, 0xffffe000, v0
	v_mov_b32_e32 v0, 0
	v_bfe_u32 v177, v136, 4, 2
	v_lshlrev_b32_e32 v128, 12, v138
	v_mov_b32_e32 v1, v0
	v_mov_b32_e32 v2, v0
	v_mov_b32_e32 v3, v0
	v_mov_b32_e32 v4, v0
	v_mov_b32_e32 v5, v0
	v_mov_b32_e32 v6, v0
	v_mov_b32_e32 v7, v0
	v_mov_b32_e32 v8, v0
	v_mov_b32_e32 v9, v0
	v_mov_b32_e32 v10, v0
	v_mov_b32_e32 v11, v0
	v_mov_b32_e32 v12, v0
	v_mov_b32_e32 v13, v0
	v_mov_b32_e32 v14, v0
	v_mov_b32_e32 v15, v0
	v_mov_b32_e32 v16, v0
	v_mov_b32_e32 v17, v0
	v_mov_b32_e32 v18, v0
	v_mov_b32_e32 v19, v0
	v_mov_b32_e32 v20, v0
	v_mov_b32_e32 v21, v0
	v_mov_b32_e32 v22, v0
	v_mov_b32_e32 v23, v0
	v_mov_b32_e32 v24, v0
	v_mov_b32_e32 v25, v0
	v_mov_b32_e32 v26, v0
	v_mov_b32_e32 v27, v0
	v_mov_b32_e32 v28, v0
	v_mov_b32_e32 v29, v0
	v_mov_b32_e32 v30, v0
	v_mov_b32_e32 v31, v0
	v_mov_b32_e32 v32, v0
	v_mov_b32_e32 v33, v0
	v_mov_b32_e32 v34, v0
	v_mov_b32_e32 v35, v0
	v_mov_b32_e32 v36, v0
	v_mov_b32_e32 v37, v0
	v_mov_b32_e32 v38, v0
	v_mov_b32_e32 v39, v0
	v_mov_b32_e32 v40, v0
	v_mov_b32_e32 v41, v0
	v_mov_b32_e32 v42, v0
	v_mov_b32_e32 v43, v0
	v_mov_b32_e32 v44, v0
	v_mov_b32_e32 v45, v0
	v_mov_b32_e32 v46, v0
	v_mov_b32_e32 v47, v0
	v_mov_b32_e32 v48, v0
	v_mov_b32_e32 v49, v0
	v_mov_b32_e32 v50, v0
	v_mov_b32_e32 v51, v0
	v_mov_b32_e32 v52, v0
	v_mov_b32_e32 v53, v0
	v_mov_b32_e32 v54, v0
	v_mov_b32_e32 v55, v0
	v_mov_b32_e32 v56, v0
	v_mov_b32_e32 v57, v0
	v_mov_b32_e32 v58, v0
	v_mov_b32_e32 v59, v0
	v_mov_b32_e32 v60, v0
	v_mov_b32_e32 v61, v0
	v_mov_b32_e32 v62, v0
	v_mov_b32_e32 v63, v0
	v_mov_b32_e32 v64, v0
	v_mov_b32_e32 v65, v0
	v_mov_b32_e32 v66, v0
	v_mov_b32_e32 v67, v0
; DEVI int opaque_tid() { int t = (int)threadIdx.x; asm volatile("" : "+v"(t)); return t; }
; template <bool TRANS, class Epi>
; DEVI int g2_body(const G2Tile& t, int st, char* smem, bool has_next, const G2Tile& nxt, const Epi& epi) {
;     const int tid = opaque_tid(), lane = tid & 63, w = tid >> 6, wr = w >> 1, wc = w & 1, fr = lane & 15, fq = lane >> 4;
;     f32x4 acc[8][4];
; #pragma unroll
;     for (int m = 0; m < 8; ++m)
; #pragma unroll
;         for (int n = 0; n < 4; ++n) acc[m][n] = (f32x4){0.f, 0.f, 0.f, 0.f};
;     const int frag = fr * 64 + ((fq ^ ((fr >> 3) << 1)) << 4);
;     const int nk = t.nk;
;     for (int kt = 0; kt < nk; ++kt) {
;         if (kt + 1 < nk) asm volatile("s_waitcnt vmcnt(6)" ::: "memory");
;         else asm volatile("s_waitcnt vmcnt(0)" ::: "memory");
;         __syncthreads();
;         if (kt + 2 < nk) g2_issue(t, kt + 2, st >= 1 ? st - 1 : 2, smem);
;         const char* sa = smem + st * 24576 + frag;
;         bf16x8 bfr[4];
; #pragma unroll
;         for (int n = 0; n < 4; ++n) bfr[n] = *(const bf16x8*)(sa + (16 + wc * 4 + n) * 1024);
; #pragma unroll
;         for (int mh = 0; mh < 2; ++mh) {
;             bf16x8 af[4];
; #pragma unroll
;             for (int m = 0; m < 4; ++m) af[m] = *(const bf16x8*)(sa + (wr * 8 + mh * 4 + m) * 1024);
;             __builtin_amdgcn_s_setprio(1);
; #pragma unroll
;             for (int m = 0; m < 4; ++m)
; #pragma unroll
;                 for (int n = 0; n < 4; ++n)
;                     acc[mh * 4 + m][n] = TRANS ? __builtin_amdgcn_mfma_f32_16x16x32_bf16(bfr[n], af[m], acc[mh * 4 + m][n], 0, 0, 0)
;                                                : __builtin_amdgcn_mfma_f32_16x16x32_bf16(af[m], bfr[n], acc[mh * 4 + m][n], 0, 0, 0);
;             __builtin_amdgcn_s_setprio(0);
;         }
;         st = st == 2 ? 0 : st + 1;
;     }
	v_mov_b32_e32 v68, v0
	v_mov_b32_e32 v69, v0
	v_mov_b32_e32 v70, v0
	v_mov_b32_e32 v71, v0
	v_mov_b32_e32 v72, v0
	v_mov_b32_e32 v73, v0
	v_mov_b32_e32 v74, v0
	v_mov_b32_e32 v75, v0
	v_mov_b32_e32 v76, v0
	v_mov_b32_e32 v77, v0
	v_mov_b32_e32 v78, v0
	v_mov_b32_e32 v79, v0
	v_mov_b32_e32 v80, v0
	v_mov_b32_e32 v81, v0
	v_mov_b32_e32 v82, v0
	v_mov_b32_e32 v83, v0
	v_mov_b32_e32 v84, v0
	v_mov_b32_e32 v85, v0
	v_mov_b32_e32 v86, v0
	v_mov_b32_e32 v87, v0
	v_mov_b32_e32 v96, v0
	v_mov_b32_e32 v97, v0
	v_mov_b32_e32 v98, v0
	v_mov_b32_e32 v99, v0
	v_mov_b32_e32 v108, v0
	v_mov_b32_e32 v109, v0
	v_mov_b32_e32 v110, v0
	v_mov_b32_e32 v111, v0
	v_mov_b32_e32 v112, v0
	v_mov_b32_e32 v113, v0
	v_mov_b32_e32 v114, v0
	v_mov_b32_e32 v115, v0
	v_mov_b32_e32 v116, v0
	v_mov_b32_e32 v117, v0
	v_mov_b32_e32 v118, v0
	v_mov_b32_e32 v119, v0
	v_mov_b32_e32 v120, v0
	v_mov_b32_e32 v121, v0
	v_mov_b32_e32 v122, v0
	v_mov_b32_e32 v123, v0
	v_mov_b32_e32 v124, v0
	v_mov_b32_e32 v125, v0
	v_mov_b32_e32 v126, v0
	v_mov_b32_e32 v127, v0
	v_mov_b32_e32 v88, v0
	v_mov_b32_e32 v89, v0
	v_mov_b32_e32 v90, v0
	v_mov_b32_e32 v91, v0
	v_mov_b32_e32 v92, v0
	v_mov_b32_e32 v93, v0
	v_mov_b32_e32 v94, v0
	v_mov_b32_e32 v95, v0
	v_mov_b32_e32 v100, v0
	v_mov_b32_e32 v101, v0
	v_mov_b32_e32 v102, v0
	v_mov_b32_e32 v103, v0
	v_mov_b32_e32 v104, v0
	v_mov_b32_e32 v105, v0
	v_mov_b32_e32 v106, v0
	v_mov_b32_e32 v107, v0
.LBB0_821:
	v_mov_b32_e32 v131, v172
	s_waitcnt vmcnt(6)
	s_waitcnt lgkmcnt(0)
	s_barrier
	s_mul_i32 s26, s72, 0x6000
	s_add_i32 s33, s26, 0xffffa000
	v_ashrrev_i32_e32 v142, 6, v131
	v_bfe_u32 v132, v131, 2, 4
	v_and_b32_e32 v139, 63, v131
	v_and_b32_e32 v133, 3, v131
	v_lshrrev_b32_e32 v131, 4, v131
	v_lshl_or_b32 v132, v142, 4, v132
	s_cmp_gt_i32 s72, 0
	v_bitop3_b32 v131, v131, v133, 2 bitop3:0x6c
	v_ashrrev_i32_e32 v133, 31, v132
	v_lshlrev_b64 v[132:133], 11, v[132:133]
	s_cselect_b32 s33, s33, 0xc000
	v_lshl_or_b32 v132, v131, 4, v132
	s_add_i32 s33, s33, 0
	v_lshlrev_b32_e32 v131, 10, v142
	v_lshlrev_b32_e32 v139, 4, v139
	v_lshl_add_u64 v[132:133], s[36:37], 0, v[132:133]
	v_add3_u32 v131, s33, v131, v139
	v_lshl_add_u64 v[134:135], s[30:31], 0, v[132:133]
	s_mov_b64 s[44:45], 0x1b100080
	v_readfirstlane_b32 s33, v131
	v_add_u32_e32 v139, 0x1000, v131
	v_lshl_add_u64 v[140:141], v[134:135], 0, s[44:45]
	s_mov_b32 m0, s33
	s_mov_b64 s[44:45], 0x1b120080
	v_readfirstlane_b32 s33, v139
	v_add_u32_e32 v139, 0x2000, v131
	global_load_lds_dwordx4 v[140:141], off
	v_lshl_add_u64 v[140:141], v[134:135], 0, s[44:45]
	s_mov_b32 m0, s33
	s_mov_b64 s[44:45], 0x1b140080
	v_readfirstlane_b32 s33, v139
	v_add_u32_e32 v139, 0x3000, v131
	global_load_lds_dwordx4 v[140:141], off
	v_lshl_add_u64 v[140:141], v[134:135], 0, s[44:45]
	s_mov_b32 m0, s33
	s_mov_b64 s[44:45], 0x1b160080
	v_readfirstlane_b32 s33, v139
	v_add_u32_e32 v139, 0x4000, v131
	global_load_lds_dwordx4 v[140:141], off
	v_lshl_add_u64 v[134:135], v[134:135], 0, s[44:45]
	s_mov_b32 m0, s33
	v_lshl_add_u64 v[132:133], s[34:35], 0, v[132:133]
	s_mov_b64 s[44:45], 0x1bd00080
	v_readfirstlane_b32 s33, v139
	v_add_u32_e32 v131, 0x5000, v131
	global_load_lds_dwordx4 v[134:135], off
	v_lshl_add_u64 v[134:135], v[132:133], 0, s[44:45]
	s_mov_b32 m0, s33
	s_mov_b64 s[44:45], 0x1bd20080
	v_readfirstlane_b32 s33, v131
	global_load_lds_dwordx4 v[134:135], off
	v_lshl_add_u64 v[132:133], v[132:133], 0, s[44:45]
	s_mov_b32 m0, s33
	v_add_u32_e32 v131, s26, v129
	global_load_lds_dwordx4 v[132:133], off
	v_add_u32_e32 v139, v131, v128
	v_add_u32_e32 v131, v131, v130
	ds_read_b128 v[132:135], v139 offset:16384
	ds_read_b128 v[140:143], v139 offset:17408
	ds_read_b128 v[144:147], v139 offset:18432
	ds_read_b128 v[148:151], v139 offset:19456
	ds_read_b128 v[152:155], v131
	ds_read_b128 v[156:159], v131 offset:1024
	ds_read_b128 v[160:163], v131 offset:2048
	ds_read_b128 v[164:167], v131 offset:3072
	s_setprio 1
	s_waitcnt lgkmcnt(0)
	v_mfma_f32_16x16x32_bf16 v[124:127], v[132:135], v[152:155], v[124:127]
	v_mfma_f32_16x16x32_bf16 v[120:123], v[140:143], v[152:155], v[120:123]
	v_mfma_f32_16x16x32_bf16 v[116:119], v[144:147], v[152:155], v[116:119]
	v_mfma_f32_16x16x32_bf16 v[112:115], v[148:151], v[152:155], v[112:115]
	v_mfma_f32_16x16x32_bf16 v[108:111], v[132:135], v[156:159], v[108:111]
	v_mfma_f32_16x16x32_bf16 v[96:99], v[140:143], v[156:159], v[96:99]
	v_mfma_f32_16x16x32_bf16 v[84:87], v[144:147], v[156:159], v[84:87]
	v_mfma_f32_16x16x32_bf16 v[80:83], v[148:151], v[156:159], v[80:83]
	v_mfma_f32_16x16x32_bf16 v[76:79], v[132:135], v[160:163], v[76:79]
	v_mfma_f32_16x16x32_bf16 v[72:75], v[140:143], v[160:163], v[72:75]
	v_mfma_f32_16x16x32_bf16 v[68:71], v[144:147], v[160:163], v[68:71]
	v_mfma_f32_16x16x32_bf16 v[64:67], v[148:151], v[160:163], v[64:67]
	v_mfma_f32_16x16x32_bf16 v[60:63], v[132:135], v[164:167], v[60:63]
	v_mfma_f32_16x16x32_bf16 v[56:59], v[140:143], v[164:167], v[56:59]
	v_mfma_f32_16x16x32_bf16 v[52:55], v[144:147], v[164:167], v[52:55]
	v_mfma_f32_16x16x32_bf16 v[48:51], v[148:151], v[164:167], v[48:51]
	s_setprio 0
	ds_read_b128 v[152:155], v131 offset:4096
	ds_read_b128 v[156:159], v131 offset:5120
	ds_read_b128 v[160:163], v131 offset:6144
	ds_read_b128 v[164:167], v131 offset:7168
	s_setprio 1
	s_waitcnt lgkmcnt(0)
	v_mfma_f32_16x16x32_bf16 v[44:47], v[132:135], v[152:155], v[44:47]
	v_mfma_f32_16x16x32_bf16 v[40:43], v[140:143], v[152:155], v[40:43]
	v_mfma_f32_16x16x32_bf16 v[36:39], v[144:147], v[152:155], v[36:39]
	v_mfma_f32_16x16x32_bf16 v[32:35], v[148:151], v[152:155], v[32:35]
	v_mfma_f32_16x16x32_bf16 v[28:31], v[132:135], v[156:159], v[28:31]
	v_mfma_f32_16x16x32_bf16 v[24:27], v[140:143], v[156:159], v[24:27]
	v_mfma_f32_16x16x32_bf16 v[20:23], v[144:147], v[156:159], v[20:23]
	v_mfma_f32_16x16x32_bf16 v[16:19], v[148:151], v[156:159], v[16:19]
	v_mfma_f32_16x16x32_bf16 v[12:15], v[132:135], v[160:163], v[12:15]
	v_mfma_f32_16x16x32_bf16 v[8:11], v[140:143], v[160:163], v[8:11]
	v_mfma_f32_16x16x32_bf16 v[4:7], v[144:147], v[160:163], v[4:7]
	v_mfma_f32_16x16x32_bf16 v[0:3], v[148:151], v[160:163], v[0:3]
	v_mfma_f32_16x16x32_bf16 v[88:91], v[132:135], v[164:167], v[88:91]
	v_mfma_f32_16x16x32_bf16 v[92:95], v[140:143], v[164:167], v[92:95]
	v_mfma_f32_16x16x32_bf16 v[100:103], v[144:147], v[164:167], v[100:103]
	v_mfma_f32_16x16x32_bf16 v[104:107], v[148:151], v[164:167], v[104:107]
	s_setprio 0
	s_add_i32 s26, s72, 1
	s_cmp_lg_u32 s72, 2
	s_cselect_b32 s72, s26, 0
	s_add_u32 s36, s36, 64
	s_addc_u32 s37, s37, 0
	s_cmpk_eq_i32 s36, 0x780
	s_cbranch_scc0 .LBB0_821
; template <bool TRANS, class Epi>
; DEVI int g2_body(const G2Tile& t, int st, char* smem, bool has_next, const G2Tile& nxt, const Epi& epi) {
;     ...
;     for (int kt = 0; kt < nk; ++kt) {
;         if (kt + 1 < nk) asm volatile("s_waitcnt vmcnt(6)" ::: "memory");
;         else asm volatile("s_waitcnt vmcnt(0)" ::: "memory");
;         __syncthreads();
;         if (kt + 2 < nk) g2_issue(t, kt + 2, st >= 1 ? st - 1 : 2, smem);
;         const char* sa = smem + st * 24576 + frag;
;         bf16x8 bfr[4];
; #pragma unroll
;         for (int n = 0; n < 4; ++n) bfr[n] = *(const bf16x8*)(sa + (16 + wc * 4 + n) * 1024);
; #pragma unroll
;         for (int mh = 0; mh < 2; ++mh) {
;             bf16x8 af[4];
; #pragma unroll
;             for (int m = 0; m < 4; ++m) af[m] = *(const bf16x8*)(sa + (wr * 8 + mh * 4 + m) * 1024);
;             __builtin_amdgcn_s_setprio(1);
; #pragma unroll
;             for (int m = 0; m < 4; ++m)
; #pragma unroll
;                 for (int n = 0; n < 4; ++n)
;                     acc[mh * 4 + m][n] = TRANS ? __builtin_amdgcn_mfma_f32_16x16x32_bf16(bfr[n], af[m], acc[mh * 4 + m][n], 0, 0, 0)
;                                                : __builtin_amdgcn_mfma_f32_16x16x32_bf16(af[m], bfr[n], acc[mh * 4 + m][n], 0, 0, 0);
;             __builtin_amdgcn_s_setprio(0);
;         }
;         st = st == 2 ? 0 : st + 1;
	s_mul_i32 s26, s72, 0x6000
	v_add_u32_e32 v131, s26, v129
	v_add_u32_e32 v139, v131, v128
	v_add_u32_e32 v131, v131, v130
	s_waitcnt vmcnt(6)
	s_barrier
	ds_read_b128 v[132:135], v139 offset:16384
	ds_read_b128 v[140:143], v139 offset:17408
	ds_read_b128 v[144:147], v139 offset:18432
	ds_read_b128 v[148:151], v139 offset:19456
	ds_read_b128 v[152:155], v131
	ds_read_b128 v[156:159], v131 offset:1024
	ds_read_b128 v[160:163], v131 offset:2048
	ds_read_b128 v[164:167], v131 offset:3072
	s_setprio 1
	s_waitcnt lgkmcnt(3)
	v_mfma_f32_16x16x32_bf16 v[116:119], v[144:147], v[152:155], v[116:119]
	s_waitcnt lgkmcnt(2)
	v_mfma_f32_16x16x32_bf16 v[108:111], v[132:135], v[156:159], v[108:111]
	v_mfma_f32_16x16x32_bf16 v[96:99], v[140:143], v[156:159], v[96:99]
	v_mfma_f32_16x16x32_bf16 v[84:87], v[144:147], v[156:159], v[84:87]
	v_mfma_f32_16x16x32_bf16 v[80:83], v[148:151], v[156:159], v[80:83]
	s_waitcnt lgkmcnt(1)
	v_mfma_f32_16x16x32_bf16 v[76:79], v[132:135], v[160:163], v[76:79]
	v_mfma_f32_16x16x32_bf16 v[72:75], v[140:143], v[160:163], v[72:75]
	v_mfma_f32_16x16x32_bf16 v[68:71], v[144:147], v[160:163], v[68:71]
	v_mfma_f32_16x16x32_bf16 v[64:67], v[148:151], v[160:163], v[64:67]
	s_waitcnt lgkmcnt(0)
	v_mfma_f32_16x16x32_bf16 v[60:63], v[132:135], v[164:167], v[60:63]
	v_mfma_f32_16x16x32_bf16 v[56:59], v[140:143], v[164:167], v[56:59]
	v_mfma_f32_16x16x32_bf16 v[52:55], v[144:147], v[164:167], v[52:55]
	v_mfma_f32_16x16x32_bf16 v[48:51], v[148:151], v[164:167], v[48:51]
	v_mfma_f32_16x16x32_bf16 v[124:127], v[132:135], v[152:155], v[124:127]
	v_mfma_f32_16x16x32_bf16 v[120:123], v[140:143], v[152:155], v[120:123]
	v_mfma_f32_16x16x32_bf16 v[112:115], v[148:151], v[152:155], v[112:115]
	s_setprio 0
	ds_read_b128 v[152:155], v131 offset:4096
	ds_read_b128 v[156:159], v131 offset:5120
	ds_read_b128 v[160:163], v131 offset:6144
	ds_read_b128 v[164:167], v131 offset:7168
	s_setprio 1
	s_waitcnt lgkmcnt(3)
	v_mfma_f32_16x16x32_bf16 v[44:47], v[132:135], v[152:155], v[44:47]
	v_mfma_f32_16x16x32_bf16 v[40:43], v[140:143], v[152:155], v[40:43]
	v_mfma_f32_16x16x32_bf16 v[36:39], v[144:147], v[152:155], v[36:39]
	v_mfma_f32_16x16x32_bf16 v[32:35], v[148:151], v[152:155], v[32:35]
	s_waitcnt lgkmcnt(2)
	v_mfma_f32_16x16x32_bf16 v[28:31], v[132:135], v[156:159], v[28:31]
	v_mfma_f32_16x16x32_bf16 v[24:27], v[140:143], v[156:159], v[24:27]
	v_mfma_f32_16x16x32_bf16 v[20:23], v[144:147], v[156:159], v[20:23]
	v_mfma_f32_16x16x32_bf16 v[16:19], v[148:151], v[156:159], v[16:19]
	s_waitcnt lgkmcnt(1)
	v_mfma_f32_16x16x32_bf16 v[12:15], v[132:135], v[160:163], v[12:15]
	v_mfma_f32_16x16x32_bf16 v[8:11], v[140:143], v[160:163], v[8:11]
	v_mfma_f32_16x16x32_bf16 v[4:7], v[144:147], v[160:163], v[4:7]
	v_mfma_f32_16x16x32_bf16 v[0:3], v[148:151], v[160:163], v[0:3]
	s_waitcnt lgkmcnt(0)
	v_mfma_f32_16x16x32_bf16 v[152:155], v[132:135], v[164:167], v[88:91]
	v_mfma_f32_16x16x32_bf16 v[140:143], v[140:143], v[164:167], v[92:95]
	v_mfma_f32_16x16x32_bf16 v[156:159], v[144:147], v[164:167], v[100:103]
	v_mfma_f32_16x16x32_bf16 v[104:107], v[148:151], v[164:167], v[104:107]
	s_setprio 0
	s_add_i32 s26, s72, 1
	s_cmp_lg_u32 s72, 2
	s_cselect_b32 s26, s26, 0
	s_mul_i32 s30, s26, 0x6000
	v_add_u32_e32 v100, s30, v129
	v_add_u32_e32 v139, v100, v130
	v_add_u32_e32 v100, v100, v128
	s_waitcnt vmcnt(0)
	s_barrier
	ds_read_b128 v[160:163], v139 offset:3072
	ds_read_b128 v[164:167], v139 offset:2048
	ds_read_b128 v[88:91], v139 offset:1024
	ds_read_b128 v[92:95], v139
	ds_read_b128 v[168:171], v100 offset:19456
	ds_read_b128 v[186:189], v100 offset:18432
	ds_read_b128 v[190:193], v100 offset:17408
	ds_read_b128 v[194:197], v100 offset:16384
	s_setprio 1
	s_waitcnt lgkmcnt(0)
	v_mfma_f32_16x16x32_bf16 v[148:151], v[194:197], v[92:95], v[124:127]
	v_mfma_f32_16x16x32_bf16 v[144:147], v[190:193], v[92:95], v[120:123]
	v_mfma_f32_16x16x32_bf16 v[132:135], v[186:189], v[92:95], v[116:119]
	v_mfma_f32_16x16x32_bf16 v[128:131], v[168:171], v[92:95], v[112:115]
	v_mfma_f32_16x16x32_bf16 v[116:119], v[194:197], v[88:91], v[108:111]
	v_mfma_f32_16x16x32_bf16 v[108:111], v[190:193], v[88:91], v[96:99]
	v_mfma_f32_16x16x32_bf16 v[100:103], v[186:189], v[88:91], v[84:87]
	v_mfma_f32_16x16x32_bf16 v[96:99], v[168:171], v[88:91], v[80:83]
	v_mfma_f32_16x16x32_bf16 v[92:95], v[194:197], v[164:167], v[76:79]
	v_mfma_f32_16x16x32_bf16 v[88:91], v[190:193], v[164:167], v[72:75]
	v_mfma_f32_16x16x32_bf16 v[84:87], v[186:189], v[164:167], v[68:71]
	v_mfma_f32_16x16x32_bf16 v[80:83], v[168:171], v[164:167], v[64:67]
	v_mfma_f32_16x16x32_bf16 v[76:79], v[194:197], v[160:163], v[60:63]
	v_mfma_f32_16x16x32_bf16 v[72:75], v[190:193], v[160:163], v[56:59]
	v_mfma_f32_16x16x32_bf16 v[68:71], v[186:189], v[160:163], v[52:55]
	v_mfma_f32_16x16x32_bf16 v[64:67], v[168:171], v[160:163], v[48:51]
	s_setprio 0
	s_nop 1
	ds_read_b128 v[48:51], v139 offset:4096
	ds_read_b128 v[112:115], v139 offset:5120
	ds_read_b128 v[120:123], v139 offset:6144
	ds_read_b128 v[124:127], v139 offset:7168
	s_setprio 1
	s_waitcnt lgkmcnt(3)
	v_mfma_f32_16x16x32_bf16 v[60:63], v[194:197], v[48:51], v[44:47]
	v_mfma_f32_16x16x32_bf16 v[56:59], v[190:193], v[48:51], v[40:43]
	v_mfma_f32_16x16x32_bf16 v[52:55], v[186:189], v[48:51], v[36:39]
	v_mfma_f32_16x16x32_bf16 v[48:51], v[168:171], v[48:51], v[32:35]
	s_waitcnt lgkmcnt(2)
	v_mfma_f32_16x16x32_bf16 v[44:47], v[194:197], v[112:115], v[28:31]
	v_mfma_f32_16x16x32_bf16 v[40:43], v[190:193], v[112:115], v[24:27]
	v_mfma_f32_16x16x32_bf16 v[36:39], v[186:189], v[112:115], v[20:23]
	v_mfma_f32_16x16x32_bf16 v[32:35], v[168:171], v[112:115], v[16:19]
	s_waitcnt lgkmcnt(1)
	v_mfma_f32_16x16x32_bf16 v[28:31], v[194:197], v[120:123], v[12:15]
	v_mfma_f32_16x16x32_bf16 v[24:27], v[190:193], v[120:123], v[8:11]
	v_mfma_f32_16x16x32_bf16 v[20:23], v[186:189], v[120:123], v[4:7]
	v_mfma_f32_16x16x32_bf16 v[16:19], v[168:171], v[120:123], v[0:3]
	s_waitcnt lgkmcnt(0)
	v_mfma_f32_16x16x32_bf16 v[12:15], v[194:197], v[124:127], v[152:155]
	v_mfma_f32_16x16x32_bf16 v[8:11], v[190:193], v[124:127], v[140:143]
	v_mfma_f32_16x16x32_bf16 v[4:7], v[186:189], v[124:127], v[156:159]
	v_mfma_f32_16x16x32_bf16 v[0:3], v[168:171], v[124:127], v[104:107]
	s_setprio 0
	s_add_i32 s30, s26, 1
	s_cmp_lg_u32 s26, 2
	s_cselect_b32 s72, s30, 0
	s_and_b64 vcc, exec, s[0:1]
	s_cbranch_vccz .LBB0_824
; DEVI int opaque_tid() { int t = (int)threadIdx.x; asm volatile("" : "+v"(t)); return t; }
; DEVI void g2_issue(const G2Tile& t, int kt, int st, char* smem) {
;     const int tid = opaque_tid(), lane = tid & 63, w = tid >> 6;
;     const int rr = lane >> 2, sch = (lane & 3) ^ ((lane >> 5) << 1);
;     const bf16_t* ap = t.A + (size_t)kt * 32 + (size_t)(w * 16 + rr) * t.lda + sch * 8;
;     const bf16_t* bp = t.Bt + (size_t)kt * 32 + (size_t)(w * 16 + rr) * t.ldb + sch * 8;
;     char* sa = smem + st * 24576 + w * 1024 + lane * 16;
; #pragma unroll
;     for (int i = 0; i < 4; ++i) __builtin_amdgcn_global_load_lds((const unsigned*)(ap + (size_t)(64 * i) * t.lda), (unsigned*)(sa + i * 4096), 16, 0, 0);
; #pragma unroll
;     for (int i = 0; i < 2; ++i) __builtin_amdgcn_global_load_lds((const unsigned*)(bp + (size_t)(64 * i) * t.ldb), (unsigned*)(sa + 16384 + i * 4096), 16, 0, 0);
; }
; DEVI void g2_prologue(const G2Tile& t, int st, char* smem) {
;     g2_issue(t, 0, st, smem);
;     g2_issue(t, 1, st == 2 ? 0 : st + 1, smem);
	v_mov_b32_e32 v104, v172
	s_mul_i32 s0, s72, 0x6000
	v_and_b32_e32 v112, 63, v104
	v_ashrrev_i32_e32 v113, 6, v104
	v_bfe_u32 v105, v104, 2, 4
	v_and_b32_e32 v106, 3, v104
	v_lshrrev_b32_e32 v104, 4, v104
	v_bitop3_b32 v114, v104, v106, 2 bitop3:0x6c
	v_lshl_or_b32 v104, v113, 4, v105
	v_ashrrev_i32_e32 v105, 31, v104
	s_add_i32 s1, s0, 0
	v_lshlrev_b32_e32 v113, 10, v113
	v_lshlrev_b32_e32 v112, 4, v112
	v_lshlrev_b64 v[104:105], 11, v[104:105]
	v_lshlrev_b32_e32 v184, 4, v114
	v_add3_u32 v114, s1, v113, v112
	v_lshl_add_u64 v[106:107], s[20:21], 0, v[104:105]
	v_readfirstlane_b32 s1, v114
	v_add_u32_e32 v115, 0x1000, v114
	v_lshl_add_u64 v[106:107], v[106:107], 0, v[184:185]
	s_mov_b32 m0, s1
	v_readfirstlane_b32 s1, v115
	v_add_u32_e32 v115, 0x2000, v114
	global_load_lds_dwordx4 v[106:107], off
	v_lshl_add_u64 v[112:113], v[106:107], 0, s[6:7]
	s_mov_b32 m0, s1
	v_readfirstlane_b32 s1, v115
	global_load_lds_dwordx4 v[112:113], off
	v_lshl_add_u64 v[112:113], v[106:107], 0, s[8:9]
	s_mov_b32 m0, s1
	v_lshl_add_u64 v[106:107], v[106:107], 0, s[10:11]
	global_load_lds_dwordx4 v[112:113], off
	v_add_u32_e32 v112, 0x3000, v114
	v_lshl_add_u64 v[104:105], s[22:23], 0, v[104:105]
	v_readfirstlane_b32 s1, v112
	s_mov_b32 m0, s1
	v_lshl_add_u64 v[104:105], v[104:105], 0, v[184:185]
	global_load_lds_dwordx4 v[106:107], off
	v_add_u32_e32 v106, 0x4000, v114
	s_addk_i32 s0, 0x6000
	v_readfirstlane_b32 s1, v106
	v_add_u32_e32 v106, 0x5000, v114
	s_mov_b32 m0, s1
	v_readfirstlane_b32 s1, v106
	global_load_lds_dwordx4 v[104:105], off
	v_lshl_add_u64 v[104:105], v[104:105], 0, s[6:7]
	s_mov_b32 m0, s1
	s_cmp_lg_u32 s72, 2
	global_load_lds_dwordx4 v[104:105], off
	v_mov_b32_e32 v104, v172
	s_cselect_b32 s0, s0, 0
	v_and_b32_e32 v114, 63, v104
	v_ashrrev_i32_e32 v115, 6, v104
	v_bfe_u32 v105, v104, 2, 4
	v_and_b32_e32 v106, 3, v104
	v_lshrrev_b32_e32 v104, 4, v104
	v_bitop3_b32 v112, v104, v106, 2 bitop3:0x6c
	v_lshl_or_b32 v104, v115, 4, v105
	v_ashrrev_i32_e32 v105, 31, v104
	v_lshlrev_b64 v[104:105], 11, v[104:105]
	s_add_i32 s0, s0, 0
	v_lshlrev_b32_e32 v115, 10, v115
	v_lshlrev_b32_e32 v114, 4, v114
	v_lshl_add_u64 v[106:107], s[20:21], 0, v[104:105]
	v_lshlrev_b32_e32 v184, 4, v112
	v_add3_u32 v114, s0, v115, v114
	v_lshl_add_u64 v[106:107], v[106:107], 0, v[184:185]
	v_readfirstlane_b32 s0, v114
	v_add_u32_e32 v115, 0x1000, v114
	v_lshl_add_u64 v[112:113], v[106:107], 0, 64
	s_mov_b32 m0, s0
	v_readfirstlane_b32 s0, v115
	v_add_u32_e32 v115, 0x2000, v114
	global_load_lds_dwordx4 v[112:113], off
	v_lshl_add_u64 v[112:113], v[106:107], 0, s[12:13]
	s_mov_b32 m0, s0
	v_readfirstlane_b32 s0, v115
	global_load_lds_dwordx4 v[112:113], off
	v_lshl_add_u64 v[112:113], v[106:107], 0, s[14:15]
	s_mov_b32 m0, s0
	v_lshl_add_u64 v[104:105], s[22:23], 0, v[104:105]
	global_load_lds_dwordx4 v[112:113], off
	v_add_u32_e32 v112, 0x3000, v114
	v_lshl_add_u64 v[106:107], v[106:107], 0, s[16:17]
	v_readfirstlane_b32 s0, v112
	v_add_u32_e32 v112, 0x4000, v114
	s_mov_b32 m0, s0
	v_lshl_add_u64 v[104:105], v[104:105], 0, v[184:185]
	v_readfirstlane_b32 s0, v112
	global_load_lds_dwordx4 v[106:107], off
	v_lshl_add_u64 v[106:107], v[104:105], 0, 64
	s_mov_b32 m0, s0
	v_lshl_add_u64 v[104:105], v[104:105], 0, s[12:13]
	global_load_lds_dwordx4 v[106:107], off
	v_add_u32_e32 v106, 0x5000, v114
	s_nop 0
	v_readfirstlane_b32 s0, v106
	s_mov_b32 m0, s0
	s_nop 0
	global_load_lds_dwordx4 v[104:105], off

; DEVI int opaque_tid() { int t = (int)threadIdx.x; asm volatile("" : "+v"(t)); return t; }
; DEVI void g2_issue(const G2Tile& t, int kt, int st, char* smem) {
;     const int tid = opaque_tid(), lane = tid & 63, w = tid >> 6;
;     const int rr = lane >> 2, sch = (lane & 3) ^ ((lane >> 5) << 1);
;     const bf16_t* ap = t.A + (size_t)kt * 32 + (size_t)(w * 16 + rr) * t.lda + sch * 8;
;     const bf16_t* bp = t.Bt + (size_t)kt * 32 + (size_t)(w * 16 + rr) * t.ldb + sch * 8;
;     char* sa = smem + st * 24576 + w * 1024 + lane * 16;
; #pragma unroll
;     for (int i = 0; i < 4; ++i) __builtin_amdgcn_global_load_lds((const unsigned*)(ap + (size_t)(64 * i) * t.lda), (unsigned*)(sa + i * 4096), 16, 0, 0);
; #pragma unroll
;     for (int i = 0; i < 2; ++i) __builtin_amdgcn_global_load_lds((const unsigned*)(bp + (size_t)(64 * i) * t.ldb), (unsigned*)(sa + 16384 + i * 4096), 16, 0, 0);
; template <bool TRANS, class Epi>
; DEVI int g2_body(const G2Tile& t, int st, char* smem, bool has_next, const G2Tile& nxt, const Epi& epi) {
;     ...
;     for (int kt = 0; kt < nk; ++kt) {
;         if (kt + 1 < nk) asm volatile("s_waitcnt vmcnt(6)" ::: "memory");
;         else asm volatile("s_waitcnt vmcnt(0)" ::: "memory");
;         __syncthreads();
;         if (kt + 2 < nk) g2_issue(t, kt + 2, st >= 1 ? st - 1 : 2, smem);
;         const char* sa = smem + st * 24576 + frag;
;         bf16x8 bfr[4];
; #pragma unroll
;         for (int n = 0; n < 4; ++n) bfr[n] = *(const bf16x8*)(sa + (16 + wc * 4 + n) * 1024);
; #pragma unroll
;         for (int mh = 0; mh < 2; ++mh) {
;             bf16x8 af[4];
; #pragma unroll
;             for (int m = 0; m < 4; ++m) af[m] = *(const bf16x8*)(sa + (wr * 8 + mh * 4 + m) * 1024);
;             __builtin_amdgcn_s_setprio(1);
; #pragma unroll
;             for (int m = 0; m < 4; ++m)
; #pragma unroll
;                 for (int n = 0; n < 4; ++n)
;                     acc[mh * 4 + m][n] = TRANS ? __builtin_amdgcn_mfma_f32_16x16x32_bf16(bfr[n], af[m], acc[mh * 4 + m][n], 0, 0, 0)
;                                                : __builtin_amdgcn_mfma_f32_16x16x32_bf16(af[m], bfr[n], acc[mh * 4 + m][n], 0, 0, 0);
;             __builtin_amdgcn_s_setprio(0);
;         }
;         st = st == 2 ? 0 : st + 1;
;     }
.LBB0_1503:
	v_mov_b32_e32 v136, v172
	s_waitcnt vmcnt(6)
	s_waitcnt lgkmcnt(0)
	s_barrier
	s_mul_i32 s26, s43, 0x6000
	v_and_b32_e32 v142, 63, v136
	v_ashrrev_i32_e32 v143, 6, v136
	v_bfe_u32 v137, v136, 2, 4
	v_and_b32_e32 v138, 3, v136
	v_lshrrev_b32_e32 v136, 4, v136
	s_add_i32 s33, s26, 0xffffa000
	v_bitop3_b32 v138, v136, v138, 2 bitop3:0x6c
	v_lshl_or_b32 v136, v143, 4, v137
	s_cmp_gt_i32 s43, 0
	v_ashrrev_i32_e32 v137, 31, v136
	v_lshlrev_b64 v[136:137], 11, v[136:137]
	s_cselect_b32 s33, s33, 0xc000
	v_lshl_or_b32 v136, v138, 4, v136
	s_add_i32 s33, s33, 0
	v_lshlrev_b32_e32 v143, 10, v143
	v_lshlrev_b32_e32 v142, 4, v142
	v_lshl_add_u64 v[136:137], s[36:37], 0, v[136:137]
	v_add3_u32 v142, s33, v143, v142
	v_lshl_add_u64 v[138:139], s[28:29], 0, v[136:137]
	v_readfirstlane_b32 s33, v142
	v_add_u32_e32 v143, 0x1000, v142
	v_lshl_add_u64 v[140:141], v[138:139], 0, s[12:13]
	s_mov_b32 m0, s33
	v_readfirstlane_b32 s33, v143
	v_add_u32_e32 v143, 0x2000, v142
	global_load_lds_dwordx4 v[140:141], off
	v_lshl_add_u64 v[140:141], v[138:139], 0, s[14:15]
	s_mov_b32 m0, s33
	v_readfirstlane_b32 s33, v143
	global_load_lds_dwordx4 v[140:141], off
	v_lshl_add_u64 v[140:141], v[138:139], 0, s[16:17]
	s_mov_b32 m0, s33
	v_lshl_add_u64 v[138:139], v[138:139], 0, s[18:19]
	global_load_lds_dwordx4 v[140:141], off
	v_add_u32_e32 v140, 0x3000, v142
	v_lshl_add_u64 v[136:137], s[30:31], 0, v[136:137]
	v_readfirstlane_b32 s33, v140
	v_add_u32_e32 v140, 0x4000, v142
	s_mov_b32 m0, s33
	v_readfirstlane_b32 s33, v140
	global_load_lds_dwordx4 v[138:139], off
	v_lshl_add_u64 v[138:139], v[136:137], 0, s[12:13]
	s_mov_b32 m0, s33
	v_lshl_add_u64 v[136:137], v[136:137], 0, s[14:15]
	global_load_lds_dwordx4 v[138:139], off
	v_add_u32_e32 v138, 0x5000, v142
	v_add_u32_e32 v152, s26, v132
	v_readfirstlane_b32 s33, v138
	s_mov_b32 m0, s33
	v_add_u32_e32 v148, v152, v128
	global_load_lds_dwordx4 v[136:137], off
	v_add_u32_e32 v168, v152, v133
	ds_read_b128 v[136:139], v148 offset:16384
	ds_read_b128 v[140:143], v148 offset:17408
	ds_read_b128 v[144:147], v148 offset:18432
	ds_read_b128 v[148:151], v148 offset:19456
	ds_read_b128 v[152:155], v168
	ds_read_b128 v[156:159], v168 offset:1024
	ds_read_b128 v[160:163], v168 offset:2048
	ds_read_b128 v[164:167], v168 offset:3072
	s_setprio 1
	s_waitcnt lgkmcnt(0)
	v_mfma_f32_16x16x32_bf16 v[124:127], v[136:139], v[152:155], v[124:127]
	v_mfma_f32_16x16x32_bf16 v[120:123], v[140:143], v[152:155], v[120:123]
	v_mfma_f32_16x16x32_bf16 v[116:119], v[144:147], v[152:155], v[116:119]
	v_mfma_f32_16x16x32_bf16 v[112:115], v[148:151], v[152:155], v[112:115]
	v_mfma_f32_16x16x32_bf16 v[108:111], v[136:139], v[156:159], v[108:111]
	v_mfma_f32_16x16x32_bf16 v[96:99], v[140:143], v[156:159], v[96:99]
	v_mfma_f32_16x16x32_bf16 v[84:87], v[144:147], v[156:159], v[84:87]
	v_mfma_f32_16x16x32_bf16 v[80:83], v[148:151], v[156:159], v[80:83]
	v_mfma_f32_16x16x32_bf16 v[76:79], v[136:139], v[160:163], v[76:79]
	v_mfma_f32_16x16x32_bf16 v[72:75], v[140:143], v[160:163], v[72:75]
	v_mfma_f32_16x16x32_bf16 v[68:71], v[144:147], v[160:163], v[68:71]
	v_mfma_f32_16x16x32_bf16 v[64:67], v[148:151], v[160:163], v[64:67]
	v_mfma_f32_16x16x32_bf16 v[60:63], v[136:139], v[164:167], v[60:63]
	v_mfma_f32_16x16x32_bf16 v[56:59], v[140:143], v[164:167], v[56:59]
	v_mfma_f32_16x16x32_bf16 v[52:55], v[144:147], v[164:167], v[52:55]
	v_mfma_f32_16x16x32_bf16 v[48:51], v[148:151], v[164:167], v[48:51]
	s_setprio 0
	ds_read_b128 v[152:155], v168 offset:4096
	ds_read_b128 v[156:159], v168 offset:5120
	ds_read_b128 v[160:163], v168 offset:6144
	ds_read_b128 v[164:167], v168 offset:7168
	s_setprio 1
	s_waitcnt lgkmcnt(0)
	v_mfma_f32_16x16x32_bf16 v[44:47], v[136:139], v[152:155], v[44:47]
	v_mfma_f32_16x16x32_bf16 v[40:43], v[140:143], v[152:155], v[40:43]
	v_mfma_f32_16x16x32_bf16 v[36:39], v[144:147], v[152:155], v[36:39]
	v_mfma_f32_16x16x32_bf16 v[32:35], v[148:151], v[152:155], v[32:35]
	v_mfma_f32_16x16x32_bf16 v[28:31], v[136:139], v[156:159], v[28:31]
	v_mfma_f32_16x16x32_bf16 v[24:27], v[140:143], v[156:159], v[24:27]
	v_mfma_f32_16x16x32_bf16 v[20:23], v[144:147], v[156:159], v[20:23]
	v_mfma_f32_16x16x32_bf16 v[16:19], v[148:151], v[156:159], v[16:19]
	v_mfma_f32_16x16x32_bf16 v[12:15], v[136:139], v[160:163], v[12:15]
	v_mfma_f32_16x16x32_bf16 v[8:11], v[140:143], v[160:163], v[8:11]
	v_mfma_f32_16x16x32_bf16 v[4:7], v[144:147], v[160:163], v[4:7]
	v_mfma_f32_16x16x32_bf16 v[0:3], v[148:151], v[160:163], v[0:3]
	v_mfma_f32_16x16x32_bf16 v[88:91], v[136:139], v[164:167], v[88:91]
	v_mfma_f32_16x16x32_bf16 v[92:95], v[140:143], v[164:167], v[92:95]
	v_mfma_f32_16x16x32_bf16 v[100:103], v[144:147], v[164:167], v[100:103]
	v_mfma_f32_16x16x32_bf16 v[104:107], v[148:151], v[164:167], v[104:107]
	s_setprio 0
	s_add_i32 s26, s43, 1
	s_cmp_lg_u32 s43, 2
	s_cselect_b32 s43, s26, 0
	s_add_u32 s36, s36, 64
	s_addc_u32 s37, s37, 0
	s_cmpk_eq_i32 s36, 0x780
	s_cbranch_scc0 .LBB0_1503
	s_mul_i32 s26, s43, 0x6000
	v_add_u32_e32 v152, s26, v132
	v_add_u32_e32 v148, v152, v128
	v_add_u32_e32 v168, v152, v133
	s_waitcnt vmcnt(6)
	s_barrier
; template <bool TRANS, class Epi>
; DEVI int g2_body(const G2Tile& t, int st, char* smem, bool has_next, const G2Tile& nxt, const Epi& epi) {
;     ...
;     for (int kt = 0; kt < nk; ++kt) {
;         if (kt + 1 < nk) asm volatile("s_waitcnt vmcnt(6)" ::: "memory");
;         else asm volatile("s_waitcnt vmcnt(0)" ::: "memory");
;         __syncthreads();
;         if (kt + 2 < nk) g2_issue(t, kt + 2, st >= 1 ? st - 1 : 2, smem);
;         const char* sa = smem + st * 24576 + frag;
;         bf16x8 bfr[4];
; #pragma unroll
;         for (int n = 0; n < 4; ++n) bfr[n] = *(const bf16x8*)(sa + (16 + wc * 4 + n) * 1024);
; #pragma unroll
;         for (int mh = 0; mh < 2; ++mh) {
;             bf16x8 af[4];
; #pragma unroll
;             for (int m = 0; m < 4; ++m) af[m] = *(const bf16x8*)(sa + (wr * 8 + mh * 4 + m) * 1024);
;             __builtin_amdgcn_s_setprio(1);
; #pragma unroll
;             for (int m = 0; m < 4; ++m)
; #pragma unroll
;                 for (int n = 0; n < 4; ++n)
;                     acc[mh * 4 + m][n] = TRANS ? __builtin_amdgcn_mfma_f32_16x16x32_bf16(bfr[n], af[m], acc[mh * 4 + m][n], 0, 0, 0)
;                                                : __builtin_amdgcn_mfma_f32_16x16x32_bf16(af[m], bfr[n], acc[mh * 4 + m][n], 0, 0, 0);
;             __builtin_amdgcn_s_setprio(0);
;         }
;         st = st == 2 ? 0 : st + 1;
	ds_read_b128 v[136:139], v148 offset:16384
	ds_read_b128 v[140:143], v148 offset:17408
	ds_read_b128 v[144:147], v148 offset:18432
	ds_read_b128 v[148:151], v148 offset:19456
	ds_read_b128 v[152:155], v168
	ds_read_b128 v[156:159], v168 offset:1024
	ds_read_b128 v[160:163], v168 offset:2048
	ds_read_b128 v[164:167], v168 offset:3072
	s_setprio 1
	s_waitcnt lgkmcnt(3)
	v_mfma_f32_16x16x32_bf16 v[124:127], v[136:139], v[152:155], v[124:127]
	v_mfma_f32_16x16x32_bf16 v[120:123], v[140:143], v[152:155], v[120:123]
	v_mfma_f32_16x16x32_bf16 v[116:119], v[144:147], v[152:155], v[116:119]
	v_mfma_f32_16x16x32_bf16 v[112:115], v[148:151], v[152:155], v[112:115]
	s_waitcnt lgkmcnt(2)
	v_mfma_f32_16x16x32_bf16 v[108:111], v[136:139], v[156:159], v[108:111]
	v_mfma_f32_16x16x32_bf16 v[96:99], v[140:143], v[156:159], v[96:99]
	v_mfma_f32_16x16x32_bf16 v[84:87], v[144:147], v[156:159], v[84:87]
	v_mfma_f32_16x16x32_bf16 v[80:83], v[148:151], v[156:159], v[80:83]
	s_waitcnt lgkmcnt(1)
	v_mfma_f32_16x16x32_bf16 v[76:79], v[136:139], v[160:163], v[76:79]
	v_mfma_f32_16x16x32_bf16 v[72:75], v[140:143], v[160:163], v[72:75]
	v_mfma_f32_16x16x32_bf16 v[68:71], v[144:147], v[160:163], v[68:71]
	v_mfma_f32_16x16x32_bf16 v[64:67], v[148:151], v[160:163], v[64:67]
	s_waitcnt lgkmcnt(0)
	v_mfma_f32_16x16x32_bf16 v[60:63], v[136:139], v[164:167], v[60:63]
	v_mfma_f32_16x16x32_bf16 v[56:59], v[140:143], v[164:167], v[56:59]
	v_mfma_f32_16x16x32_bf16 v[52:55], v[144:147], v[164:167], v[52:55]
	v_mfma_f32_16x16x32_bf16 v[48:51], v[148:151], v[164:167], v[48:51]
	s_setprio 0
	ds_read_b128 v[152:155], v168 offset:4096
	ds_read_b128 v[156:159], v168 offset:5120
	ds_read_b128 v[160:163], v168 offset:6144
	ds_read_b128 v[164:167], v168 offset:7168
	s_setprio 1
	s_waitcnt lgkmcnt(3)
	v_mfma_f32_16x16x32_bf16 v[44:47], v[136:139], v[152:155], v[44:47]
	v_mfma_f32_16x16x32_bf16 v[40:43], v[140:143], v[152:155], v[40:43]
	v_mfma_f32_16x16x32_bf16 v[36:39], v[144:147], v[152:155], v[36:39]
	v_mfma_f32_16x16x32_bf16 v[32:35], v[148:151], v[152:155], v[32:35]
	s_waitcnt lgkmcnt(2)
	v_mfma_f32_16x16x32_bf16 v[28:31], v[136:139], v[156:159], v[28:31]
	v_mfma_f32_16x16x32_bf16 v[24:27], v[140:143], v[156:159], v[24:27]
	v_mfma_f32_16x16x32_bf16 v[20:23], v[144:147], v[156:159], v[20:23]
	v_mfma_f32_16x16x32_bf16 v[16:19], v[148:151], v[156:159], v[16:19]
	s_waitcnt lgkmcnt(1)
	v_mfma_f32_16x16x32_bf16 v[12:15], v[136:139], v[160:163], v[12:15]
	v_mfma_f32_16x16x32_bf16 v[8:11], v[140:143], v[160:163], v[8:11]
	v_mfma_f32_16x16x32_bf16 v[4:7], v[144:147], v[160:163], v[4:7]
	v_mfma_f32_16x16x32_bf16 v[0:3], v[148:151], v[160:163], v[0:3]
	s_waitcnt lgkmcnt(0)
	v_mfma_f32_16x16x32_bf16 v[136:139], v[136:139], v[164:167], v[88:91]
	v_mfma_f32_16x16x32_bf16 v[140:143], v[140:143], v[164:167], v[92:95]
	v_mfma_f32_16x16x32_bf16 v[144:147], v[144:147], v[164:167], v[100:103]
	v_mfma_f32_16x16x32_bf16 v[148:151], v[148:151], v[164:167], v[104:107]
	s_setprio 0
	s_add_i32 s26, s43, 1
	s_cmp_lg_u32 s43, 2
	s_cselect_b32 s26, s26, 0
	s_mul_i32 s28, s26, 0x6000
	v_add_u32_e32 v100, s28, v132
	v_add_u32_e32 v132, v100, v133
	v_add_u32_e32 v100, v100, v128
	s_waitcnt vmcnt(0)
	s_barrier
	ds_read_b128 v[152:155], v132 offset:3072
	ds_read_b128 v[156:159], v132 offset:2048
	ds_read_b128 v[88:91], v132 offset:1024
	ds_read_b128 v[92:95], v132
	ds_read_b128 v[160:163], v100 offset:19456
	ds_read_b128 v[164:167], v100 offset:18432
	ds_read_b128 v[168:171], v100 offset:17408
	ds_read_b128 v[182:185], v100 offset:16384
	s_setprio 1
	s_waitcnt lgkmcnt(0)
	v_mfma_f32_16x16x32_bf16 v[124:127], v[182:185], v[92:95], v[124:127]
	v_mfma_f32_16x16x32_bf16 v[120:123], v[168:171], v[92:95], v[120:123]
	v_mfma_f32_16x16x32_bf16 v[116:119], v[164:167], v[92:95], v[116:119]
	v_mfma_f32_16x16x32_bf16 v[112:115], v[160:163], v[92:95], v[112:115]
	v_mfma_f32_16x16x32_bf16 v[108:111], v[182:185], v[88:91], v[108:111]
	v_mfma_f32_16x16x32_bf16 v[104:107], v[168:171], v[88:91], v[96:99]
	v_mfma_f32_16x16x32_bf16 v[100:103], v[164:167], v[88:91], v[84:87]
	v_mfma_f32_16x16x32_bf16 v[96:99], v[160:163], v[88:91], v[80:83]
	v_mfma_f32_16x16x32_bf16 v[92:95], v[182:185], v[156:159], v[76:79]
	v_mfma_f32_16x16x32_bf16 v[88:91], v[168:171], v[156:159], v[72:75]
	v_mfma_f32_16x16x32_bf16 v[84:87], v[164:167], v[156:159], v[68:71]
	v_mfma_f32_16x16x32_bf16 v[80:83], v[160:163], v[156:159], v[64:67]
	v_mfma_f32_16x16x32_bf16 v[76:79], v[182:185], v[152:155], v[60:63]
	v_mfma_f32_16x16x32_bf16 v[72:75], v[168:171], v[152:155], v[56:59]
	v_mfma_f32_16x16x32_bf16 v[68:71], v[164:167], v[152:155], v[52:55]
	v_mfma_f32_16x16x32_bf16 v[64:67], v[160:163], v[152:155], v[48:51]
	s_setprio 0
	s_nop 1
	ds_read_b128 v[48:51], v132 offset:4096
	ds_read_b128 v[152:155], v132 offset:5120
	ds_read_b128 v[156:159], v132 offset:6144
	ds_read_b128 v[186:189], v132 offset:7168
	s_setprio 1
	s_waitcnt lgkmcnt(3)
	v_mfma_f32_16x16x32_bf16 v[60:63], v[182:185], v[48:51], v[44:47]
	v_mfma_f32_16x16x32_bf16 v[56:59], v[168:171], v[48:51], v[40:43]
	v_mfma_f32_16x16x32_bf16 v[52:55], v[164:167], v[48:51], v[36:39]
	v_mfma_f32_16x16x32_bf16 v[48:51], v[160:163], v[48:51], v[32:35]
	s_waitcnt lgkmcnt(2)
	v_mfma_f32_16x16x32_bf16 v[44:47], v[182:185], v[152:155], v[28:31]
	v_mfma_f32_16x16x32_bf16 v[40:43], v[168:171], v[152:155], v[24:27]
	v_mfma_f32_16x16x32_bf16 v[36:39], v[164:167], v[152:155], v[20:23]
	v_mfma_f32_16x16x32_bf16 v[32:35], v[160:163], v[152:155], v[16:19]
	s_waitcnt lgkmcnt(1)
	v_mfma_f32_16x16x32_bf16 v[28:31], v[182:185], v[156:159], v[12:15]
	v_mfma_f32_16x16x32_bf16 v[24:27], v[168:171], v[156:159], v[8:11]
	v_mfma_f32_16x16x32_bf16 v[20:23], v[164:167], v[156:159], v[4:7]
	v_mfma_f32_16x16x32_bf16 v[16:19], v[160:163], v[156:159], v[0:3]
	s_waitcnt lgkmcnt(0)
	v_mfma_f32_16x16x32_bf16 v[12:15], v[182:185], v[186:189], v[136:139]
	v_mfma_f32_16x16x32_bf16 v[8:11], v[168:171], v[186:189], v[140:143]
	v_mfma_f32_16x16x32_bf16 v[4:7], v[164:167], v[186:189], v[144:147]
	v_mfma_f32_16x16x32_bf16 v[0:3], v[160:163], v[186:189], v[148:151]
	s_setprio 0
	s_add_i32 s28, s26, 1
	s_cmp_lg_u32 s26, 2
	s_cselect_b32 s43, s28, 0
	s_and_b64 vcc, exec, s[34:35]
	s_cbranch_vccz .LBB0_1499
; DEVI int opaque_tid() { int t = (int)threadIdx.x; asm volatile("" : "+v"(t)); return t; }
; DEVI void g2_issue(const G2Tile& t, int kt, int st, char* smem) {
;     const int tid = opaque_tid(), lane = tid & 63, w = tid >> 6;
;     const int rr = lane >> 2, sch = (lane & 3) ^ ((lane >> 5) << 1);
;     const bf16_t* ap = t.A + (size_t)kt * 32 + (size_t)(w * 16 + rr) * t.lda + sch * 8;
;     const bf16_t* bp = t.Bt + (size_t)kt * 32 + (size_t)(w * 16 + rr) * t.ldb + sch * 8;
;     char* sa = smem + st * 24576 + w * 1024 + lane * 16;
; #pragma unroll
;     for (int i = 0; i < 4; ++i) __builtin_amdgcn_global_load_lds((const unsigned*)(ap + (size_t)(64 * i) * t.lda), (unsigned*)(sa + i * 4096), 16, 0, 0);
; #pragma unroll
;     for (int i = 0; i < 2; ++i) __builtin_amdgcn_global_load_lds((const unsigned*)(bp + (size_t)(64 * i) * t.ldb), (unsigned*)(sa + 16384 + i * 4096), 16, 0, 0);
; }
; DEVI void g2_prologue(const G2Tile& t, int st, char* smem) {
;     g2_issue(t, 0, st, smem);
;     g2_issue(t, 1, st == 2 ? 0 : st + 1, smem);
	v_mov_b32_e32 v128, v172
	s_mul_i32 s26, s43, 0x6000
	v_ashrrev_i32_e32 v139, 6, v128
	v_bfe_u32 v132, v128, 2, 4
	v_and_b32_e32 v138, 63, v128
	v_and_b32_e32 v133, 3, v128
	v_lshrrev_b32_e32 v128, 4, v128
	v_lshl_or_b32 v132, v139, 4, v132
	v_bitop3_b32 v128, v128, v133, 2 bitop3:0x6c
	v_ashrrev_i32_e32 v133, 31, v132
	s_add_i32 s28, s26, 0
	v_lshlrev_b32_e32 v139, 10, v139
	v_lshlrev_b32_e32 v138, 4, v138
	v_lshlrev_b64 v[132:133], 11, v[132:133]
	v_add3_u32 v140, s28, v139, v138
	v_lshl_add_u64 v[136:137], s[20:21], 0, v[132:133]
	v_lshlrev_b32_e32 v128, 4, v128
	v_readfirstlane_b32 s28, v140
	v_add_u32_e32 v141, 0x1000, v140
	v_lshl_add_u64 v[136:137], v[136:137], 0, v[128:129]
	s_mov_b32 m0, s28
	v_readfirstlane_b32 s28, v141
	v_add_u32_e32 v141, 0x2000, v140
	global_load_lds_dwordx4 v[136:137], off
	v_lshl_add_u64 v[138:139], v[136:137], 0, s[0:1]
	s_mov_b32 m0, s28
	v_readfirstlane_b32 s28, v141
	global_load_lds_dwordx4 v[138:139], off
	v_lshl_add_u64 v[138:139], v[136:137], 0, s[2:3]
	s_mov_b32 m0, s28
	v_lshl_add_u64 v[132:133], s[22:23], 0, v[132:133]
	global_load_lds_dwordx4 v[138:139], off
	v_add_u32_e32 v138, 0x3000, v140
	v_lshl_add_u64 v[132:133], v[132:133], 0, v[128:129]
	v_readfirstlane_b32 s28, v138
	v_add_u32_e32 v128, 0x4000, v140
	v_lshl_add_u64 v[136:137], v[136:137], 0, s[4:5]
	s_mov_b32 m0, s28
	v_readfirstlane_b32 s28, v128
	v_add_u32_e32 v128, 0x5000, v140
	global_load_lds_dwordx4 v[136:137], off
	s_mov_b32 m0, s28
	v_readfirstlane_b32 s28, v128
	global_load_lds_dwordx4 v[132:133], off
	v_lshl_add_u64 v[132:133], v[132:133], 0, s[0:1]
	s_mov_b32 m0, s28
	v_mov_b32_e32 v128, v172
	global_load_lds_dwordx4 v[132:133], off
	s_addk_i32 s26, 0x6000
	v_ashrrev_i32_e32 v141, 6, v128
	v_bfe_u32 v132, v128, 2, 4
	v_and_b32_e32 v140, 63, v128
	v_and_b32_e32 v133, 3, v128
	v_lshrrev_b32_e32 v128, 4, v128
	v_lshl_or_b32 v132, v141, 4, v132
	s_cmp_lg_u32 s43, 2
	v_bitop3_b32 v128, v128, v133, 2 bitop3:0x6c
	v_ashrrev_i32_e32 v133, 31, v132
	s_cselect_b32 s26, s26, 0
	v_lshlrev_b64 v[132:133], 11, v[132:133]
	s_add_i32 s26, s26, 0
	v_lshlrev_b32_e32 v141, 10, v141
	v_lshlrev_b32_e32 v140, 4, v140
	v_lshl_add_u64 v[136:137], s[20:21], 0, v[132:133]
	v_lshlrev_b32_e32 v128, 4, v128
	v_add3_u32 v140, s26, v141, v140
	v_lshl_add_u64 v[136:137], v[136:137], 0, v[128:129]
	v_readfirstlane_b32 s26, v140
	v_add_u32_e32 v141, 0x1000, v140
	v_lshl_add_u64 v[138:139], v[136:137], 0, 64
	s_mov_b32 m0, s26
	v_readfirstlane_b32 s26, v141
	v_add_u32_e32 v141, 0x2000, v140
	global_load_lds_dwordx4 v[138:139], off
	v_lshl_add_u64 v[138:139], v[136:137], 0, s[6:7]
	s_mov_b32 m0, s26
	v_readfirstlane_b32 s26, v141
	global_load_lds_dwordx4 v[138:139], off
	v_lshl_add_u64 v[138:139], v[136:137], 0, s[8:9]
	s_mov_b32 m0, s26
	v_lshl_add_u64 v[132:133], s[22:23], 0, v[132:133]
	global_load_lds_dwordx4 v[138:139], off
	v_add_u32_e32 v138, 0x3000, v140
	v_lshl_add_u64 v[132:133], v[132:133], 0, v[128:129]
	v_readfirstlane_b32 s26, v138
	v_add_u32_e32 v128, 0x4000, v140
	v_lshl_add_u64 v[136:137], v[136:137], 0, s[10:11]
	s_mov_b32 m0, s26
	v_readfirstlane_b32 s26, v128
	v_add_u32_e32 v128, 0x5000, v140
	global_load_lds_dwordx4 v[136:137], off
	v_lshl_add_u64 v[136:137], v[132:133], 0, 64
	s_mov_b32 m0, s26
	v_readfirstlane_b32 s26, v128
	global_load_lds_dwordx4 v[136:137], off
	v_lshl_add_u64 v[132:133], v[132:133], 0, s[6:7]
	s_mov_b32 m0, s26
	s_nop 0
	global_load_lds_dwordx4 v[132:133], off
	s_branch .LBB0_1499
